# static-priority strategy step B: flips deleted + one s_setprio 1 for waves 4-7 (trailing half) before each K-loop
# baseline (speedup 1.0000x reference)
; #define PG8_STAGE(bufoff, gbase, voff) do { _Pragma("unroll") for (int _i = 0; _i < 2; ++_i) \
;         __builtin_amdgcn_global_load_lds((const unsigned*)((const char*)(gbase) + (voff)[_i]), (LAS unsigned*)(lds + (bufoff) + ldsw + _i * 8192), 16, 0, 0); } while (0)
; #define PG8_LDA(dst, b, h) do { _Pragma("unroll") for (int m = 0; m < 4; ++m) _Pragma("unroll") for (int k = 0; k < 2; ++k) dst[m][k] = *(const LAS bf16x8*)(lds + PG8_SA(b, h) + aoff + m * 2048 + k * 1024); } while (0)
; #define PG8_LDB(dst, b, h) do { _Pragma("unroll") for (int n = 0; n < 2; ++n) _Pragma("unroll") for (int k = 0; k < 2; ++k) dst[n][k] = *(const LAS bf16x8*)(lds + PG8_SB(b, h) + boff + n * 2048 + k * 1024); } while (0)
; #define PG8_SCHED __builtin_amdgcn_sched_barrier(0)
; template <class Epi>
; __device__ __forceinline__ void gemm_phase(LAS unsigned char* lds, const Gemm g, const StaticOrder& S, const Epi& E, const int tid) {
;     ...
;         const bool has_next = S.next(ui + 1, nxt);
;         const char* nA = has_next ? (const char*)g.A + (size_t)nxt.pm * tstep : cA; const char* nB = has_next ? (const char*)g.Bt + (size_t)nxt.pn * tstep : cB;
;         for (int t = 0; t < ntt; t += 2) {
;             const bool last = (t == ntt - 2);
;             const bool s1 = Epi::TWO && (t >= nt), s2 = Epi::TWO && (t + 2 >= nt);
;             const char* a1 = (s1 ? cA2 + (size_t)(t - nt + 1) * kstep : cA + (size_t)(t + 1) * kstep);
;             const char* a2 = last ? nA : (s2 ? cA2 + (size_t)(t + 2 - nt) * kstep : cA + (size_t)(t + 2) * kstep);
;             const char* b2 = last ? nB : (s2 ? cB2 + (size_t)(t + 2 - nt) * kstep : cB + (size_t)(t + 2) * kstep);
;             const char* a3 = a2 + kstep; const char* b3 = b2 + kstep;
;             if constexpr (Epi::TWO) { if (t == nt) E.mid(acc, cur, wr, wc, fr, fq); }
;             if constexpr (SP2) {
;             PG8_LDB(B0, 0, 0); PG8_LDB(B1, 0, 1); PG8_SCHED; PG8_LDA(At, 0, 0); PG8_STAGE(PG8_SA(1, 1), a1 + hstep, voffA);
;     ...
; #pragma unroll
;         for (int a = 0; a < 2; ++a)
; #pragma unroll
;             for (int b = 0; b < 2; ++b)
; #pragma unroll
;                 for (int m = 0; m < 4; ++m)
; #pragma unroll
;                     for (int n = 0; n < 2; ++n) acc[a][b][m][n] = (f32x4){0.f, 0.f, 0.f, 0.f};
.LBB0_125:
	s_ashr_i32 s17, s16, 31
	s_lshl_b64 s[18:19], s[16:17], 22
	v_readlane_b32 s20, v251, 43
	v_readlane_b32 s21, v251, 44
	s_add_u32 s18, s20, s18
	s_addc_u32 s19, s21, s19
	s_and_b64 s[20:21], s[22:23], exec
	s_cselect_b32 s17, s19, s31
	s_cselect_b32 s27, s18, s30
	s_ashr_i32 s15, s14, 31
	s_lshl_b64 s[20:21], s[14:15], 22
	v_readlane_b32 s34, v251, 41
	v_readlane_b32 s35, v251, 42
	s_add_u32 s20, s34, s20
	s_addc_u32 s21, s35, s21
	s_and_b64 s[34:35], s[22:23], exec
	s_cselect_b32 s15, s21, s29
	s_cselect_b32 s33, s20, s28
	s_add_u32 s49, s28, 0x100
	s_addc_u32 s50, s29, 0
	s_add_u32 s28, s30, 0x200080
	v_mov_b32_e32 v2, 0
	s_addc_u32 s29, s31, 0
	s_mov_b32 s51, -2
	v_mov_b32_e32 v3, v2
	s_waitcnt lgkmcnt(0)
	v_mov_b32_e32 v4, v2
	v_mov_b32_e32 v5, v2
	v_mov_b32_e32 v6, v2
	v_mov_b32_e32 v7, v2
	v_mov_b32_e32 v8, v2
	v_mov_b32_e32 v9, v2
	v_mov_b32_e32 v34, v2
	v_mov_b32_e32 v35, v2
	v_mov_b32_e32 v36, v2
	v_mov_b32_e32 v37, v2
	v_mov_b32_e32 v38, v2
	v_mov_b32_e32 v39, v2
	v_mov_b32_e32 v40, v2
	v_mov_b32_e32 v41, v2
	v_mov_b32_e32 v66, v2
	v_mov_b32_e32 v67, v2
	v_mov_b32_e32 v68, v2
	v_mov_b32_e32 v69, v2
	v_mov_b32_e32 v70, v2
	v_mov_b32_e32 v71, v2
	v_mov_b32_e32 v72, v2
	v_mov_b32_e32 v73, v2
	v_mov_b32_e32 v82, v2
	v_mov_b32_e32 v83, v2
	v_mov_b32_e32 v84, v2
	v_mov_b32_e32 v85, v2
	v_mov_b32_e32 v86, v2
	v_mov_b32_e32 v87, v2
	v_mov_b32_e32 v88, v2
	v_mov_b32_e32 v89, v2
	v_mov_b32_e32 v10, v2
	v_mov_b32_e32 v11, v2
	v_mov_b32_e32 v12, v2
	v_mov_b32_e32 v13, v2
	v_mov_b32_e32 v14, v2
	v_mov_b32_e32 v15, v2
	v_mov_b32_e32 v16, v2
	v_mov_b32_e32 v17, v2
	v_mov_b32_e32 v58, v2
	v_mov_b32_e32 v59, v2
	v_mov_b32_e32 v60, v2
	v_mov_b32_e32 v61, v2
	v_mov_b32_e32 v62, v2
	v_mov_b32_e32 v63, v2
	v_mov_b32_e32 v64, v2
	v_mov_b32_e32 v65, v2
	v_mov_b32_e32 v74, v2
	v_mov_b32_e32 v75, v2
	v_mov_b32_e32 v76, v2
	v_mov_b32_e32 v77, v2
	v_mov_b32_e32 v78, v2
	v_mov_b32_e32 v79, v2
	v_mov_b32_e32 v80, v2
	v_mov_b32_e32 v81, v2
	v_mov_b32_e32 v90, v2
	v_mov_b32_e32 v91, v2
	v_mov_b32_e32 v92, v2
	v_mov_b32_e32 v93, v2
	v_mov_b32_e32 v94, v2
	v_mov_b32_e32 v95, v2
	v_mov_b32_e32 v96, v2
	v_mov_b32_e32 v97, v2
	v_mov_b32_e32 v98, v2
	v_mov_b32_e32 v99, v2
	v_mov_b32_e32 v100, v2
	v_mov_b32_e32 v101, v2
	v_mov_b32_e32 v102, v2
	v_mov_b32_e32 v103, v2
	v_mov_b32_e32 v104, v2
	v_mov_b32_e32 v105, v2
	v_mov_b32_e32 v114, v2
	v_mov_b32_e32 v115, v2
	v_mov_b32_e32 v116, v2
	v_mov_b32_e32 v117, v2
	v_mov_b32_e32 v118, v2
	v_mov_b32_e32 v119, v2
	v_mov_b32_e32 v120, v2
	v_mov_b32_e32 v121, v2
	v_mov_b32_e32 v130, v2
	v_mov_b32_e32 v131, v2
	v_mov_b32_e32 v132, v2
	v_mov_b32_e32 v133, v2
	v_mov_b32_e32 v134, v2
	v_mov_b32_e32 v135, v2
	v_mov_b32_e32 v136, v2
	v_mov_b32_e32 v137, v2
	v_mov_b32_e32 v146, v2
	v_mov_b32_e32 v147, v2
	v_mov_b32_e32 v148, v2
	v_mov_b32_e32 v149, v2
	v_mov_b32_e32 v150, v2
	v_mov_b32_e32 v151, v2
	v_mov_b32_e32 v152, v2
	v_mov_b32_e32 v153, v2
	v_mov_b32_e32 v106, v2
	v_mov_b32_e32 v107, v2
	v_mov_b32_e32 v108, v2
	v_mov_b32_e32 v109, v2
	v_mov_b32_e32 v110, v2
	v_mov_b32_e32 v111, v2
	v_mov_b32_e32 v112, v2
	v_mov_b32_e32 v113, v2
	v_mov_b32_e32 v122, v2
	v_mov_b32_e32 v123, v2
	v_mov_b32_e32 v124, v2
	v_mov_b32_e32 v125, v2
	v_mov_b32_e32 v126, v2
	v_mov_b32_e32 v127, v2
	v_mov_b32_e32 v128, v2
	v_mov_b32_e32 v129, v2
	v_mov_b32_e32 v138, v2
	v_mov_b32_e32 v139, v2
	v_mov_b32_e32 v140, v2
	v_mov_b32_e32 v141, v2
	v_mov_b32_e32 v142, v2
	v_mov_b32_e32 v143, v2
	v_mov_b32_e32 v144, v2
	v_mov_b32_e32 v145, v2
	v_mov_b32_e32 v154, v2
	v_mov_b32_e32 v155, v2
	v_mov_b32_e32 v156, v2
	v_mov_b32_e32 v157, v2
	v_mov_b32_e32 v158, v2
	v_mov_b32_e32 v159, v2
	v_mov_b32_e32 v160, v2
	v_mov_b32_e32 v161, v2
	s_and_b64 vcc, exec, s[12:13]
	s_cbranch_vccnz .Lprio_skip_126
	s_setprio 1
.Lprio_skip_126:
.LBB0_126:
	s_add_u32 s30, s28, 0xffe00080
	s_addc_u32 s31, s29, -1
	s_add_i32 s52, 0, 0x10000
	s_cmpk_eq_i32 s51, 0x7c
	s_cselect_b32 s35, s17, s31
	s_cselect_b32 s34, s27, s30
	s_cselect_b32 s31, s15, s50
	s_cselect_b32 s30, s33, s49
	s_add_i32 s54, 0, 0x14000
	v_add_u32_e32 v30, s52, v193
	v_add_u32_e32 v54, s54, v193
	ds_read_b128 v[18:21], v30
	ds_read_b128 v[22:25], v30 offset:1024
	ds_read_b128 v[26:29], v30 offset:2048
	ds_read_b128 v[30:33], v30 offset:3072
	ds_read_b128 v[42:45], v54
	ds_read_b128 v[46:49], v54 offset:1024
	ds_read_b128 v[50:53], v54 offset:2048
	ds_read_b128 v[54:57], v54 offset:3072
	v_lshl_add_u64 v[172:173], s[28:29], 0, v[180:181]
	s_add_i32 m0, s37, 0xc000
	ds_read_b128 v[182:185], v199
	global_load_lds_dwordx4 v[172:173], off
	ds_read_b128 v[186:189], v199 offset:1024
	ds_read_b128 v[212:215], v199 offset:2048
	v_lshl_add_u64 v[172:173], s[28:29], 0, v[178:179]
	s_add_i32 m0, s37, 0xe000
	s_nop 0
	global_load_lds_dwordx4 v[172:173], off
	ds_read_b128 v[216:219], v199 offset:3072
	ds_read_b128 v[220:223], v199 offset:4096
	ds_read_b128 v[224:227], v199 offset:5120
	ds_read_b128 v[228:231], v199 offset:6144
	ds_read_b128 v[232:235], v199 offset:7168
	s_waitcnt vmcnt(8)
	s_waitcnt lgkmcnt(0)
	s_barrier
; #define PG8_STAGE(bufoff, gbase, voff) do { _Pragma("unroll") for (int _i = 0; _i < 2; ++_i) \
;         __builtin_amdgcn_global_load_lds((const unsigned*)((const char*)(gbase) + (voff)[_i]), (LAS unsigned*)(lds + (bufoff) + ldsw + _i * 8192), 16, 0, 0); } while (0)
; #define PG8_LDA(dst, b, h) do { _Pragma("unroll") for (int m = 0; m < 4; ++m) _Pragma("unroll") for (int k = 0; k < 2; ++k) dst[m][k] = *(const LAS bf16x8*)(lds + PG8_SA(b, h) + aoff + m * 2048 + k * 1024); } while (0)
; #define PG8_LDB(dst, b, h) do { _Pragma("unroll") for (int n = 0; n < 2; ++n) _Pragma("unroll") for (int k = 0; k < 2; ++k) dst[n][k] = *(const LAS bf16x8*)(lds + PG8_SB(b, h) + boff + n * 2048 + k * 1024); } while (0)
; #define PG8_MMA(ai, bj, At, Bt) do { __builtin_amdgcn_s_setprio(1); _Pragma("unroll") for (int m = 0; m < 4; ++m) _Pragma("unroll") for (int n = 0; n < 2; ++n) _Pragma("unroll") for (int k = 0; k < 2; ++k) \
;         acc[ai][bj][m][n] = __builtin_amdgcn_mfma_f32_16x16x32_bf16(Bt[n][k], At[m][k], acc[ai][bj][m][n], 0, 0, 0); __builtin_amdgcn_s_setprio(0); } while (0)
; #define PG8_WAIT_V(n) asm volatile("s_waitcnt vmcnt(" #n ")" ::: "memory")
; #define PG8_WAIT_L(n) asm volatile("s_waitcnt lgkmcnt(" #n ")" ::: "memory")
; #define PG8_BAR __builtin_amdgcn_s_barrier()
; #define PG8_SCHED __builtin_amdgcn_sched_barrier(0)
; template <class Epi>
; __device__ __forceinline__ void gemm_phase(LAS unsigned char* lds, const Gemm g, const StaticOrder& S, const Epi& E, const int tid) {
;     ...
;             PG8_LDB(B0, 0, 0); PG8_LDB(B1, 0, 1); PG8_SCHED; PG8_LDA(At, 0, 0); PG8_STAGE(PG8_SA(1, 1), a1 + hstep, voffA);
;             PG8_WAIT_V(8); PG8_WAIT_L(0); PG8_BAR; PG8_MMA(0, 0, At, B0); PG8_MMA(0, 1, At, B1); PG8_BAR; PG8_SCHED;
;             PG8_LDA(At, 0, 1); PG8_STAGE(PG8_SB(0, 0), b2, voffB); PG8_STAGE(PG8_SB(0, 1), b2 + bhs, voffB); PG8_STAGE(PG8_SA(0, 0), a2, voffA);
;             PG8_WAIT_V(8); PG8_WAIT_L(0); PG8_BAR; PG8_MMA(1, 0, At, B0); PG8_MMA(1, 1, At, B1); PG8_BAR; PG8_SCHED;
	s_waitcnt lgkmcnt(0)
	v_mfma_f32_16x16x32_bf16 v[158:161], v[18:21], v[182:185], v[158:161]
	v_mfma_f32_16x16x32_bf16 v[154:157], v[26:29], v[182:185], v[154:157]
	v_mfma_f32_16x16x32_bf16 v[142:145], v[18:21], v[212:215], v[142:145]
	v_mfma_f32_16x16x32_bf16 v[138:141], v[26:29], v[212:215], v[138:141]
	v_mfma_f32_16x16x32_bf16 v[126:129], v[18:21], v[220:223], v[126:129]
	v_mfma_f32_16x16x32_bf16 v[122:125], v[26:29], v[220:223], v[122:125]
	v_mfma_f32_16x16x32_bf16 v[110:113], v[18:21], v[228:231], v[110:113]
	v_mfma_f32_16x16x32_bf16 v[106:109], v[26:29], v[228:231], v[106:109]
	v_mfma_f32_16x16x32_bf16 v[158:161], v[22:25], v[186:189], v[158:161]
	v_mfma_f32_16x16x32_bf16 v[154:157], v[30:33], v[186:189], v[154:157]
	v_mfma_f32_16x16x32_bf16 v[142:145], v[22:25], v[216:219], v[142:145]
	v_mfma_f32_16x16x32_bf16 v[138:141], v[30:33], v[216:219], v[138:141]
	v_mfma_f32_16x16x32_bf16 v[126:129], v[22:25], v[224:227], v[126:129]
	v_mfma_f32_16x16x32_bf16 v[122:125], v[30:33], v[224:227], v[122:125]
	v_mfma_f32_16x16x32_bf16 v[110:113], v[22:25], v[232:235], v[110:113]
	v_mfma_f32_16x16x32_bf16 v[106:109], v[30:33], v[232:235], v[106:109]
	v_mfma_f32_16x16x32_bf16 v[150:153], v[42:45], v[182:185], v[150:153]
	v_mfma_f32_16x16x32_bf16 v[146:149], v[50:53], v[182:185], v[146:149]
	v_mfma_f32_16x16x32_bf16 v[134:137], v[42:45], v[212:215], v[134:137]
	v_mfma_f32_16x16x32_bf16 v[130:133], v[50:53], v[212:215], v[130:133]
	v_mfma_f32_16x16x32_bf16 v[118:121], v[42:45], v[220:223], v[118:121]
	v_mfma_f32_16x16x32_bf16 v[114:117], v[50:53], v[220:223], v[114:117]
	v_mfma_f32_16x16x32_bf16 v[102:105], v[42:45], v[228:231], v[102:105]
	v_mfma_f32_16x16x32_bf16 v[98:101], v[50:53], v[228:231], v[98:101]
	v_mfma_f32_16x16x32_bf16 v[150:153], v[46:49], v[186:189], v[150:153]
	v_mfma_f32_16x16x32_bf16 v[146:149], v[54:57], v[186:189], v[146:149]
	v_mfma_f32_16x16x32_bf16 v[134:137], v[46:49], v[216:219], v[134:137]
	v_mfma_f32_16x16x32_bf16 v[130:133], v[54:57], v[216:219], v[130:133]
	v_mfma_f32_16x16x32_bf16 v[118:121], v[46:49], v[224:227], v[118:121]
	v_mfma_f32_16x16x32_bf16 v[114:117], v[54:57], v[224:227], v[114:117]
	v_mfma_f32_16x16x32_bf16 v[102:105], v[46:49], v[232:235], v[102:105]
	v_mfma_f32_16x16x32_bf16 v[98:101], v[54:57], v[232:235], v[98:101]
	s_barrier
	s_add_i32 s52, s52, s36
	v_lshl_add_u64 v[172:173], s[30:31], 0, v[0:1]
	s_mov_b32 m0, s52
	ds_read_b128 v[182:185], v199 offset:16384
	global_load_lds_dwordx4 v[172:173], off
	ds_read_b128 v[186:189], v199 offset:17408
	ds_read_b128 v[212:215], v199 offset:18432
	s_add_i32 m0, s52, 0x2000
	s_add_u32 s52, s30, 0x20000
	v_lshl_add_u64 v[174:175], s[30:31], 0, v[166:167]
	s_addc_u32 s53, s31, 0
	s_add_i32 s54, s54, s36
	global_load_lds_dwordx4 v[174:175], off
	ds_read_b128 v[216:219], v199 offset:19456
	ds_read_b128 v[220:223], v199 offset:20480
	v_lshl_add_u64 v[176:177], s[52:53], 0, v[0:1]
	s_mov_b32 m0, s54
	v_lshl_add_u64 v[200:201], s[34:35], 0, v[164:165]
	global_load_lds_dwordx4 v[176:177], off
	ds_read_b128 v[224:227], v199 offset:21504
	ds_read_b128 v[228:231], v199 offset:22528
	v_lshl_add_u64 v[176:177], s[52:53], 0, v[166:167]
	s_add_i32 m0, s54, 0x2000
	s_nop 0
	global_load_lds_dwordx4 v[176:177], off
	ds_read_b128 v[232:235], v199 offset:23552
	v_lshl_add_u64 v[176:177], s[34:35], 0, v[162:163]
	s_mov_b32 m0, s37
	s_nop 0
	global_load_lds_dwordx4 v[176:177], off
	s_mov_b32 m0, s38
	s_nop 0
	global_load_lds_dwordx4 v[200:201], off
	s_waitcnt vmcnt(8)
	s_waitcnt lgkmcnt(0)
	s_barrier
	s_waitcnt lgkmcnt(0)
	v_mfma_f32_16x16x32_bf16 v[94:97], v[18:21], v[182:185], v[94:97]
	v_mfma_f32_16x16x32_bf16 v[90:93], v[26:29], v[182:185], v[90:93]
	v_mfma_f32_16x16x32_bf16 v[78:81], v[18:21], v[212:215], v[78:81]
	v_mfma_f32_16x16x32_bf16 v[74:77], v[26:29], v[212:215], v[74:77]
	v_mfma_f32_16x16x32_bf16 v[62:65], v[18:21], v[220:223], v[62:65]
	v_mfma_f32_16x16x32_bf16 v[58:61], v[26:29], v[220:223], v[58:61]
	v_mfma_f32_16x16x32_bf16 v[14:17], v[18:21], v[228:231], v[14:17]
	v_mfma_f32_16x16x32_bf16 v[10:13], v[26:29], v[228:231], v[10:13]
	v_mfma_f32_16x16x32_bf16 v[94:97], v[22:25], v[186:189], v[94:97]
	v_mfma_f32_16x16x32_bf16 v[90:93], v[30:33], v[186:189], v[90:93]
	v_mfma_f32_16x16x32_bf16 v[78:81], v[22:25], v[216:219], v[78:81]
	v_mfma_f32_16x16x32_bf16 v[74:77], v[30:33], v[216:219], v[74:77]
	v_mfma_f32_16x16x32_bf16 v[62:65], v[22:25], v[224:227], v[62:65]
	v_mfma_f32_16x16x32_bf16 v[58:61], v[30:33], v[224:227], v[58:61]
	v_mfma_f32_16x16x32_bf16 v[14:17], v[22:25], v[232:235], v[14:17]
	v_mfma_f32_16x16x32_bf16 v[10:13], v[30:33], v[232:235], v[10:13]
	v_mfma_f32_16x16x32_bf16 v[38:41], v[42:45], v[220:223], v[38:41]
	v_mfma_f32_16x16x32_bf16 v[34:37], v[50:53], v[220:223], v[34:37]
	v_mfma_f32_16x16x32_bf16 v[6:9], v[42:45], v[228:231], v[6:9]
	v_mfma_f32_16x16x32_bf16 v[2:5], v[50:53], v[228:231], v[2:5]
	v_mfma_f32_16x16x32_bf16 v[18:21], v[42:45], v[182:185], v[86:89]
	v_mfma_f32_16x16x32_bf16 v[22:25], v[50:53], v[182:185], v[82:85]
	v_mfma_f32_16x16x32_bf16 v[26:29], v[42:45], v[212:215], v[70:73]
	v_mfma_f32_16x16x32_bf16 v[30:33], v[50:53], v[212:215], v[66:69]
	v_mfma_f32_16x16x32_bf16 v[38:41], v[46:49], v[224:227], v[38:41]
	v_mfma_f32_16x16x32_bf16 v[34:37], v[54:57], v[224:227], v[34:37]
	v_mfma_f32_16x16x32_bf16 v[6:9], v[46:49], v[232:235], v[6:9]
	v_mfma_f32_16x16x32_bf16 v[2:5], v[54:57], v[232:235], v[2:5]
	v_mfma_f32_16x16x32_bf16 v[18:21], v[46:49], v[186:189], v[18:21]
	v_mfma_f32_16x16x32_bf16 v[22:25], v[54:57], v[186:189], v[22:25]
	v_mfma_f32_16x16x32_bf16 v[26:29], v[46:49], v[216:219], v[26:29]
	v_mfma_f32_16x16x32_bf16 v[30:33], v[54:57], v[216:219], v[30:33]
	s_barrier
; #define PG8_STAGE(bufoff, gbase, voff) do { _Pragma("unroll") for (int _i = 0; _i < 2; ++_i) \
;         __builtin_amdgcn_global_load_lds((const unsigned*)((const char*)(gbase) + (voff)[_i]), (LAS unsigned*)(lds + (bufoff) + ldsw + _i * 8192), 16, 0, 0); } while (0)
; #define PG8_LDA(dst, b, h) do { _Pragma("unroll") for (int m = 0; m < 4; ++m) _Pragma("unroll") for (int k = 0; k < 2; ++k) dst[m][k] = *(const LAS bf16x8*)(lds + PG8_SA(b, h) + aoff + m * 2048 + k * 1024); } while (0)
; #define PG8_LDB(dst, b, h) do { _Pragma("unroll") for (int n = 0; n < 2; ++n) _Pragma("unroll") for (int k = 0; k < 2; ++k) dst[n][k] = *(const LAS bf16x8*)(lds + PG8_SB(b, h) + boff + n * 2048 + k * 1024); } while (0)
; #define PG8_MMA(ai, bj, At, Bt) do { __builtin_amdgcn_s_setprio(1); _Pragma("unroll") for (int m = 0; m < 4; ++m) _Pragma("unroll") for (int n = 0; n < 2; ++n) _Pragma("unroll") for (int k = 0; k < 2; ++k) \
;         acc[ai][bj][m][n] = __builtin_amdgcn_mfma_f32_16x16x32_bf16(Bt[n][k], At[m][k], acc[ai][bj][m][n], 0, 0, 0); __builtin_amdgcn_s_setprio(0); } while (0)
; #define PG8_WAIT_V(n) asm volatile("s_waitcnt vmcnt(" #n ")" ::: "memory")
; #define PG8_WAIT_L(n) asm volatile("s_waitcnt lgkmcnt(" #n ")" ::: "memory")
; #define PG8_BAR __builtin_amdgcn_s_barrier()
; #define PG8_SCHED __builtin_amdgcn_sched_barrier(0)
; template <class Epi>
; __device__ __forceinline__ void gemm_phase(LAS unsigned char* lds, const Gemm g, const StaticOrder& S, const Epi& E, const int tid) {
;     ...
;             PG8_LDB(B0, 1, 0); PG8_LDB(B1, 1, 1); PG8_SCHED; PG8_LDA(At, 1, 0); PG8_STAGE(PG8_SA(0, 1), a2 + hstep, voffA);
;             PG8_WAIT_V(8); PG8_WAIT_L(0); PG8_BAR; PG8_MMA(0, 0, At, B0); PG8_MMA(0, 1, At, B1); PG8_BAR; PG8_SCHED;
;             PG8_LDA(At, 1, 1); PG8_STAGE(PG8_SB(1, 0), b3, voffB); PG8_STAGE(PG8_SB(1, 1), b3 + bhs, voffB); PG8_STAGE(PG8_SA(1, 0), a3, voffA);
;             PG8_WAIT_V(8); PG8_WAIT_L(0); PG8_BAR; PG8_MMA(1, 0, At, B0); PG8_MMA(1, 1, At, B1); PG8_BAR; PG8_SCHED;
;     ...
;         if (ALIGN_EPI) { if (wr == 0) PG8_BAR; }
	s_add_i32 s52, 0, 0x18000
	s_add_i32 s53, 0, 0x1c000
	v_add_u32_e32 v54, s52, v193
	v_add_u32_e32 v66, s53, v193
	ds_read_b128 v[42:45], v54
	ds_read_b128 v[46:49], v54 offset:1024
	ds_read_b128 v[50:53], v54 offset:2048
	ds_read_b128 v[54:57], v54 offset:3072
	ds_read_b128 v[182:185], v66
	ds_read_b128 v[186:189], v66 offset:1024
	ds_read_b128 v[212:215], v66 offset:2048
	ds_read_b128 v[216:219], v66 offset:3072
	s_add_u32 s34, s34, 0x200000
	s_addc_u32 s35, s35, 0
	s_mov_b32 m0, s39
	v_lshl_add_u64 v[236:237], s[34:35], 0, v[162:163]
	ds_read_b128 v[66:69], v199 offset:32768
	global_load_lds_dwordx4 v[236:237], off
	ds_read_b128 v[70:73], v199 offset:33792
	ds_read_b128 v[82:85], v199 offset:34816
	v_lshl_add_u64 v[236:237], s[34:35], 0, v[164:165]
	s_mov_b32 m0, s44
	s_nop 0
	global_load_lds_dwordx4 v[236:237], off
	ds_read_b128 v[86:89], v199 offset:35840
	ds_read_b128 v[220:223], v199 offset:36864
	ds_read_b128 v[224:227], v199 offset:37888
	ds_read_b128 v[228:231], v199 offset:38912
	ds_read_b128 v[232:235], v199 offset:39936
	s_waitcnt vmcnt(8)
	s_waitcnt lgkmcnt(0)
	s_barrier
	s_waitcnt lgkmcnt(0)
	v_mfma_f32_16x16x32_bf16 v[158:161], v[42:45], v[66:69], v[158:161]
	v_mfma_f32_16x16x32_bf16 v[154:157], v[50:53], v[66:69], v[154:157]
	v_mfma_f32_16x16x32_bf16 v[142:145], v[42:45], v[82:85], v[142:145]
	v_mfma_f32_16x16x32_bf16 v[138:141], v[50:53], v[82:85], v[138:141]
	v_mfma_f32_16x16x32_bf16 v[126:129], v[42:45], v[220:223], v[126:129]
	v_mfma_f32_16x16x32_bf16 v[122:125], v[50:53], v[220:223], v[122:125]
	v_mfma_f32_16x16x32_bf16 v[110:113], v[42:45], v[228:231], v[110:113]
	v_mfma_f32_16x16x32_bf16 v[106:109], v[50:53], v[228:231], v[106:109]
	v_mfma_f32_16x16x32_bf16 v[158:161], v[46:49], v[70:73], v[158:161]
	v_mfma_f32_16x16x32_bf16 v[154:157], v[54:57], v[70:73], v[154:157]
	v_mfma_f32_16x16x32_bf16 v[142:145], v[46:49], v[86:89], v[142:145]
	v_mfma_f32_16x16x32_bf16 v[138:141], v[54:57], v[86:89], v[138:141]
	v_mfma_f32_16x16x32_bf16 v[126:129], v[46:49], v[224:227], v[126:129]
	v_mfma_f32_16x16x32_bf16 v[122:125], v[54:57], v[224:227], v[122:125]
	v_mfma_f32_16x16x32_bf16 v[110:113], v[46:49], v[232:235], v[110:113]
	v_mfma_f32_16x16x32_bf16 v[106:109], v[54:57], v[232:235], v[106:109]
	v_mfma_f32_16x16x32_bf16 v[150:153], v[182:185], v[66:69], v[150:153]
	v_mfma_f32_16x16x32_bf16 v[66:69], v[212:215], v[66:69], v[146:149]
	v_mfma_f32_16x16x32_bf16 v[146:149], v[216:219], v[70:73], v[66:69]
	v_mfma_f32_16x16x32_bf16 v[66:69], v[182:185], v[82:85], v[134:137]
	v_mfma_f32_16x16x32_bf16 v[134:137], v[186:189], v[86:89], v[66:69]
	v_mfma_f32_16x16x32_bf16 v[66:69], v[212:215], v[82:85], v[130:133]
	v_mfma_f32_16x16x32_bf16 v[130:133], v[216:219], v[86:89], v[66:69]
	v_mfma_f32_16x16x32_bf16 v[66:69], v[182:185], v[220:223], v[118:121]
	v_mfma_f32_16x16x32_bf16 v[118:121], v[186:189], v[224:227], v[66:69]
	v_mfma_f32_16x16x32_bf16 v[66:69], v[212:215], v[220:223], v[114:117]
	v_mfma_f32_16x16x32_bf16 v[114:117], v[216:219], v[224:227], v[66:69]
	v_mfma_f32_16x16x32_bf16 v[66:69], v[182:185], v[228:231], v[102:105]
	v_mfma_f32_16x16x32_bf16 v[102:105], v[186:189], v[232:235], v[66:69]
	v_mfma_f32_16x16x32_bf16 v[66:69], v[212:215], v[228:231], v[98:101]
	v_mfma_f32_16x16x32_bf16 v[150:153], v[186:189], v[70:73], v[150:153]
	v_mfma_f32_16x16x32_bf16 v[98:101], v[216:219], v[232:235], v[66:69]
	s_barrier
	s_add_i32 s34, s52, s36
	v_lshl_add_u64 v[82:83], v[172:173], 0, s[70:71]
	s_mov_b32 m0, s34
	s_nop 0
	ds_read_b128 v[66:69], v199 offset:49152
	global_load_lds_dwordx4 v[82:83], off
	ds_read_b128 v[70:73], v199 offset:50176
	ds_read_b128 v[220:223], v199 offset:51200
	s_add_i32 m0, s34, 0x2000
	s_add_u32 s30, s30, 0x20080
	v_lshl_add_u64 v[82:83], v[174:175], 0, s[70:71]
	s_addc_u32 s31, s31, 0
	s_add_i32 s34, s53, s36
	global_load_lds_dwordx4 v[82:83], off
	ds_read_b128 v[224:227], v199 offset:52224
	ds_read_b128 v[228:231], v199 offset:53248
	v_lshl_add_u64 v[82:83], s[30:31], 0, v[0:1]
	s_mov_b32 m0, s34
	s_nop 0
	global_load_lds_dwordx4 v[82:83], off
	ds_read_b128 v[232:235], v199 offset:54272
	ds_read_b128 v[236:239], v199 offset:55296
	v_lshl_add_u64 v[82:83], s[30:31], 0, v[166:167]
	s_add_i32 m0, s34, 0x2000
	s_nop 0
	global_load_lds_dwordx4 v[82:83], off
	ds_read_b128 v[240:243], v199 offset:56320
	v_lshl_add_u64 v[82:83], v[176:177], 0, s[70:71]
	s_mov_b32 m0, s45
	s_nop 0
	global_load_lds_dwordx4 v[82:83], off
	v_lshl_add_u64 v[82:83], v[200:201], 0, s[70:71]
	s_mov_b32 m0, s46
	s_nop 0
	global_load_lds_dwordx4 v[82:83], off
	s_waitcnt vmcnt(8)
	s_waitcnt lgkmcnt(0)
	s_barrier
	s_waitcnt lgkmcnt(0)
	v_mfma_f32_16x16x32_bf16 v[82:85], v[42:45], v[66:69], v[94:97]
	v_mfma_f32_16x16x32_bf16 v[94:97], v[46:49], v[70:73], v[82:85]
	v_mfma_f32_16x16x32_bf16 v[82:85], v[50:53], v[66:69], v[90:93]
	v_mfma_f32_16x16x32_bf16 v[78:81], v[42:45], v[220:223], v[78:81]
	v_mfma_f32_16x16x32_bf16 v[74:77], v[50:53], v[220:223], v[74:77]
	v_mfma_f32_16x16x32_bf16 v[62:65], v[42:45], v[228:231], v[62:65]
	v_mfma_f32_16x16x32_bf16 v[58:61], v[50:53], v[228:231], v[58:61]
	v_mfma_f32_16x16x32_bf16 v[14:17], v[42:45], v[236:239], v[14:17]
	v_mfma_f32_16x16x32_bf16 v[10:13], v[50:53], v[236:239], v[10:13]
	v_mfma_f32_16x16x32_bf16 v[90:93], v[54:57], v[70:73], v[82:85]
	v_mfma_f32_16x16x32_bf16 v[78:81], v[46:49], v[224:227], v[78:81]
	v_mfma_f32_16x16x32_bf16 v[74:77], v[54:57], v[224:227], v[74:77]
	v_mfma_f32_16x16x32_bf16 v[62:65], v[46:49], v[232:235], v[62:65]
	v_mfma_f32_16x16x32_bf16 v[58:61], v[54:57], v[232:235], v[58:61]
	v_mfma_f32_16x16x32_bf16 v[14:17], v[46:49], v[240:243], v[14:17]
	v_mfma_f32_16x16x32_bf16 v[10:13], v[54:57], v[240:243], v[10:13]
	v_mfma_f32_16x16x32_bf16 v[18:21], v[182:185], v[66:69], v[18:21]
	v_mfma_f32_16x16x32_bf16 v[86:89], v[186:189], v[70:73], v[18:21]
	v_mfma_f32_16x16x32_bf16 v[18:21], v[212:215], v[66:69], v[22:25]
	v_mfma_f32_16x16x32_bf16 v[82:85], v[216:219], v[70:73], v[18:21]
	v_mfma_f32_16x16x32_bf16 v[18:21], v[182:185], v[220:223], v[26:29]
	v_mfma_f32_16x16x32_bf16 v[70:73], v[186:189], v[224:227], v[18:21]
	v_mfma_f32_16x16x32_bf16 v[18:21], v[212:215], v[220:223], v[30:33]
	v_mfma_f32_16x16x32_bf16 v[66:69], v[216:219], v[224:227], v[18:21]
	v_mfma_f32_16x16x32_bf16 v[18:21], v[182:185], v[228:231], v[38:41]
	v_mfma_f32_16x16x32_bf16 v[38:41], v[186:189], v[232:235], v[18:21]
	v_mfma_f32_16x16x32_bf16 v[18:21], v[212:215], v[228:231], v[34:37]
	v_mfma_f32_16x16x32_bf16 v[6:9], v[182:185], v[236:239], v[6:9]
	v_mfma_f32_16x16x32_bf16 v[2:5], v[212:215], v[236:239], v[2:5]
	v_mfma_f32_16x16x32_bf16 v[34:37], v[216:219], v[232:235], v[18:21]
	v_mfma_f32_16x16x32_bf16 v[6:9], v[186:189], v[240:243], v[6:9]
	v_mfma_f32_16x16x32_bf16 v[2:5], v[216:219], v[240:243], v[2:5]
	s_barrier
	s_add_i32 s51, s51, 2
	s_add_u32 s49, s49, 0x100
	s_addc_u32 s50, s50, 0
	s_add_u32 s28, s28, 0x100
	s_addc_u32 s29, s29, 0
	s_cmpk_gt_u32 s51, 0x7d
	s_cbranch_scc0 .LBB0_126
	s_and_b64 vcc, exec, s[12:13]
	s_cbranch_vccz .LBB0_129
	s_barrier

; #define PG8_STAGE(bufoff, gbase, voff) do { _Pragma("unroll") for (int _i = 0; _i < 2; ++_i) \
;         __builtin_amdgcn_global_load_lds((const unsigned*)((const char*)(gbase) + (voff)[_i]), (LAS unsigned*)(lds + (bufoff) + ldsw + _i * 8192), 16, 0, 0); } while (0)
; #define PG8_LDA(dst, b, h) do { _Pragma("unroll") for (int m = 0; m < 4; ++m) _Pragma("unroll") for (int k = 0; k < 2; ++k) dst[m][k] = *(const LAS bf16x8*)(lds + PG8_SA(b, h) + aoff + m * 2048 + k * 1024); } while (0)
; #define PG8_LDB(dst, b, h) do { _Pragma("unroll") for (int n = 0; n < 2; ++n) _Pragma("unroll") for (int k = 0; k < 2; ++k) dst[n][k] = *(const LAS bf16x8*)(lds + PG8_SB(b, h) + boff + n * 2048 + k * 1024); } while (0)
; #define PG8_SCHED __builtin_amdgcn_sched_barrier(0)
; template <class Epi>
; __device__ __forceinline__ void gemm_phase(LAS unsigned char* lds, const Gemm g, const StaticOrder& S, const Epi& E, const int tid) {
;     ...
;         const bool has_next = S.next(ui + 1, nxt);
;         const char* nA = has_next ? (const char*)g.A + (size_t)nxt.pm * tstep : cA; const char* nB = has_next ? (const char*)g.Bt + (size_t)nxt.pn * tstep : cB;
;         for (int t = 0; t < ntt; t += 2) {
;             const bool last = (t == ntt - 2);
;             const bool s1 = Epi::TWO && (t >= nt), s2 = Epi::TWO && (t + 2 >= nt);
;             const char* a1 = (s1 ? cA2 + (size_t)(t - nt + 1) * kstep : cA + (size_t)(t + 1) * kstep);
;             const char* a2 = last ? nA : (s2 ? cA2 + (size_t)(t + 2 - nt) * kstep : cA + (size_t)(t + 2) * kstep);
;             const char* b2 = last ? nB : (s2 ? cB2 + (size_t)(t + 2 - nt) * kstep : cB + (size_t)(t + 2) * kstep);
;             const char* a3 = a2 + kstep; const char* b3 = b2 + kstep;
;             if constexpr (Epi::TWO) { if (t == nt) E.mid(acc, cur, wr, wc, fr, fq); }
;             if constexpr (SP2) {
;             PG8_LDB(B0, 0, 0); PG8_LDB(B1, 0, 1); PG8_SCHED; PG8_LDA(At, 0, 0); PG8_STAGE(PG8_SA(1, 1), a1 + hstep, voffA);
;     ...
; #pragma unroll
;         for (int a = 0; a < 2; ++a)
; #pragma unroll
;             for (int b = 0; b < 2; ++b)
; #pragma unroll
;                 for (int m = 0; m < 4; ++m)
; #pragma unroll
;                     for (int n = 0; n < 2; ++n) acc[a][b][m][n] = (f32x4){0.f, 0.f, 0.f, 0.f};
.LBB0_172:
	s_ashr_i32 s17, s16, 31
	s_lshl_b64 s[18:19], s[16:17], 20
	v_readlane_b32 s20, v251, 31
	v_readlane_b32 s21, v251, 32
	s_add_u32 s18, s20, s18
	s_addc_u32 s19, s21, s19
	s_and_b64 s[20:21], s[22:23], exec
	s_cselect_b32 s17, s19, s29
	s_cselect_b32 s42, s18, s28
	s_ashr_i32 s15, s14, 31
	s_lshl_b64 s[20:21], s[14:15], 20
	s_add_u32 s20, s8, s20
	s_addc_u32 s21, s9, s21
	s_and_b64 s[30:31], s[22:23], exec
	s_cselect_b32 s15, s21, s27
	s_cselect_b32 s43, s20, s26
	s_add_u32 s44, s26, 0x100
	s_addc_u32 s45, s27, 0
	s_add_u32 s26, s28, 0x80080
	v_mov_b32_e32 v2, 0
	s_addc_u32 s27, s29, 0
	s_mov_b32 s46, -2
	v_mov_b32_e32 v3, v2
	v_mov_b32_e32 v4, v2
	v_mov_b32_e32 v5, v2
	v_mov_b32_e32 v6, v2
	v_mov_b32_e32 v7, v2
	v_mov_b32_e32 v8, v2
	v_mov_b32_e32 v9, v2
	v_mov_b32_e32 v18, v2
	v_mov_b32_e32 v19, v2
	v_mov_b32_e32 v20, v2
	v_mov_b32_e32 v21, v2
	v_mov_b32_e32 v22, v2
	v_mov_b32_e32 v23, v2
	v_mov_b32_e32 v24, v2
	v_mov_b32_e32 v25, v2
	v_mov_b32_e32 v34, v2
	v_mov_b32_e32 v35, v2
	v_mov_b32_e32 v36, v2
	v_mov_b32_e32 v37, v2
	v_mov_b32_e32 v38, v2
	v_mov_b32_e32 v39, v2
	v_mov_b32_e32 v40, v2
	v_mov_b32_e32 v41, v2
	v_mov_b32_e32 v50, v2
	v_mov_b32_e32 v51, v2
	v_mov_b32_e32 v52, v2
	v_mov_b32_e32 v53, v2
	v_mov_b32_e32 v54, v2
	v_mov_b32_e32 v55, v2
	v_mov_b32_e32 v56, v2
	v_mov_b32_e32 v57, v2
	v_mov_b32_e32 v10, v2
	v_mov_b32_e32 v11, v2
	v_mov_b32_e32 v12, v2
	v_mov_b32_e32 v13, v2
	v_mov_b32_e32 v14, v2
	v_mov_b32_e32 v15, v2
	v_mov_b32_e32 v16, v2
	v_mov_b32_e32 v17, v2
	v_mov_b32_e32 v26, v2
	v_mov_b32_e32 v27, v2
	v_mov_b32_e32 v28, v2
	v_mov_b32_e32 v29, v2
	v_mov_b32_e32 v30, v2
	v_mov_b32_e32 v31, v2
	v_mov_b32_e32 v32, v2
	v_mov_b32_e32 v33, v2
	v_mov_b32_e32 v42, v2
	v_mov_b32_e32 v43, v2
	v_mov_b32_e32 v44, v2
	v_mov_b32_e32 v45, v2
	v_mov_b32_e32 v46, v2
	v_mov_b32_e32 v47, v2
	v_mov_b32_e32 v48, v2
	v_mov_b32_e32 v49, v2
	v_mov_b32_e32 v58, v2
	v_mov_b32_e32 v59, v2
	v_mov_b32_e32 v60, v2
	v_mov_b32_e32 v61, v2
	v_mov_b32_e32 v62, v2
	v_mov_b32_e32 v63, v2
	v_mov_b32_e32 v64, v2
	v_mov_b32_e32 v65, v2
	v_mov_b32_e32 v66, v2
	v_mov_b32_e32 v67, v2
	v_mov_b32_e32 v68, v2
	v_mov_b32_e32 v69, v2
	v_mov_b32_e32 v70, v2
	v_mov_b32_e32 v71, v2
	v_mov_b32_e32 v72, v2
	v_mov_b32_e32 v73, v2
	v_mov_b32_e32 v82, v2
	v_mov_b32_e32 v83, v2
	v_mov_b32_e32 v84, v2
	v_mov_b32_e32 v85, v2
	v_mov_b32_e32 v86, v2
	v_mov_b32_e32 v87, v2
	v_mov_b32_e32 v88, v2
	v_mov_b32_e32 v89, v2
	v_mov_b32_e32 v98, v2
	v_mov_b32_e32 v99, v2
	v_mov_b32_e32 v100, v2
	v_mov_b32_e32 v101, v2
	v_mov_b32_e32 v102, v2
	v_mov_b32_e32 v103, v2
	v_mov_b32_e32 v104, v2
	v_mov_b32_e32 v105, v2
	v_mov_b32_e32 v114, v2
	v_mov_b32_e32 v115, v2
	v_mov_b32_e32 v116, v2
	v_mov_b32_e32 v117, v2
	v_mov_b32_e32 v118, v2
	v_mov_b32_e32 v119, v2
	v_mov_b32_e32 v120, v2
	v_mov_b32_e32 v121, v2
	v_mov_b32_e32 v74, v2
	v_mov_b32_e32 v75, v2
	v_mov_b32_e32 v76, v2
	v_mov_b32_e32 v77, v2
	v_mov_b32_e32 v78, v2
	v_mov_b32_e32 v79, v2
	v_mov_b32_e32 v80, v2
	v_mov_b32_e32 v81, v2
	v_mov_b32_e32 v90, v2
	v_mov_b32_e32 v91, v2
	v_mov_b32_e32 v92, v2
	v_mov_b32_e32 v93, v2
	v_mov_b32_e32 v94, v2
	v_mov_b32_e32 v95, v2
	v_mov_b32_e32 v96, v2
	v_mov_b32_e32 v97, v2
	v_mov_b32_e32 v106, v2
	v_mov_b32_e32 v107, v2
	v_mov_b32_e32 v108, v2
	v_mov_b32_e32 v109, v2
	v_mov_b32_e32 v110, v2
	v_mov_b32_e32 v111, v2
	v_mov_b32_e32 v112, v2
	v_mov_b32_e32 v113, v2
	v_mov_b32_e32 v122, v2
	v_mov_b32_e32 v123, v2
	v_mov_b32_e32 v124, v2
	v_mov_b32_e32 v125, v2
	v_mov_b32_e32 v126, v2
	v_mov_b32_e32 v127, v2
	v_mov_b32_e32 v128, v2
	v_mov_b32_e32 v129, v2
	s_and_b64 vcc, exec, s[12:13]
	s_cbranch_vccnz .Lprio_skip_173
	s_setprio 1
.Lprio_skip_173:
.LBB0_173:
	s_add_u32 s28, s26, 0xfff80080
	s_addc_u32 s29, s27, -1
	s_add_i32 s47, 0, 0x10000
	s_cmp_eq_u32 s46, 28
	s_cselect_b32 s31, s17, s29
	s_cselect_b32 s30, s42, s28
	v_add_u32_e32 v142, s47, v149
	s_cselect_b32 s29, s15, s45
	s_cselect_b32 s28, s43, s44
	s_add_i32 s50, 0, 0x14000
	ds_read_b128 v[156:159], v142
	ds_read_b128 v[160:163], v142 offset:1024
	ds_read_b128 v[164:167], v142 offset:2048
	ds_read_b128 v[178:181], v142 offset:3072
	v_add_u32_e32 v142, s50, v149
	ds_read_b128 v[182:185], v142
	ds_read_b128 v[186:189], v142 offset:1024
	ds_read_b128 v[190:193], v142 offset:2048
	ds_read_b128 v[194:197], v142 offset:3072
	v_lshl_add_u64 v[142:143], s[26:27], 0, v[140:141]
	s_add_i32 m0, s2, 0xc000
	ds_read_b128 v[198:201], v154
	global_load_lds_dwordx4 v[142:143], off
	ds_read_b128 v[212:215], v154 offset:1024
	ds_read_b128 v[216:219], v154 offset:2048
	v_lshl_add_u64 v[142:143], s[26:27], 0, v[138:139]
	s_add_i32 m0, s2, 0xe000
	s_nop 0
	global_load_lds_dwordx4 v[142:143], off
	ds_read_b128 v[220:223], v154 offset:3072
	ds_read_b128 v[224:227], v154 offset:4096
	ds_read_b128 v[228:231], v154 offset:5120
	ds_read_b128 v[232:235], v154 offset:6144
	ds_read_b128 v[236:239], v154 offset:7168
	s_waitcnt vmcnt(8)
	s_waitcnt lgkmcnt(0)
	s_barrier
; #define PG8_STAGE(bufoff, gbase, voff) do { _Pragma("unroll") for (int _i = 0; _i < 2; ++_i) \
;         __builtin_amdgcn_global_load_lds((const unsigned*)((const char*)(gbase) + (voff)[_i]), (LAS unsigned*)(lds + (bufoff) + ldsw + _i * 8192), 16, 0, 0); } while (0)
; #define PG8_LDA(dst, b, h) do { _Pragma("unroll") for (int m = 0; m < 4; ++m) _Pragma("unroll") for (int k = 0; k < 2; ++k) dst[m][k] = *(const LAS bf16x8*)(lds + PG8_SA(b, h) + aoff + m * 2048 + k * 1024); } while (0)
; #define PG8_LDB(dst, b, h) do { _Pragma("unroll") for (int n = 0; n < 2; ++n) _Pragma("unroll") for (int k = 0; k < 2; ++k) dst[n][k] = *(const LAS bf16x8*)(lds + PG8_SB(b, h) + boff + n * 2048 + k * 1024); } while (0)
; #define PG8_MMA(ai, bj, At, Bt) do { __builtin_amdgcn_s_setprio(1); _Pragma("unroll") for (int m = 0; m < 4; ++m) _Pragma("unroll") for (int n = 0; n < 2; ++n) _Pragma("unroll") for (int k = 0; k < 2; ++k) \
;         acc[ai][bj][m][n] = __builtin_amdgcn_mfma_f32_16x16x32_bf16(Bt[n][k], At[m][k], acc[ai][bj][m][n], 0, 0, 0); __builtin_amdgcn_s_setprio(0); } while (0)
; #define PG8_WAIT_V(n) asm volatile("s_waitcnt vmcnt(" #n ")" ::: "memory")
; #define PG8_WAIT_L(n) asm volatile("s_waitcnt lgkmcnt(" #n ")" ::: "memory")
; #define PG8_BAR __builtin_amdgcn_s_barrier()
; #define PG8_SCHED __builtin_amdgcn_sched_barrier(0)
; template <class Epi>
; __device__ __forceinline__ void gemm_phase(LAS unsigned char* lds, const Gemm g, const StaticOrder& S, const Epi& E, const int tid) {
;     ...
;             PG8_LDB(B0, 0, 0); PG8_LDB(B1, 0, 1); PG8_SCHED; PG8_LDA(At, 0, 0); PG8_STAGE(PG8_SA(1, 1), a1 + hstep, voffA);
;             PG8_WAIT_V(8); PG8_WAIT_L(0); PG8_BAR; PG8_MMA(0, 0, At, B0); PG8_MMA(0, 1, At, B1); PG8_BAR; PG8_SCHED;
;             PG8_LDA(At, 0, 1); PG8_STAGE(PG8_SB(0, 0), b2, voffB); PG8_STAGE(PG8_SB(0, 1), b2 + bhs, voffB); PG8_STAGE(PG8_SA(0, 0), a2, voffA);
;             PG8_WAIT_V(8); PG8_WAIT_L(0); PG8_BAR; PG8_MMA(1, 0, At, B0); PG8_MMA(1, 1, At, B1); PG8_BAR; PG8_SCHED;
	s_waitcnt lgkmcnt(0)
	v_mfma_f32_16x16x32_bf16 v[126:129], v[156:159], v[198:201], v[126:129]
	v_mfma_f32_16x16x32_bf16 v[122:125], v[164:167], v[198:201], v[122:125]
	v_mfma_f32_16x16x32_bf16 v[110:113], v[156:159], v[216:219], v[110:113]
	v_mfma_f32_16x16x32_bf16 v[106:109], v[164:167], v[216:219], v[106:109]
	v_mfma_f32_16x16x32_bf16 v[94:97], v[156:159], v[224:227], v[94:97]
	v_mfma_f32_16x16x32_bf16 v[90:93], v[164:167], v[224:227], v[90:93]
	v_mfma_f32_16x16x32_bf16 v[78:81], v[156:159], v[232:235], v[78:81]
	v_mfma_f32_16x16x32_bf16 v[74:77], v[164:167], v[232:235], v[74:77]
	v_mfma_f32_16x16x32_bf16 v[126:129], v[160:163], v[212:215], v[126:129]
	v_mfma_f32_16x16x32_bf16 v[122:125], v[178:181], v[212:215], v[122:125]
	v_mfma_f32_16x16x32_bf16 v[110:113], v[160:163], v[220:223], v[110:113]
	v_mfma_f32_16x16x32_bf16 v[106:109], v[178:181], v[220:223], v[106:109]
	v_mfma_f32_16x16x32_bf16 v[94:97], v[160:163], v[228:231], v[94:97]
	v_mfma_f32_16x16x32_bf16 v[90:93], v[178:181], v[228:231], v[90:93]
	v_mfma_f32_16x16x32_bf16 v[78:81], v[160:163], v[236:239], v[78:81]
	v_mfma_f32_16x16x32_bf16 v[74:77], v[178:181], v[236:239], v[74:77]
	v_mfma_f32_16x16x32_bf16 v[118:121], v[182:185], v[198:201], v[118:121]
	v_mfma_f32_16x16x32_bf16 v[114:117], v[190:193], v[198:201], v[114:117]
	v_mfma_f32_16x16x32_bf16 v[102:105], v[182:185], v[216:219], v[102:105]
	v_mfma_f32_16x16x32_bf16 v[98:101], v[190:193], v[216:219], v[98:101]
	v_mfma_f32_16x16x32_bf16 v[86:89], v[182:185], v[224:227], v[86:89]
	v_mfma_f32_16x16x32_bf16 v[82:85], v[190:193], v[224:227], v[82:85]
	v_mfma_f32_16x16x32_bf16 v[70:73], v[182:185], v[232:235], v[70:73]
	v_mfma_f32_16x16x32_bf16 v[66:69], v[190:193], v[232:235], v[66:69]
	v_mfma_f32_16x16x32_bf16 v[118:121], v[186:189], v[212:215], v[118:121]
	v_mfma_f32_16x16x32_bf16 v[114:117], v[194:197], v[212:215], v[114:117]
	v_mfma_f32_16x16x32_bf16 v[102:105], v[186:189], v[220:223], v[102:105]
	v_mfma_f32_16x16x32_bf16 v[98:101], v[194:197], v[220:223], v[98:101]
	v_mfma_f32_16x16x32_bf16 v[86:89], v[186:189], v[228:231], v[86:89]
	v_mfma_f32_16x16x32_bf16 v[82:85], v[194:197], v[228:231], v[82:85]
	v_mfma_f32_16x16x32_bf16 v[70:73], v[186:189], v[236:239], v[70:73]
	v_mfma_f32_16x16x32_bf16 v[66:69], v[194:197], v[236:239], v[66:69]
	s_barrier
	s_add_i32 s47, s47, s34
	v_lshl_add_u64 v[142:143], s[28:29], 0, v[0:1]
	s_mov_b32 m0, s47
	ds_read_b128 v[198:201], v154 offset:16384
	global_load_lds_dwordx4 v[142:143], off
	ds_read_b128 v[212:215], v154 offset:17408
	ds_read_b128 v[216:219], v154 offset:18432
	s_add_i32 m0, s47, 0x2000
	s_add_u32 s48, s28, 0x8000
	v_lshl_add_u64 v[168:169], s[28:29], 0, v[134:135]
	s_addc_u32 s49, s29, 0
	s_add_i32 s47, s50, s34
	global_load_lds_dwordx4 v[168:169], off
	ds_read_b128 v[220:223], v154 offset:19456
	ds_read_b128 v[224:227], v154 offset:20480
	v_lshl_add_u64 v[172:173], s[48:49], 0, v[0:1]
	s_mov_b32 m0, s47
	v_lshl_add_u64 v[174:175], s[30:31], 0, v[132:133]
	global_load_lds_dwordx4 v[172:173], off
	ds_read_b128 v[228:231], v154 offset:21504
	ds_read_b128 v[232:235], v154 offset:22528
	v_lshl_add_u64 v[172:173], s[48:49], 0, v[134:135]
	s_add_i32 m0, s47, 0x2000
	s_nop 0
	global_load_lds_dwordx4 v[172:173], off
	ds_read_b128 v[236:239], v154 offset:23552
	v_lshl_add_u64 v[172:173], s[30:31], 0, v[130:131]
	s_mov_b32 m0, s2
	s_nop 0
	global_load_lds_dwordx4 v[172:173], off
	s_mov_b32 m0, s25
	s_nop 0
	global_load_lds_dwordx4 v[174:175], off
	s_waitcnt vmcnt(8)
	s_waitcnt lgkmcnt(0)
	s_barrier
	s_waitcnt lgkmcnt(0)
	v_mfma_f32_16x16x32_bf16 v[62:65], v[156:159], v[198:201], v[62:65]
	v_mfma_f32_16x16x32_bf16 v[58:61], v[164:167], v[198:201], v[58:61]
	v_mfma_f32_16x16x32_bf16 v[46:49], v[156:159], v[216:219], v[46:49]
	v_mfma_f32_16x16x32_bf16 v[42:45], v[164:167], v[216:219], v[42:45]
	v_mfma_f32_16x16x32_bf16 v[30:33], v[156:159], v[224:227], v[30:33]
	v_mfma_f32_16x16x32_bf16 v[26:29], v[164:167], v[224:227], v[26:29]
	v_mfma_f32_16x16x32_bf16 v[14:17], v[156:159], v[232:235], v[14:17]
	v_mfma_f32_16x16x32_bf16 v[10:13], v[164:167], v[232:235], v[10:13]
	v_mfma_f32_16x16x32_bf16 v[62:65], v[160:163], v[212:215], v[62:65]
	v_mfma_f32_16x16x32_bf16 v[58:61], v[178:181], v[212:215], v[58:61]
	v_mfma_f32_16x16x32_bf16 v[46:49], v[160:163], v[220:223], v[46:49]
	v_mfma_f32_16x16x32_bf16 v[42:45], v[178:181], v[220:223], v[42:45]
	v_mfma_f32_16x16x32_bf16 v[30:33], v[160:163], v[228:231], v[30:33]
	v_mfma_f32_16x16x32_bf16 v[26:29], v[178:181], v[228:231], v[26:29]
	v_mfma_f32_16x16x32_bf16 v[14:17], v[160:163], v[236:239], v[14:17]
	v_mfma_f32_16x16x32_bf16 v[10:13], v[178:181], v[236:239], v[10:13]
	v_mfma_f32_16x16x32_bf16 v[54:57], v[182:185], v[198:201], v[54:57]
	v_mfma_f32_16x16x32_bf16 v[50:53], v[190:193], v[198:201], v[50:53]
	v_mfma_f32_16x16x32_bf16 v[38:41], v[182:185], v[216:219], v[38:41]
	v_mfma_f32_16x16x32_bf16 v[34:37], v[190:193], v[216:219], v[34:37]
	v_mfma_f32_16x16x32_bf16 v[22:25], v[182:185], v[224:227], v[22:25]
	v_mfma_f32_16x16x32_bf16 v[18:21], v[190:193], v[224:227], v[18:21]
	v_mfma_f32_16x16x32_bf16 v[6:9], v[182:185], v[232:235], v[6:9]
	v_mfma_f32_16x16x32_bf16 v[2:5], v[190:193], v[232:235], v[2:5]
	v_mfma_f32_16x16x32_bf16 v[54:57], v[186:189], v[212:215], v[54:57]
	v_mfma_f32_16x16x32_bf16 v[50:53], v[194:197], v[212:215], v[50:53]
	v_mfma_f32_16x16x32_bf16 v[38:41], v[186:189], v[220:223], v[38:41]
	v_mfma_f32_16x16x32_bf16 v[34:37], v[194:197], v[220:223], v[34:37]
	v_mfma_f32_16x16x32_bf16 v[22:25], v[186:189], v[228:231], v[22:25]
	v_mfma_f32_16x16x32_bf16 v[18:21], v[194:197], v[228:231], v[18:21]
	v_mfma_f32_16x16x32_bf16 v[6:9], v[186:189], v[236:239], v[6:9]
	v_mfma_f32_16x16x32_bf16 v[2:5], v[194:197], v[236:239], v[2:5]
	s_barrier
; #define PG8_STAGE(bufoff, gbase, voff) do { _Pragma("unroll") for (int _i = 0; _i < 2; ++_i) \
;         __builtin_amdgcn_global_load_lds((const unsigned*)((const char*)(gbase) + (voff)[_i]), (LAS unsigned*)(lds + (bufoff) + ldsw + _i * 8192), 16, 0, 0); } while (0)
; #define PG8_LDA(dst, b, h) do { _Pragma("unroll") for (int m = 0; m < 4; ++m) _Pragma("unroll") for (int k = 0; k < 2; ++k) dst[m][k] = *(const LAS bf16x8*)(lds + PG8_SA(b, h) + aoff + m * 2048 + k * 1024); } while (0)
; #define PG8_LDB(dst, b, h) do { _Pragma("unroll") for (int n = 0; n < 2; ++n) _Pragma("unroll") for (int k = 0; k < 2; ++k) dst[n][k] = *(const LAS bf16x8*)(lds + PG8_SB(b, h) + boff + n * 2048 + k * 1024); } while (0)
; #define PG8_MMA(ai, bj, At, Bt) do { __builtin_amdgcn_s_setprio(1); _Pragma("unroll") for (int m = 0; m < 4; ++m) _Pragma("unroll") for (int n = 0; n < 2; ++n) _Pragma("unroll") for (int k = 0; k < 2; ++k) \
;         acc[ai][bj][m][n] = __builtin_amdgcn_mfma_f32_16x16x32_bf16(Bt[n][k], At[m][k], acc[ai][bj][m][n], 0, 0, 0); __builtin_amdgcn_s_setprio(0); } while (0)
; #define PG8_WAIT_V(n) asm volatile("s_waitcnt vmcnt(" #n ")" ::: "memory")
; #define PG8_WAIT_L(n) asm volatile("s_waitcnt lgkmcnt(" #n ")" ::: "memory")
; #define PG8_BAR __builtin_amdgcn_s_barrier()
; #define PG8_SCHED __builtin_amdgcn_sched_barrier(0)
; template <class Epi>
; __device__ __forceinline__ void gemm_phase(LAS unsigned char* lds, const Gemm g, const StaticOrder& S, const Epi& E, const int tid) {
;     ...
;             PG8_LDB(B0, 1, 0); PG8_LDB(B1, 1, 1); PG8_SCHED; PG8_LDA(At, 1, 0); PG8_STAGE(PG8_SA(0, 1), a2 + hstep, voffA);
;             PG8_WAIT_V(8); PG8_WAIT_L(0); PG8_BAR; PG8_MMA(0, 0, At, B0); PG8_MMA(0, 1, At, B1); PG8_BAR; PG8_SCHED;
	s_add_i32 s47, 0, 0x18000
	v_add_u32_e32 v155, s47, v149
	s_add_i32 s48, 0, 0x1c000
	ds_read_b128 v[156:159], v155
	ds_read_b128 v[160:163], v155 offset:1024
	ds_read_b128 v[164:167], v155 offset:2048
	ds_read_b128 v[178:181], v155 offset:3072
	v_add_u32_e32 v155, s48, v149
	ds_read_b128 v[182:185], v155
	ds_read_b128 v[186:189], v155 offset:1024
	ds_read_b128 v[190:193], v155 offset:2048
	ds_read_b128 v[194:197], v155 offset:3072
	s_add_u32 s30, s30, 0x80000
	s_addc_u32 s31, s31, 0
	s_mov_b32 m0, s35
	v_lshl_add_u64 v[176:177], s[30:31], 0, v[130:131]
	ds_read_b128 v[198:201], v154 offset:32768
	global_load_lds_dwordx4 v[176:177], off
	ds_read_b128 v[212:215], v154 offset:33792
	ds_read_b128 v[216:219], v154 offset:34816
	v_lshl_add_u64 v[176:177], s[30:31], 0, v[132:133]
	s_mov_b32 m0, s36
	s_nop 0
	global_load_lds_dwordx4 v[176:177], off
	ds_read_b128 v[220:223], v154 offset:35840
	ds_read_b128 v[224:227], v154 offset:36864
	ds_read_b128 v[228:231], v154 offset:37888
	ds_read_b128 v[232:235], v154 offset:38912
	ds_read_b128 v[236:239], v154 offset:39936
	s_waitcnt vmcnt(8)
	s_waitcnt lgkmcnt(0)
	s_barrier
	s_waitcnt lgkmcnt(0)
	v_mfma_f32_16x16x32_bf16 v[126:129], v[156:159], v[198:201], v[126:129]
	v_mfma_f32_16x16x32_bf16 v[122:125], v[164:167], v[198:201], v[122:125]
	v_mfma_f32_16x16x32_bf16 v[110:113], v[156:159], v[216:219], v[110:113]
	v_mfma_f32_16x16x32_bf16 v[106:109], v[164:167], v[216:219], v[106:109]
	v_mfma_f32_16x16x32_bf16 v[94:97], v[156:159], v[224:227], v[94:97]
	v_mfma_f32_16x16x32_bf16 v[90:93], v[164:167], v[224:227], v[90:93]
	v_mfma_f32_16x16x32_bf16 v[78:81], v[156:159], v[232:235], v[78:81]
	v_mfma_f32_16x16x32_bf16 v[74:77], v[164:167], v[232:235], v[74:77]
	v_mfma_f32_16x16x32_bf16 v[126:129], v[160:163], v[212:215], v[126:129]
	v_mfma_f32_16x16x32_bf16 v[122:125], v[178:181], v[212:215], v[122:125]
	v_mfma_f32_16x16x32_bf16 v[110:113], v[160:163], v[220:223], v[110:113]
	v_mfma_f32_16x16x32_bf16 v[106:109], v[178:181], v[220:223], v[106:109]
	v_mfma_f32_16x16x32_bf16 v[94:97], v[160:163], v[228:231], v[94:97]
	v_mfma_f32_16x16x32_bf16 v[90:93], v[178:181], v[228:231], v[90:93]
	v_mfma_f32_16x16x32_bf16 v[78:81], v[160:163], v[236:239], v[78:81]
	v_mfma_f32_16x16x32_bf16 v[74:77], v[178:181], v[236:239], v[74:77]
	v_mfma_f32_16x16x32_bf16 v[118:121], v[182:185], v[198:201], v[118:121]
	v_mfma_f32_16x16x32_bf16 v[114:117], v[190:193], v[198:201], v[114:117]
	v_mfma_f32_16x16x32_bf16 v[102:105], v[182:185], v[216:219], v[102:105]
	v_mfma_f32_16x16x32_bf16 v[98:101], v[190:193], v[216:219], v[98:101]
	v_mfma_f32_16x16x32_bf16 v[86:89], v[182:185], v[224:227], v[86:89]
	v_mfma_f32_16x16x32_bf16 v[82:85], v[190:193], v[224:227], v[82:85]
	v_mfma_f32_16x16x32_bf16 v[70:73], v[182:185], v[232:235], v[70:73]
	v_mfma_f32_16x16x32_bf16 v[66:69], v[190:193], v[232:235], v[66:69]
	v_mfma_f32_16x16x32_bf16 v[118:121], v[186:189], v[212:215], v[118:121]
	v_mfma_f32_16x16x32_bf16 v[114:117], v[194:197], v[212:215], v[114:117]
	v_mfma_f32_16x16x32_bf16 v[102:105], v[186:189], v[220:223], v[102:105]
	v_mfma_f32_16x16x32_bf16 v[98:101], v[194:197], v[220:223], v[98:101]
	v_mfma_f32_16x16x32_bf16 v[86:89], v[186:189], v[228:231], v[86:89]
	v_mfma_f32_16x16x32_bf16 v[82:85], v[194:197], v[228:231], v[82:85]
	v_mfma_f32_16x16x32_bf16 v[70:73], v[186:189], v[236:239], v[70:73]
	v_mfma_f32_16x16x32_bf16 v[66:69], v[194:197], v[236:239], v[66:69]
	s_barrier
; #define PG8_STAGE(bufoff, gbase, voff) do { _Pragma("unroll") for (int _i = 0; _i < 2; ++_i) \
;         __builtin_amdgcn_global_load_lds((const unsigned*)((const char*)(gbase) + (voff)[_i]), (LAS unsigned*)(lds + (bufoff) + ldsw + _i * 8192), 16, 0, 0); } while (0)
; #define PG8_LDA(dst, b, h) do { _Pragma("unroll") for (int m = 0; m < 4; ++m) _Pragma("unroll") for (int k = 0; k < 2; ++k) dst[m][k] = *(const LAS bf16x8*)(lds + PG8_SA(b, h) + aoff + m * 2048 + k * 1024); } while (0)
; #define PG8_MMA(ai, bj, At, Bt) do { __builtin_amdgcn_s_setprio(1); _Pragma("unroll") for (int m = 0; m < 4; ++m) _Pragma("unroll") for (int n = 0; n < 2; ++n) _Pragma("unroll") for (int k = 0; k < 2; ++k) \
;         acc[ai][bj][m][n] = __builtin_amdgcn_mfma_f32_16x16x32_bf16(Bt[n][k], At[m][k], acc[ai][bj][m][n], 0, 0, 0); __builtin_amdgcn_s_setprio(0); } while (0)
; #define PG8_WAIT_V(n) asm volatile("s_waitcnt vmcnt(" #n ")" ::: "memory")
; #define PG8_WAIT_L(n) asm volatile("s_waitcnt lgkmcnt(" #n ")" ::: "memory")
; #define PG8_BAR __builtin_amdgcn_s_barrier()
; #define PG8_SCHED __builtin_amdgcn_sched_barrier(0)
; template <class Epi>
; __device__ __forceinline__ void gemm_phase(LAS unsigned char* lds, const Gemm g, const StaticOrder& S, const Epi& E, const int tid) {
;     ...
;             PG8_LDA(At, 1, 1); PG8_STAGE(PG8_SB(1, 0), b3, voffB); PG8_STAGE(PG8_SB(1, 1), b3 + bhs, voffB); PG8_STAGE(PG8_SA(1, 0), a3, voffA);
;             PG8_WAIT_V(8); PG8_WAIT_L(0); PG8_BAR; PG8_MMA(1, 0, At, B0); PG8_MMA(1, 1, At, B1); PG8_BAR; PG8_SCHED;
;     ...
;         if (ALIGN_EPI) { if (wr == 0) PG8_BAR; }
	s_add_i32 s30, s47, s34
	v_lshl_add_u64 v[142:143], v[142:143], 0, s[70:71]
	s_mov_b32 m0, s30
	ds_read_b128 v[198:201], v154 offset:49152
	global_load_lds_dwordx4 v[142:143], off
	ds_read_b128 v[212:215], v154 offset:50176
	ds_read_b128 v[216:219], v154 offset:51200
	s_add_i32 m0, s30, 0x2000
	s_add_u32 s28, s28, 0x8080
	v_lshl_add_u64 v[142:143], v[168:169], 0, s[70:71]
	s_addc_u32 s29, s29, 0
	s_add_i32 s30, s48, s34
	global_load_lds_dwordx4 v[142:143], off
	ds_read_b128 v[220:223], v154 offset:52224
	ds_read_b128 v[224:227], v154 offset:53248
	v_lshl_add_u64 v[142:143], s[28:29], 0, v[0:1]
	s_mov_b32 m0, s30
	s_nop 0
	global_load_lds_dwordx4 v[142:143], off
	ds_read_b128 v[228:231], v154 offset:54272
	ds_read_b128 v[232:235], v154 offset:55296
	v_lshl_add_u64 v[142:143], s[28:29], 0, v[134:135]
	s_add_i32 m0, s30, 0x2000
	s_nop 0
	global_load_lds_dwordx4 v[142:143], off
	ds_read_b128 v[236:239], v154 offset:56320
	v_lshl_add_u64 v[142:143], v[172:173], 0, s[70:71]
	s_mov_b32 m0, s37
	s_nop 0
	global_load_lds_dwordx4 v[142:143], off
	v_lshl_add_u64 v[142:143], v[174:175], 0, s[70:71]
	s_mov_b32 m0, s38
	s_nop 0
	global_load_lds_dwordx4 v[142:143], off
	s_waitcnt vmcnt(8)
	s_waitcnt lgkmcnt(0)
	s_barrier
	s_waitcnt lgkmcnt(0)
	v_mfma_f32_16x16x32_bf16 v[62:65], v[156:159], v[198:201], v[62:65]
	v_mfma_f32_16x16x32_bf16 v[58:61], v[164:167], v[198:201], v[58:61]
	v_mfma_f32_16x16x32_bf16 v[46:49], v[156:159], v[216:219], v[46:49]
	v_mfma_f32_16x16x32_bf16 v[42:45], v[164:167], v[216:219], v[42:45]
	v_mfma_f32_16x16x32_bf16 v[30:33], v[156:159], v[224:227], v[30:33]
	v_mfma_f32_16x16x32_bf16 v[26:29], v[164:167], v[224:227], v[26:29]
	v_mfma_f32_16x16x32_bf16 v[14:17], v[156:159], v[232:235], v[14:17]
	v_mfma_f32_16x16x32_bf16 v[10:13], v[164:167], v[232:235], v[10:13]
	v_mfma_f32_16x16x32_bf16 v[62:65], v[160:163], v[212:215], v[62:65]
	v_mfma_f32_16x16x32_bf16 v[58:61], v[178:181], v[212:215], v[58:61]
	v_mfma_f32_16x16x32_bf16 v[46:49], v[160:163], v[220:223], v[46:49]
	v_mfma_f32_16x16x32_bf16 v[42:45], v[178:181], v[220:223], v[42:45]
	v_mfma_f32_16x16x32_bf16 v[30:33], v[160:163], v[228:231], v[30:33]
	v_mfma_f32_16x16x32_bf16 v[26:29], v[178:181], v[228:231], v[26:29]
	v_mfma_f32_16x16x32_bf16 v[14:17], v[160:163], v[236:239], v[14:17]
	v_mfma_f32_16x16x32_bf16 v[10:13], v[178:181], v[236:239], v[10:13]
	v_mfma_f32_16x16x32_bf16 v[54:57], v[182:185], v[198:201], v[54:57]
	v_mfma_f32_16x16x32_bf16 v[50:53], v[190:193], v[198:201], v[50:53]
	v_mfma_f32_16x16x32_bf16 v[38:41], v[182:185], v[216:219], v[38:41]
	v_mfma_f32_16x16x32_bf16 v[34:37], v[190:193], v[216:219], v[34:37]
	v_mfma_f32_16x16x32_bf16 v[22:25], v[182:185], v[224:227], v[22:25]
	v_mfma_f32_16x16x32_bf16 v[18:21], v[190:193], v[224:227], v[18:21]
	v_mfma_f32_16x16x32_bf16 v[6:9], v[182:185], v[232:235], v[6:9]
	v_mfma_f32_16x16x32_bf16 v[2:5], v[190:193], v[232:235], v[2:5]
	v_mfma_f32_16x16x32_bf16 v[54:57], v[186:189], v[212:215], v[54:57]
	v_mfma_f32_16x16x32_bf16 v[50:53], v[194:197], v[212:215], v[50:53]
	v_mfma_f32_16x16x32_bf16 v[38:41], v[186:189], v[220:223], v[38:41]
	v_mfma_f32_16x16x32_bf16 v[34:37], v[194:197], v[220:223], v[34:37]
	v_mfma_f32_16x16x32_bf16 v[22:25], v[186:189], v[228:231], v[22:25]
	v_mfma_f32_16x16x32_bf16 v[18:21], v[194:197], v[228:231], v[18:21]
	v_mfma_f32_16x16x32_bf16 v[6:9], v[186:189], v[236:239], v[6:9]
	v_mfma_f32_16x16x32_bf16 v[2:5], v[194:197], v[236:239], v[2:5]
	s_barrier
	s_add_i32 s46, s46, 2
	s_add_u32 s44, s44, 0x100
	s_addc_u32 s45, s45, 0
	s_add_u32 s26, s26, 0x100
	s_addc_u32 s27, s27, 0
	s_cmp_gt_u32 s46, 29
	s_cbranch_scc0 .LBB0_173
	v_readlane_b32 s42, v251, 53
	s_and_b64 vcc, exec, s[12:13]
	v_readlane_b32 s43, v251, 54
	s_cbranch_vccz .LBB0_176
	s_barrier

; #define PG8_STAGE(bufoff, gbase, voff) do { _Pragma("unroll") for (int _i = 0; _i < 2; ++_i) \
;         __builtin_amdgcn_global_load_lds((const unsigned*)((const char*)(gbase) + (voff)[_i]), (LAS unsigned*)(lds + (bufoff) + ldsw + _i * 8192), 16, 0, 0); } while (0)
; #define PG8_LDA(dst, b, h) do { _Pragma("unroll") for (int m = 0; m < 4; ++m) _Pragma("unroll") for (int k = 0; k < 2; ++k) dst[m][k] = *(const LAS bf16x8*)(lds + PG8_SA(b, h) + aoff + m * 2048 + k * 1024); } while (0)
; #define PG8_LDB(dst, b, h) do { _Pragma("unroll") for (int n = 0; n < 2; ++n) _Pragma("unroll") for (int k = 0; k < 2; ++k) dst[n][k] = *(const LAS bf16x8*)(lds + PG8_SB(b, h) + boff + n * 2048 + k * 1024); } while (0)
; #define PG8_SCHED __builtin_amdgcn_sched_barrier(0)
; template <class Epi>
; __device__ __forceinline__ void gemm_phase(LAS unsigned char* lds, const Gemm g, const StaticOrder& S, const Epi& E, const int tid) {
;     ...
;         const bool has_next = S.next(ui + 1, nxt);
;         const char* nA = has_next ? (const char*)g.A + (size_t)nxt.pm * tstep : cA; const char* nB = has_next ? (const char*)g.Bt + (size_t)nxt.pn * tstep : cB;
;         for (int t = 0; t < ntt; t += 2) {
;             const bool last = (t == ntt - 2);
;             const bool s1 = Epi::TWO && (t >= nt), s2 = Epi::TWO && (t + 2 >= nt);
;             const char* a1 = (s1 ? cA2 + (size_t)(t - nt + 1) * kstep : cA + (size_t)(t + 1) * kstep);
;             const char* a2 = last ? nA : (s2 ? cA2 + (size_t)(t + 2 - nt) * kstep : cA + (size_t)(t + 2) * kstep);
;             const char* b2 = last ? nB : (s2 ? cB2 + (size_t)(t + 2 - nt) * kstep : cB + (size_t)(t + 2) * kstep);
;             const char* a3 = a2 + kstep; const char* b3 = b2 + kstep;
;             if constexpr (Epi::TWO) { if (t == nt) E.mid(acc, cur, wr, wc, fr, fq); }
;             if constexpr (SP2) {
;             PG8_LDB(B0, 0, 0); PG8_LDB(B1, 0, 1); PG8_SCHED; PG8_LDA(At, 0, 0); PG8_STAGE(PG8_SA(1, 1), a1 + hstep, voffA);
;     ...
; #pragma unroll
;         for (int a = 0; a < 2; ++a)
; #pragma unroll
;             for (int b = 0; b < 2; ++b)
; #pragma unroll
;                 for (int m = 0; m < 4; ++m)
; #pragma unroll
;                     for (int n = 0; n < 2; ++n) acc[a][b][m][n] = (f32x4){0.f, 0.f, 0.f, 0.f};
.LBB0_205:
	s_ashr_i32 s17, s16, 31
	s_lshl_b64 s[18:19], s[16:17], 18
	v_readlane_b32 s20, v251, 47
	v_readlane_b32 s21, v251, 48
	s_add_u32 s18, s20, s18
	s_addc_u32 s19, s21, s19
	s_and_b64 s[20:21], s[22:23], exec
	s_cselect_b32 s17, s19, s31
	s_cselect_b32 s27, s18, s30
	s_ashr_i32 s15, s14, 31
	s_lshl_b64 s[20:21], s[14:15], 18
	v_readlane_b32 s34, v251, 39
	v_readlane_b32 s35, v251, 40
	s_add_u32 s20, s34, s20
	s_addc_u32 s21, s35, s21
	s_and_b64 s[34:35], s[22:23], exec
	s_cselect_b32 s15, s21, s29
	s_cselect_b32 s33, s20, s28
	s_add_u32 s49, s28, 0x100
	s_addc_u32 s50, s29, 0
	s_add_u32 s28, s30, 0x20080
	v_mov_b32_e32 v2, 0
	s_addc_u32 s29, s31, 0
	s_mov_b32 s51, -2
	v_mov_b32_e32 v3, v2
	s_waitcnt lgkmcnt(0)
	v_mov_b32_e32 v4, v2
	v_mov_b32_e32 v5, v2
	v_mov_b32_e32 v6, v2
	v_mov_b32_e32 v7, v2
	v_mov_b32_e32 v8, v2
	v_mov_b32_e32 v9, v2
	v_mov_b32_e32 v34, v2
	v_mov_b32_e32 v35, v2
	v_mov_b32_e32 v36, v2
	v_mov_b32_e32 v37, v2
	v_mov_b32_e32 v38, v2
	v_mov_b32_e32 v39, v2
	v_mov_b32_e32 v40, v2
	v_mov_b32_e32 v41, v2
	v_mov_b32_e32 v66, v2
	v_mov_b32_e32 v67, v2
	v_mov_b32_e32 v68, v2
	v_mov_b32_e32 v69, v2
	v_mov_b32_e32 v70, v2
	v_mov_b32_e32 v71, v2
	v_mov_b32_e32 v72, v2
	v_mov_b32_e32 v73, v2
	v_mov_b32_e32 v82, v2
	v_mov_b32_e32 v83, v2
	v_mov_b32_e32 v84, v2
	v_mov_b32_e32 v85, v2
	v_mov_b32_e32 v86, v2
	v_mov_b32_e32 v87, v2
	v_mov_b32_e32 v88, v2
	v_mov_b32_e32 v89, v2
	v_mov_b32_e32 v10, v2
	v_mov_b32_e32 v11, v2
	v_mov_b32_e32 v12, v2
	v_mov_b32_e32 v13, v2
	v_mov_b32_e32 v14, v2
	v_mov_b32_e32 v15, v2
	v_mov_b32_e32 v16, v2
	v_mov_b32_e32 v17, v2
	v_mov_b32_e32 v58, v2
	v_mov_b32_e32 v59, v2
	v_mov_b32_e32 v60, v2
	v_mov_b32_e32 v61, v2
	v_mov_b32_e32 v62, v2
	v_mov_b32_e32 v63, v2
	v_mov_b32_e32 v64, v2
	v_mov_b32_e32 v65, v2
	v_mov_b32_e32 v74, v2
	v_mov_b32_e32 v75, v2
	v_mov_b32_e32 v76, v2
	v_mov_b32_e32 v77, v2
	v_mov_b32_e32 v78, v2
	v_mov_b32_e32 v79, v2
	v_mov_b32_e32 v80, v2
	v_mov_b32_e32 v81, v2
	v_mov_b32_e32 v90, v2
	v_mov_b32_e32 v91, v2
	v_mov_b32_e32 v92, v2
	v_mov_b32_e32 v93, v2
	v_mov_b32_e32 v94, v2
	v_mov_b32_e32 v95, v2
	v_mov_b32_e32 v96, v2
	v_mov_b32_e32 v97, v2
	v_mov_b32_e32 v98, v2
	v_mov_b32_e32 v99, v2
	v_mov_b32_e32 v100, v2
	v_mov_b32_e32 v101, v2
	v_mov_b32_e32 v102, v2
	v_mov_b32_e32 v103, v2
	v_mov_b32_e32 v104, v2
	v_mov_b32_e32 v105, v2
	v_mov_b32_e32 v114, v2
	v_mov_b32_e32 v115, v2
	v_mov_b32_e32 v116, v2
	v_mov_b32_e32 v117, v2
	v_mov_b32_e32 v118, v2
	v_mov_b32_e32 v119, v2
	v_mov_b32_e32 v120, v2
	v_mov_b32_e32 v121, v2
	v_mov_b32_e32 v130, v2
	v_mov_b32_e32 v131, v2
	v_mov_b32_e32 v132, v2
	v_mov_b32_e32 v133, v2
	v_mov_b32_e32 v134, v2
	v_mov_b32_e32 v135, v2
	v_mov_b32_e32 v136, v2
	v_mov_b32_e32 v137, v2
	v_mov_b32_e32 v146, v2
	v_mov_b32_e32 v147, v2
	v_mov_b32_e32 v148, v2
	v_mov_b32_e32 v149, v2
	v_mov_b32_e32 v150, v2
	v_mov_b32_e32 v151, v2
	v_mov_b32_e32 v152, v2
	v_mov_b32_e32 v153, v2
	v_mov_b32_e32 v106, v2
	v_mov_b32_e32 v107, v2
	v_mov_b32_e32 v108, v2
	v_mov_b32_e32 v109, v2
	v_mov_b32_e32 v110, v2
	v_mov_b32_e32 v111, v2
	v_mov_b32_e32 v112, v2
	v_mov_b32_e32 v113, v2
	v_mov_b32_e32 v122, v2
	v_mov_b32_e32 v123, v2
	v_mov_b32_e32 v124, v2
	v_mov_b32_e32 v125, v2
	v_mov_b32_e32 v126, v2
	v_mov_b32_e32 v127, v2
	v_mov_b32_e32 v128, v2
	v_mov_b32_e32 v129, v2
	v_mov_b32_e32 v138, v2
	v_mov_b32_e32 v139, v2
	v_mov_b32_e32 v140, v2
	v_mov_b32_e32 v141, v2
	v_mov_b32_e32 v142, v2
	v_mov_b32_e32 v143, v2
	v_mov_b32_e32 v144, v2
	v_mov_b32_e32 v145, v2
	v_mov_b32_e32 v154, v2
	v_mov_b32_e32 v155, v2
	v_mov_b32_e32 v156, v2
	v_mov_b32_e32 v157, v2
	v_mov_b32_e32 v158, v2
	v_mov_b32_e32 v159, v2
	v_mov_b32_e32 v160, v2
	v_mov_b32_e32 v161, v2
	s_and_b64 vcc, exec, s[12:13]
	s_cbranch_vccnz .Lprio_skip_206
	s_setprio 1
.Lprio_skip_206:
.LBB0_206:
	s_add_u32 s30, s28, 0xfffe0080
	s_addc_u32 s31, s29, -1
	s_add_i32 s52, 0, 0x10000
	s_cmp_eq_u32 s51, 4
	s_cselect_b32 s35, s17, s31
	s_cselect_b32 s34, s27, s30
	s_cselect_b32 s31, s15, s50
	s_cselect_b32 s30, s33, s49
	s_add_i32 s54, 0, 0x14000
	v_add_u32_e32 v30, s52, v193
	v_add_u32_e32 v54, s54, v193
	ds_read_b128 v[18:21], v30
	ds_read_b128 v[22:25], v30 offset:1024
	ds_read_b128 v[26:29], v30 offset:2048
	ds_read_b128 v[30:33], v30 offset:3072
	ds_read_b128 v[42:45], v54
	ds_read_b128 v[46:49], v54 offset:1024
	ds_read_b128 v[50:53], v54 offset:2048
	ds_read_b128 v[54:57], v54 offset:3072
	v_lshl_add_u64 v[172:173], s[28:29], 0, v[180:181]
	s_add_i32 m0, s37, 0xc000
	ds_read_b128 v[182:185], v199
	global_load_lds_dwordx4 v[172:173], off
	ds_read_b128 v[186:189], v199 offset:1024
	ds_read_b128 v[212:215], v199 offset:2048
	v_lshl_add_u64 v[172:173], s[28:29], 0, v[178:179]
	s_add_i32 m0, s37, 0xe000
	s_nop 0
	global_load_lds_dwordx4 v[172:173], off
	ds_read_b128 v[216:219], v199 offset:3072
	ds_read_b128 v[220:223], v199 offset:4096
	ds_read_b128 v[224:227], v199 offset:5120
	ds_read_b128 v[228:231], v199 offset:6144
	ds_read_b128 v[232:235], v199 offset:7168
	s_waitcnt vmcnt(8)
	s_waitcnt lgkmcnt(0)
	s_barrier
; #define PG8_STAGE(bufoff, gbase, voff) do { _Pragma("unroll") for (int _i = 0; _i < 2; ++_i) \
;         __builtin_amdgcn_global_load_lds((const unsigned*)((const char*)(gbase) + (voff)[_i]), (LAS unsigned*)(lds + (bufoff) + ldsw + _i * 8192), 16, 0, 0); } while (0)
; #define PG8_LDA(dst, b, h) do { _Pragma("unroll") for (int m = 0; m < 4; ++m) _Pragma("unroll") for (int k = 0; k < 2; ++k) dst[m][k] = *(const LAS bf16x8*)(lds + PG8_SA(b, h) + aoff + m * 2048 + k * 1024); } while (0)
; #define PG8_LDB(dst, b, h) do { _Pragma("unroll") for (int n = 0; n < 2; ++n) _Pragma("unroll") for (int k = 0; k < 2; ++k) dst[n][k] = *(const LAS bf16x8*)(lds + PG8_SB(b, h) + boff + n * 2048 + k * 1024); } while (0)
; #define PG8_MMA(ai, bj, At, Bt) do { __builtin_amdgcn_s_setprio(1); _Pragma("unroll") for (int m = 0; m < 4; ++m) _Pragma("unroll") for (int n = 0; n < 2; ++n) _Pragma("unroll") for (int k = 0; k < 2; ++k) \
;         acc[ai][bj][m][n] = __builtin_amdgcn_mfma_f32_16x16x32_bf16(Bt[n][k], At[m][k], acc[ai][bj][m][n], 0, 0, 0); __builtin_amdgcn_s_setprio(0); } while (0)
; #define PG8_WAIT_V(n) asm volatile("s_waitcnt vmcnt(" #n ")" ::: "memory")
; #define PG8_WAIT_L(n) asm volatile("s_waitcnt lgkmcnt(" #n ")" ::: "memory")
; #define PG8_BAR __builtin_amdgcn_s_barrier()
; #define PG8_SCHED __builtin_amdgcn_sched_barrier(0)
; template <class Epi>
; __device__ __forceinline__ void gemm_phase(LAS unsigned char* lds, const Gemm g, const StaticOrder& S, const Epi& E, const int tid) {
;     ...
;             PG8_LDB(B0, 0, 0); PG8_LDB(B1, 0, 1); PG8_SCHED; PG8_LDA(At, 0, 0); PG8_STAGE(PG8_SA(1, 1), a1 + hstep, voffA);
;             PG8_WAIT_V(8); PG8_WAIT_L(0); PG8_BAR; PG8_MMA(0, 0, At, B0); PG8_MMA(0, 1, At, B1); PG8_BAR; PG8_SCHED;
;             PG8_LDA(At, 0, 1); PG8_STAGE(PG8_SB(0, 0), b2, voffB); PG8_STAGE(PG8_SB(0, 1), b2 + bhs, voffB); PG8_STAGE(PG8_SA(0, 0), a2, voffA);
;             PG8_WAIT_V(8); PG8_WAIT_L(0); PG8_BAR; PG8_MMA(1, 0, At, B0); PG8_MMA(1, 1, At, B1); PG8_BAR; PG8_SCHED;
	s_waitcnt lgkmcnt(0)
	v_mfma_f32_16x16x32_bf16 v[158:161], v[18:21], v[182:185], v[158:161]
	v_mfma_f32_16x16x32_bf16 v[154:157], v[26:29], v[182:185], v[154:157]
	v_mfma_f32_16x16x32_bf16 v[142:145], v[18:21], v[212:215], v[142:145]
	v_mfma_f32_16x16x32_bf16 v[138:141], v[26:29], v[212:215], v[138:141]
	v_mfma_f32_16x16x32_bf16 v[126:129], v[18:21], v[220:223], v[126:129]
	v_mfma_f32_16x16x32_bf16 v[122:125], v[26:29], v[220:223], v[122:125]
	v_mfma_f32_16x16x32_bf16 v[110:113], v[18:21], v[228:231], v[110:113]
	v_mfma_f32_16x16x32_bf16 v[106:109], v[26:29], v[228:231], v[106:109]
	v_mfma_f32_16x16x32_bf16 v[158:161], v[22:25], v[186:189], v[158:161]
	v_mfma_f32_16x16x32_bf16 v[154:157], v[30:33], v[186:189], v[154:157]
	v_mfma_f32_16x16x32_bf16 v[142:145], v[22:25], v[216:219], v[142:145]
	v_mfma_f32_16x16x32_bf16 v[138:141], v[30:33], v[216:219], v[138:141]
	v_mfma_f32_16x16x32_bf16 v[126:129], v[22:25], v[224:227], v[126:129]
	v_mfma_f32_16x16x32_bf16 v[122:125], v[30:33], v[224:227], v[122:125]
	v_mfma_f32_16x16x32_bf16 v[110:113], v[22:25], v[232:235], v[110:113]
	v_mfma_f32_16x16x32_bf16 v[106:109], v[30:33], v[232:235], v[106:109]
	v_mfma_f32_16x16x32_bf16 v[150:153], v[42:45], v[182:185], v[150:153]
	v_mfma_f32_16x16x32_bf16 v[146:149], v[50:53], v[182:185], v[146:149]
	v_mfma_f32_16x16x32_bf16 v[134:137], v[42:45], v[212:215], v[134:137]
	v_mfma_f32_16x16x32_bf16 v[130:133], v[50:53], v[212:215], v[130:133]
	v_mfma_f32_16x16x32_bf16 v[118:121], v[42:45], v[220:223], v[118:121]
	v_mfma_f32_16x16x32_bf16 v[114:117], v[50:53], v[220:223], v[114:117]
	v_mfma_f32_16x16x32_bf16 v[102:105], v[42:45], v[228:231], v[102:105]
	v_mfma_f32_16x16x32_bf16 v[98:101], v[50:53], v[228:231], v[98:101]
	v_mfma_f32_16x16x32_bf16 v[150:153], v[46:49], v[186:189], v[150:153]
	v_mfma_f32_16x16x32_bf16 v[146:149], v[54:57], v[186:189], v[146:149]
	v_mfma_f32_16x16x32_bf16 v[134:137], v[46:49], v[216:219], v[134:137]
	v_mfma_f32_16x16x32_bf16 v[130:133], v[54:57], v[216:219], v[130:133]
	v_mfma_f32_16x16x32_bf16 v[118:121], v[46:49], v[224:227], v[118:121]
	v_mfma_f32_16x16x32_bf16 v[114:117], v[54:57], v[224:227], v[114:117]
	v_mfma_f32_16x16x32_bf16 v[102:105], v[46:49], v[232:235], v[102:105]
	v_mfma_f32_16x16x32_bf16 v[98:101], v[54:57], v[232:235], v[98:101]
	s_barrier
	s_add_i32 s52, s52, s36
	v_lshl_add_u64 v[172:173], s[30:31], 0, v[0:1]
	s_mov_b32 m0, s52
	ds_read_b128 v[182:185], v199 offset:16384
	global_load_lds_dwordx4 v[172:173], off
	ds_read_b128 v[186:189], v199 offset:17408
	ds_read_b128 v[212:215], v199 offset:18432
	s_add_i32 m0, s52, 0x2000
	s_add_u32 s52, s30, 0x2000
	v_lshl_add_u64 v[174:175], s[30:31], 0, v[166:167]
	s_addc_u32 s53, s31, 0
	s_add_i32 s54, s54, s36
	global_load_lds_dwordx4 v[174:175], off
	ds_read_b128 v[216:219], v199 offset:19456
	ds_read_b128 v[220:223], v199 offset:20480
	v_lshl_add_u64 v[176:177], s[52:53], 0, v[0:1]
	s_mov_b32 m0, s54
	v_lshl_add_u64 v[200:201], s[34:35], 0, v[164:165]
	global_load_lds_dwordx4 v[176:177], off
	ds_read_b128 v[224:227], v199 offset:21504
	ds_read_b128 v[228:231], v199 offset:22528
	v_lshl_add_u64 v[176:177], s[52:53], 0, v[166:167]
	s_add_i32 m0, s54, 0x2000
	s_nop 0
	global_load_lds_dwordx4 v[176:177], off
	ds_read_b128 v[232:235], v199 offset:23552
	v_lshl_add_u64 v[176:177], s[34:35], 0, v[162:163]
	s_mov_b32 m0, s37
	s_nop 0
	global_load_lds_dwordx4 v[176:177], off
	s_mov_b32 m0, s38
	s_nop 0
	global_load_lds_dwordx4 v[200:201], off
	s_waitcnt vmcnt(8)
	s_waitcnt lgkmcnt(0)
	s_barrier
	s_waitcnt lgkmcnt(0)
	v_mfma_f32_16x16x32_bf16 v[94:97], v[18:21], v[182:185], v[94:97]
	v_mfma_f32_16x16x32_bf16 v[90:93], v[26:29], v[182:185], v[90:93]
	v_mfma_f32_16x16x32_bf16 v[78:81], v[18:21], v[212:215], v[78:81]
	v_mfma_f32_16x16x32_bf16 v[74:77], v[26:29], v[212:215], v[74:77]
	v_mfma_f32_16x16x32_bf16 v[62:65], v[18:21], v[220:223], v[62:65]
	v_mfma_f32_16x16x32_bf16 v[58:61], v[26:29], v[220:223], v[58:61]
	v_mfma_f32_16x16x32_bf16 v[14:17], v[18:21], v[228:231], v[14:17]
	v_mfma_f32_16x16x32_bf16 v[10:13], v[26:29], v[228:231], v[10:13]
	v_mfma_f32_16x16x32_bf16 v[94:97], v[22:25], v[186:189], v[94:97]
	v_mfma_f32_16x16x32_bf16 v[90:93], v[30:33], v[186:189], v[90:93]
	v_mfma_f32_16x16x32_bf16 v[78:81], v[22:25], v[216:219], v[78:81]
	v_mfma_f32_16x16x32_bf16 v[74:77], v[30:33], v[216:219], v[74:77]
	v_mfma_f32_16x16x32_bf16 v[62:65], v[22:25], v[224:227], v[62:65]
	v_mfma_f32_16x16x32_bf16 v[58:61], v[30:33], v[224:227], v[58:61]
	v_mfma_f32_16x16x32_bf16 v[14:17], v[22:25], v[232:235], v[14:17]
	v_mfma_f32_16x16x32_bf16 v[10:13], v[30:33], v[232:235], v[10:13]
	v_mfma_f32_16x16x32_bf16 v[38:41], v[42:45], v[220:223], v[38:41]
	v_mfma_f32_16x16x32_bf16 v[34:37], v[50:53], v[220:223], v[34:37]
	v_mfma_f32_16x16x32_bf16 v[6:9], v[42:45], v[228:231], v[6:9]
	v_mfma_f32_16x16x32_bf16 v[2:5], v[50:53], v[228:231], v[2:5]
	v_mfma_f32_16x16x32_bf16 v[18:21], v[42:45], v[182:185], v[86:89]
	v_mfma_f32_16x16x32_bf16 v[22:25], v[50:53], v[182:185], v[82:85]
	v_mfma_f32_16x16x32_bf16 v[26:29], v[42:45], v[212:215], v[70:73]
	v_mfma_f32_16x16x32_bf16 v[30:33], v[50:53], v[212:215], v[66:69]
	v_mfma_f32_16x16x32_bf16 v[38:41], v[46:49], v[224:227], v[38:41]
	v_mfma_f32_16x16x32_bf16 v[34:37], v[54:57], v[224:227], v[34:37]
	v_mfma_f32_16x16x32_bf16 v[6:9], v[46:49], v[232:235], v[6:9]
	v_mfma_f32_16x16x32_bf16 v[2:5], v[54:57], v[232:235], v[2:5]
	v_mfma_f32_16x16x32_bf16 v[18:21], v[46:49], v[186:189], v[18:21]
	v_mfma_f32_16x16x32_bf16 v[22:25], v[54:57], v[186:189], v[22:25]
	v_mfma_f32_16x16x32_bf16 v[26:29], v[46:49], v[216:219], v[26:29]
	v_mfma_f32_16x16x32_bf16 v[30:33], v[54:57], v[216:219], v[30:33]
	s_barrier
; #define PG8_STAGE(bufoff, gbase, voff) do { _Pragma("unroll") for (int _i = 0; _i < 2; ++_i) \
;         __builtin_amdgcn_global_load_lds((const unsigned*)((const char*)(gbase) + (voff)[_i]), (LAS unsigned*)(lds + (bufoff) + ldsw + _i * 8192), 16, 0, 0); } while (0)
; #define PG8_LDA(dst, b, h) do { _Pragma("unroll") for (int m = 0; m < 4; ++m) _Pragma("unroll") for (int k = 0; k < 2; ++k) dst[m][k] = *(const LAS bf16x8*)(lds + PG8_SA(b, h) + aoff + m * 2048 + k * 1024); } while (0)
; #define PG8_LDB(dst, b, h) do { _Pragma("unroll") for (int n = 0; n < 2; ++n) _Pragma("unroll") for (int k = 0; k < 2; ++k) dst[n][k] = *(const LAS bf16x8*)(lds + PG8_SB(b, h) + boff + n * 2048 + k * 1024); } while (0)
; #define PG8_MMA(ai, bj, At, Bt) do { __builtin_amdgcn_s_setprio(1); _Pragma("unroll") for (int m = 0; m < 4; ++m) _Pragma("unroll") for (int n = 0; n < 2; ++n) _Pragma("unroll") for (int k = 0; k < 2; ++k) \
;         acc[ai][bj][m][n] = __builtin_amdgcn_mfma_f32_16x16x32_bf16(Bt[n][k], At[m][k], acc[ai][bj][m][n], 0, 0, 0); __builtin_amdgcn_s_setprio(0); } while (0)
; #define PG8_WAIT_V(n) asm volatile("s_waitcnt vmcnt(" #n ")" ::: "memory")
; #define PG8_WAIT_L(n) asm volatile("s_waitcnt lgkmcnt(" #n ")" ::: "memory")
; #define PG8_BAR __builtin_amdgcn_s_barrier()
; #define PG8_SCHED __builtin_amdgcn_sched_barrier(0)
; template <class Epi>
; __device__ __forceinline__ void gemm_phase(LAS unsigned char* lds, const Gemm g, const StaticOrder& S, const Epi& E, const int tid) {
;     ...
;             PG8_LDB(B0, 1, 0); PG8_LDB(B1, 1, 1); PG8_SCHED; PG8_LDA(At, 1, 0); PG8_STAGE(PG8_SA(0, 1), a2 + hstep, voffA);
;             PG8_WAIT_V(8); PG8_WAIT_L(0); PG8_BAR; PG8_MMA(0, 0, At, B0); PG8_MMA(0, 1, At, B1); PG8_BAR; PG8_SCHED;
;             PG8_LDA(At, 1, 1); PG8_STAGE(PG8_SB(1, 0), b3, voffB); PG8_STAGE(PG8_SB(1, 1), b3 + bhs, voffB); PG8_STAGE(PG8_SA(1, 0), a3, voffA);
;             PG8_WAIT_V(8); PG8_WAIT_L(0); PG8_BAR; PG8_MMA(1, 0, At, B0); PG8_MMA(1, 1, At, B1); PG8_BAR; PG8_SCHED;
;     ...
;         if (ALIGN_EPI) { if (wr == 0) PG8_BAR; }
	s_add_i32 s52, 0, 0x18000
	s_add_i32 s53, 0, 0x1c000
	v_add_u32_e32 v54, s52, v193
	v_add_u32_e32 v66, s53, v193
	ds_read_b128 v[42:45], v54
	ds_read_b128 v[46:49], v54 offset:1024
	ds_read_b128 v[50:53], v54 offset:2048
	ds_read_b128 v[54:57], v54 offset:3072
	ds_read_b128 v[182:185], v66
	ds_read_b128 v[186:189], v66 offset:1024
	ds_read_b128 v[212:215], v66 offset:2048
	ds_read_b128 v[216:219], v66 offset:3072
	s_add_u32 s34, s34, 0x20000
	s_addc_u32 s35, s35, 0
	s_mov_b32 m0, s39
	v_lshl_add_u64 v[236:237], s[34:35], 0, v[162:163]
	ds_read_b128 v[66:69], v199 offset:32768
	global_load_lds_dwordx4 v[236:237], off
	ds_read_b128 v[70:73], v199 offset:33792
	ds_read_b128 v[82:85], v199 offset:34816
	v_lshl_add_u64 v[236:237], s[34:35], 0, v[164:165]
	s_mov_b32 m0, s44
	s_nop 0
	global_load_lds_dwordx4 v[236:237], off
	ds_read_b128 v[86:89], v199 offset:35840
	ds_read_b128 v[220:223], v199 offset:36864
	ds_read_b128 v[224:227], v199 offset:37888
	ds_read_b128 v[228:231], v199 offset:38912
	ds_read_b128 v[232:235], v199 offset:39936
	s_waitcnt vmcnt(8)
	s_waitcnt lgkmcnt(0)
	s_barrier
	s_waitcnt lgkmcnt(0)
	v_mfma_f32_16x16x32_bf16 v[158:161], v[42:45], v[66:69], v[158:161]
	v_mfma_f32_16x16x32_bf16 v[154:157], v[50:53], v[66:69], v[154:157]
	v_mfma_f32_16x16x32_bf16 v[142:145], v[42:45], v[82:85], v[142:145]
	v_mfma_f32_16x16x32_bf16 v[138:141], v[50:53], v[82:85], v[138:141]
	v_mfma_f32_16x16x32_bf16 v[126:129], v[42:45], v[220:223], v[126:129]
	v_mfma_f32_16x16x32_bf16 v[122:125], v[50:53], v[220:223], v[122:125]
	v_mfma_f32_16x16x32_bf16 v[110:113], v[42:45], v[228:231], v[110:113]
	v_mfma_f32_16x16x32_bf16 v[106:109], v[50:53], v[228:231], v[106:109]
	v_mfma_f32_16x16x32_bf16 v[158:161], v[46:49], v[70:73], v[158:161]
	v_mfma_f32_16x16x32_bf16 v[154:157], v[54:57], v[70:73], v[154:157]
	v_mfma_f32_16x16x32_bf16 v[142:145], v[46:49], v[86:89], v[142:145]
	v_mfma_f32_16x16x32_bf16 v[138:141], v[54:57], v[86:89], v[138:141]
	v_mfma_f32_16x16x32_bf16 v[126:129], v[46:49], v[224:227], v[126:129]
	v_mfma_f32_16x16x32_bf16 v[122:125], v[54:57], v[224:227], v[122:125]
	v_mfma_f32_16x16x32_bf16 v[110:113], v[46:49], v[232:235], v[110:113]
	v_mfma_f32_16x16x32_bf16 v[106:109], v[54:57], v[232:235], v[106:109]
	v_mfma_f32_16x16x32_bf16 v[150:153], v[182:185], v[66:69], v[150:153]
	v_mfma_f32_16x16x32_bf16 v[66:69], v[212:215], v[66:69], v[146:149]
	v_mfma_f32_16x16x32_bf16 v[146:149], v[216:219], v[70:73], v[66:69]
	v_mfma_f32_16x16x32_bf16 v[66:69], v[182:185], v[82:85], v[134:137]
	v_mfma_f32_16x16x32_bf16 v[134:137], v[186:189], v[86:89], v[66:69]
	v_mfma_f32_16x16x32_bf16 v[66:69], v[212:215], v[82:85], v[130:133]
	v_mfma_f32_16x16x32_bf16 v[130:133], v[216:219], v[86:89], v[66:69]
	v_mfma_f32_16x16x32_bf16 v[66:69], v[182:185], v[220:223], v[118:121]
	v_mfma_f32_16x16x32_bf16 v[118:121], v[186:189], v[224:227], v[66:69]
	v_mfma_f32_16x16x32_bf16 v[66:69], v[212:215], v[220:223], v[114:117]
	v_mfma_f32_16x16x32_bf16 v[114:117], v[216:219], v[224:227], v[66:69]
	v_mfma_f32_16x16x32_bf16 v[66:69], v[182:185], v[228:231], v[102:105]
	v_mfma_f32_16x16x32_bf16 v[102:105], v[186:189], v[232:235], v[66:69]
	v_mfma_f32_16x16x32_bf16 v[66:69], v[212:215], v[228:231], v[98:101]
	v_mfma_f32_16x16x32_bf16 v[150:153], v[186:189], v[70:73], v[150:153]
	v_mfma_f32_16x16x32_bf16 v[98:101], v[216:219], v[232:235], v[66:69]
	s_barrier
	s_add_i32 s34, s52, s36
	v_lshl_add_u64 v[82:83], v[172:173], 0, s[70:71]
	s_mov_b32 m0, s34
	s_nop 0
	ds_read_b128 v[66:69], v199 offset:49152
	global_load_lds_dwordx4 v[82:83], off
	ds_read_b128 v[70:73], v199 offset:50176
	ds_read_b128 v[220:223], v199 offset:51200
	s_add_i32 m0, s34, 0x2000
	s_add_u32 s30, s30, 0x2080
	v_lshl_add_u64 v[82:83], v[174:175], 0, s[70:71]
	s_addc_u32 s31, s31, 0
	s_add_i32 s34, s53, s36
	global_load_lds_dwordx4 v[82:83], off
	ds_read_b128 v[224:227], v199 offset:52224
	ds_read_b128 v[228:231], v199 offset:53248
	v_lshl_add_u64 v[82:83], s[30:31], 0, v[0:1]
	s_mov_b32 m0, s34
	s_nop 0
	global_load_lds_dwordx4 v[82:83], off
	ds_read_b128 v[232:235], v199 offset:54272
	ds_read_b128 v[236:239], v199 offset:55296
	v_lshl_add_u64 v[82:83], s[30:31], 0, v[166:167]
	s_add_i32 m0, s34, 0x2000
	s_nop 0
	global_load_lds_dwordx4 v[82:83], off
	ds_read_b128 v[240:243], v199 offset:56320
	v_lshl_add_u64 v[82:83], v[176:177], 0, s[70:71]
	s_mov_b32 m0, s45
	s_nop 0
	global_load_lds_dwordx4 v[82:83], off
	v_lshl_add_u64 v[82:83], v[200:201], 0, s[70:71]
	s_mov_b32 m0, s46
	s_nop 0
	global_load_lds_dwordx4 v[82:83], off
	s_waitcnt vmcnt(8)
	s_waitcnt lgkmcnt(0)
	s_barrier
	s_waitcnt lgkmcnt(0)
	v_mfma_f32_16x16x32_bf16 v[82:85], v[42:45], v[66:69], v[94:97]
	v_mfma_f32_16x16x32_bf16 v[94:97], v[46:49], v[70:73], v[82:85]
	v_mfma_f32_16x16x32_bf16 v[82:85], v[50:53], v[66:69], v[90:93]
	v_mfma_f32_16x16x32_bf16 v[78:81], v[42:45], v[220:223], v[78:81]
	v_mfma_f32_16x16x32_bf16 v[74:77], v[50:53], v[220:223], v[74:77]
	v_mfma_f32_16x16x32_bf16 v[62:65], v[42:45], v[228:231], v[62:65]
	v_mfma_f32_16x16x32_bf16 v[58:61], v[50:53], v[228:231], v[58:61]
	v_mfma_f32_16x16x32_bf16 v[14:17], v[42:45], v[236:239], v[14:17]
	v_mfma_f32_16x16x32_bf16 v[10:13], v[50:53], v[236:239], v[10:13]
	v_mfma_f32_16x16x32_bf16 v[90:93], v[54:57], v[70:73], v[82:85]
	v_mfma_f32_16x16x32_bf16 v[78:81], v[46:49], v[224:227], v[78:81]
	v_mfma_f32_16x16x32_bf16 v[74:77], v[54:57], v[224:227], v[74:77]
	v_mfma_f32_16x16x32_bf16 v[62:65], v[46:49], v[232:235], v[62:65]
	v_mfma_f32_16x16x32_bf16 v[58:61], v[54:57], v[232:235], v[58:61]
	v_mfma_f32_16x16x32_bf16 v[14:17], v[46:49], v[240:243], v[14:17]
	v_mfma_f32_16x16x32_bf16 v[10:13], v[54:57], v[240:243], v[10:13]
	v_mfma_f32_16x16x32_bf16 v[18:21], v[182:185], v[66:69], v[18:21]
	v_mfma_f32_16x16x32_bf16 v[86:89], v[186:189], v[70:73], v[18:21]
	v_mfma_f32_16x16x32_bf16 v[18:21], v[212:215], v[66:69], v[22:25]
	v_mfma_f32_16x16x32_bf16 v[82:85], v[216:219], v[70:73], v[18:21]
	v_mfma_f32_16x16x32_bf16 v[18:21], v[182:185], v[220:223], v[26:29]
	v_mfma_f32_16x16x32_bf16 v[70:73], v[186:189], v[224:227], v[18:21]
	v_mfma_f32_16x16x32_bf16 v[18:21], v[212:215], v[220:223], v[30:33]
	v_mfma_f32_16x16x32_bf16 v[66:69], v[216:219], v[224:227], v[18:21]
	v_mfma_f32_16x16x32_bf16 v[18:21], v[182:185], v[228:231], v[38:41]
	v_mfma_f32_16x16x32_bf16 v[38:41], v[186:189], v[232:235], v[18:21]
	v_mfma_f32_16x16x32_bf16 v[18:21], v[212:215], v[228:231], v[34:37]
	v_mfma_f32_16x16x32_bf16 v[6:9], v[182:185], v[236:239], v[6:9]
	v_mfma_f32_16x16x32_bf16 v[2:5], v[212:215], v[236:239], v[2:5]
	v_mfma_f32_16x16x32_bf16 v[34:37], v[216:219], v[232:235], v[18:21]
	v_mfma_f32_16x16x32_bf16 v[6:9], v[186:189], v[240:243], v[6:9]
	v_mfma_f32_16x16x32_bf16 v[2:5], v[216:219], v[240:243], v[2:5]
	s_barrier
	s_add_i32 s51, s51, 2
	s_add_u32 s49, s49, 0x100
	s_addc_u32 s50, s50, 0
	s_add_u32 s28, s28, 0x100
	s_addc_u32 s29, s29, 0
	s_cmp_gt_u32 s51, 5
	s_cbranch_scc0 .LBB0_206
	s_and_b64 vcc, exec, s[12:13]
	s_cbranch_vccz .LBB0_209
	s_barrier

; #define PG8_STAGE(bufoff, gbase, voff) do { _Pragma("unroll") for (int _i = 0; _i < 2; ++_i) \
;         __builtin_amdgcn_global_load_lds((const unsigned*)((const char*)(gbase) + (voff)[_i]), (LAS unsigned*)(lds + (bufoff) + ldsw + _i * 8192), 16, 0, 0); } while (0)
; #define PG8_LDA(dst, b, h) do { _Pragma("unroll") for (int m = 0; m < 4; ++m) _Pragma("unroll") for (int k = 0; k < 2; ++k) dst[m][k] = *(const LAS bf16x8*)(lds + PG8_SA(b, h) + aoff + m * 2048 + k * 1024); } while (0)
; #define PG8_LDB(dst, b, h) do { _Pragma("unroll") for (int n = 0; n < 2; ++n) _Pragma("unroll") for (int k = 0; k < 2; ++k) dst[n][k] = *(const LAS bf16x8*)(lds + PG8_SB(b, h) + boff + n * 2048 + k * 1024); } while (0)
; #define PG8_BAR __builtin_amdgcn_s_barrier()
; template <class Epi>
; __device__ __forceinline__ void gemm_phase(LAS unsigned char* lds, const Gemm g, const StaticOrder& S, const Epi& E, const int tid) {
;     ...
;         const bool has_next = S.next(ui + 1, nxt);
;         const char* nA = has_next ? (const char*)g.A + (size_t)nxt.pm * tstep : cA; const char* nB = has_next ? (const char*)g.Bt + (size_t)nxt.pn * tstep : cB;
;         for (int t = 0; t < ntt; t += 2) {
;             const bool last = (t == ntt - 2);
;             const bool s1 = Epi::TWO && (t >= nt), s2 = Epi::TWO && (t + 2 >= nt);
;             const char* a1 = (s1 ? cA2 + (size_t)(t - nt + 1) * kstep : cA + (size_t)(t + 1) * kstep);
;             const char* a2 = last ? nA : (s2 ? cA2 + (size_t)(t + 2 - nt) * kstep : cA + (size_t)(t + 2) * kstep);
;             const char* b2 = last ? nB : (s2 ? cB2 + (size_t)(t + 2 - nt) * kstep : cB + (size_t)(t + 2) * kstep);
;             const char* a3 = a2 + kstep; const char* b3 = b2 + kstep;
;             if constexpr (Epi::TWO) { if (t == nt) E.mid(acc, cur, wr, wc, fr, fq); }
;             if constexpr (SP2) {
;             PG8_LDB(B0, 0, 0); PG8_LDB(B1, 0, 1); PG8_SCHED; PG8_LDA(At, 0, 0); PG8_STAGE(PG8_SA(1, 1), a1 + hstep, voffA);
;             PG8_WAIT_V(8); PG8_WAIT_L(0); PG8_BAR; PG8_MMA(0, 0, At, B0); PG8_MMA(0, 1, At, B1); PG8_BAR; PG8_SCHED;
;     ...
; #pragma unroll
;         for (int a = 0; a < 2; ++a)
; #pragma unroll
;             for (int b = 0; b < 2; ++b)
; #pragma unroll
;                 for (int m = 0; m < 4; ++m)
; #pragma unroll
;                     for (int n = 0; n < 2; ++n) acc[a][b][m][n] = (f32x4){0.f, 0.f, 0.f, 0.f};
.LBB0_260:
	s_ashr_i32 s19, s18, 31
	s_lshl_b64 s[20:21], s[18:19], 20
	v_readlane_b32 s22, v251, 31
	v_readlane_b32 s23, v251, 32
	s_add_u32 s20, s22, s20
	s_addc_u32 s21, s23, s21
	s_and_b64 s[22:23], s[24:25], exec
	s_cselect_b32 s19, s21, s31
	s_cselect_b32 s44, s20, s30
	s_ashr_i32 s17, s16, 31
	s_lshl_b64 s[22:23], s[16:17], 20
	v_readlane_b32 s34, v251, 37
	v_readlane_b32 s35, v251, 38
	s_add_u32 s22, s34, s22
	s_addc_u32 s23, s35, s23
	s_and_b64 s[34:35], s[24:25], exec
	s_cselect_b32 s17, s23, s29
	s_cselect_b32 s45, s22, s28
	s_add_u32 s46, s28, 0x100
	s_addc_u32 s47, s29, 0
	s_add_u32 s28, s30, 0x80080
	v_mov_b32_e32 v2, 0
	s_addc_u32 s29, s31, 0
	s_mov_b32 s48, -2
	v_mov_b32_e32 v3, v2
	v_mov_b32_e32 v4, v2
	v_mov_b32_e32 v5, v2
	v_mov_b32_e32 v6, v2
	v_mov_b32_e32 v7, v2
	v_mov_b32_e32 v8, v2
	v_mov_b32_e32 v9, v2
	v_mov_b32_e32 v18, v2
	v_mov_b32_e32 v19, v2
	v_mov_b32_e32 v20, v2
	v_mov_b32_e32 v21, v2
	v_mov_b32_e32 v22, v2
	v_mov_b32_e32 v23, v2
	v_mov_b32_e32 v24, v2
	v_mov_b32_e32 v25, v2
	v_mov_b32_e32 v34, v2
	v_mov_b32_e32 v35, v2
	v_mov_b32_e32 v36, v2
	v_mov_b32_e32 v37, v2
	v_mov_b32_e32 v38, v2
	v_mov_b32_e32 v39, v2
	v_mov_b32_e32 v40, v2
	v_mov_b32_e32 v41, v2
	v_mov_b32_e32 v50, v2
	v_mov_b32_e32 v51, v2
	v_mov_b32_e32 v52, v2
	v_mov_b32_e32 v53, v2
	v_mov_b32_e32 v54, v2
	v_mov_b32_e32 v55, v2
	v_mov_b32_e32 v56, v2
	v_mov_b32_e32 v57, v2
	v_mov_b32_e32 v10, v2
	v_mov_b32_e32 v11, v2
	v_mov_b32_e32 v12, v2
	v_mov_b32_e32 v13, v2
	v_mov_b32_e32 v14, v2
	v_mov_b32_e32 v15, v2
	v_mov_b32_e32 v16, v2
	v_mov_b32_e32 v17, v2
	v_mov_b32_e32 v26, v2
	v_mov_b32_e32 v27, v2
	v_mov_b32_e32 v28, v2
	v_mov_b32_e32 v29, v2
	v_mov_b32_e32 v30, v2
	v_mov_b32_e32 v31, v2
	v_mov_b32_e32 v32, v2
	v_mov_b32_e32 v33, v2
	v_mov_b32_e32 v42, v2
	v_mov_b32_e32 v43, v2
	v_mov_b32_e32 v44, v2
	v_mov_b32_e32 v45, v2
	v_mov_b32_e32 v46, v2
	v_mov_b32_e32 v47, v2
	v_mov_b32_e32 v48, v2
	v_mov_b32_e32 v49, v2
	v_mov_b32_e32 v58, v2
	v_mov_b32_e32 v59, v2
	v_mov_b32_e32 v60, v2
	v_mov_b32_e32 v61, v2
	v_mov_b32_e32 v62, v2
	v_mov_b32_e32 v63, v2
	v_mov_b32_e32 v64, v2
	v_mov_b32_e32 v65, v2
	v_mov_b32_e32 v66, v2
	v_mov_b32_e32 v67, v2
	v_mov_b32_e32 v68, v2
	v_mov_b32_e32 v69, v2
	v_mov_b32_e32 v70, v2
	v_mov_b32_e32 v71, v2
	v_mov_b32_e32 v72, v2
	v_mov_b32_e32 v73, v2
	v_mov_b32_e32 v82, v2
	v_mov_b32_e32 v83, v2
	v_mov_b32_e32 v84, v2
	v_mov_b32_e32 v85, v2
	v_mov_b32_e32 v86, v2
	v_mov_b32_e32 v87, v2
	v_mov_b32_e32 v88, v2
	v_mov_b32_e32 v89, v2
	v_mov_b32_e32 v98, v2
	v_mov_b32_e32 v99, v2
	v_mov_b32_e32 v100, v2
	v_mov_b32_e32 v101, v2
	v_mov_b32_e32 v102, v2
	v_mov_b32_e32 v103, v2
	v_mov_b32_e32 v104, v2
	v_mov_b32_e32 v105, v2
	v_mov_b32_e32 v114, v2
	v_mov_b32_e32 v115, v2
	v_mov_b32_e32 v116, v2
	v_mov_b32_e32 v117, v2
	v_mov_b32_e32 v118, v2
	v_mov_b32_e32 v119, v2
	v_mov_b32_e32 v120, v2
	v_mov_b32_e32 v121, v2
	v_mov_b32_e32 v74, v2
	v_mov_b32_e32 v75, v2
	v_mov_b32_e32 v76, v2
	v_mov_b32_e32 v77, v2
	v_mov_b32_e32 v78, v2
	v_mov_b32_e32 v79, v2
	v_mov_b32_e32 v80, v2
	v_mov_b32_e32 v81, v2
	v_mov_b32_e32 v90, v2
	v_mov_b32_e32 v91, v2
	v_mov_b32_e32 v92, v2
	v_mov_b32_e32 v93, v2
	v_mov_b32_e32 v94, v2
	v_mov_b32_e32 v95, v2
	v_mov_b32_e32 v96, v2
	v_mov_b32_e32 v97, v2
	v_mov_b32_e32 v106, v2
	v_mov_b32_e32 v107, v2
	v_mov_b32_e32 v108, v2
	v_mov_b32_e32 v109, v2
	v_mov_b32_e32 v110, v2
	v_mov_b32_e32 v111, v2
	v_mov_b32_e32 v112, v2
	v_mov_b32_e32 v113, v2
	v_mov_b32_e32 v122, v2
	v_mov_b32_e32 v123, v2
	v_mov_b32_e32 v124, v2
	v_mov_b32_e32 v125, v2
	v_mov_b32_e32 v126, v2
	v_mov_b32_e32 v127, v2
	v_mov_b32_e32 v128, v2
	v_mov_b32_e32 v129, v2
	s_and_b64 vcc, exec, s[14:15]
	s_cbranch_vccnz .Lprio_skip_261
	s_setprio 1
.Lprio_skip_261:
.LBB0_261:
	s_add_u32 s30, s28, 0xfff80080
	s_addc_u32 s31, s29, -1
	s_add_i32 s49, 0, 0x10000
	s_cmp_eq_u32 s48, 28
	s_cselect_b32 s35, s19, s31
	s_cselect_b32 s34, s44, s30
	v_add_u32_e32 v142, s49, v149
	s_cselect_b32 s31, s17, s47
	s_cselect_b32 s30, s45, s46
	s_add_i32 s52, 0, 0x14000
	ds_read_b128 v[156:159], v142
	ds_read_b128 v[160:163], v142 offset:1024
	ds_read_b128 v[164:167], v142 offset:2048
	ds_read_b128 v[178:181], v142 offset:3072
	v_add_u32_e32 v142, s52, v149
	ds_read_b128 v[182:185], v142
	ds_read_b128 v[186:189], v142 offset:1024
	ds_read_b128 v[190:193], v142 offset:2048
	ds_read_b128 v[194:197], v142 offset:3072
	v_lshl_add_u64 v[142:143], s[28:29], 0, v[140:141]
	s_add_i32 m0, s2, 0xc000
	ds_read_b128 v[198:201], v154
	global_load_lds_dwordx4 v[142:143], off
	ds_read_b128 v[212:215], v154 offset:1024
	ds_read_b128 v[216:219], v154 offset:2048
	v_lshl_add_u64 v[142:143], s[28:29], 0, v[138:139]
	s_add_i32 m0, s2, 0xe000
	s_nop 0
	global_load_lds_dwordx4 v[142:143], off
	ds_read_b128 v[220:223], v154 offset:3072
	ds_read_b128 v[224:227], v154 offset:4096
	ds_read_b128 v[228:231], v154 offset:5120
	ds_read_b128 v[232:235], v154 offset:6144
	ds_read_b128 v[236:239], v154 offset:7168
	s_waitcnt vmcnt(8)
	s_waitcnt lgkmcnt(0)
	s_barrier
; #define PG8_STAGE(bufoff, gbase, voff) do { _Pragma("unroll") for (int _i = 0; _i < 2; ++_i) \
;         __builtin_amdgcn_global_load_lds((const unsigned*)((const char*)(gbase) + (voff)[_i]), (LAS unsigned*)(lds + (bufoff) + ldsw + _i * 8192), 16, 0, 0); } while (0)
; #define PG8_LDA(dst, b, h) do { _Pragma("unroll") for (int m = 0; m < 4; ++m) _Pragma("unroll") for (int k = 0; k < 2; ++k) dst[m][k] = *(const LAS bf16x8*)(lds + PG8_SA(b, h) + aoff + m * 2048 + k * 1024); } while (0)
; #define PG8_MMA(ai, bj, At, Bt) do { __builtin_amdgcn_s_setprio(1); _Pragma("unroll") for (int m = 0; m < 4; ++m) _Pragma("unroll") for (int n = 0; n < 2; ++n) _Pragma("unroll") for (int k = 0; k < 2; ++k) \
;         acc[ai][bj][m][n] = __builtin_amdgcn_mfma_f32_16x16x32_bf16(Bt[n][k], At[m][k], acc[ai][bj][m][n], 0, 0, 0); __builtin_amdgcn_s_setprio(0); } while (0)
; #define PG8_WAIT_V(n) asm volatile("s_waitcnt vmcnt(" #n ")" ::: "memory")
; #define PG8_WAIT_L(n) asm volatile("s_waitcnt lgkmcnt(" #n ")" ::: "memory")
; #define PG8_BAR __builtin_amdgcn_s_barrier()
; #define PG8_SCHED __builtin_amdgcn_sched_barrier(0)
; template <class Epi>
; __device__ __forceinline__ void gemm_phase(LAS unsigned char* lds, const Gemm g, const StaticOrder& S, const Epi& E, const int tid) {
;     ...
;             PG8_WAIT_V(8); PG8_WAIT_L(0); PG8_BAR; PG8_MMA(0, 0, At, B0); PG8_MMA(0, 1, At, B1); PG8_BAR; PG8_SCHED;
;             PG8_LDA(At, 0, 1); PG8_STAGE(PG8_SB(0, 0), b2, voffB); PG8_STAGE(PG8_SB(0, 1), b2 + bhs, voffB); PG8_STAGE(PG8_SA(0, 0), a2, voffA);
;             PG8_WAIT_V(8); PG8_WAIT_L(0); PG8_BAR; PG8_MMA(1, 0, At, B0); PG8_MMA(1, 1, At, B1); PG8_BAR; PG8_SCHED;
	s_waitcnt lgkmcnt(0)
	v_mfma_f32_16x16x32_bf16 v[126:129], v[156:159], v[198:201], v[126:129]
	v_mfma_f32_16x16x32_bf16 v[122:125], v[164:167], v[198:201], v[122:125]
	v_mfma_f32_16x16x32_bf16 v[110:113], v[156:159], v[216:219], v[110:113]
	v_mfma_f32_16x16x32_bf16 v[106:109], v[164:167], v[216:219], v[106:109]
	v_mfma_f32_16x16x32_bf16 v[94:97], v[156:159], v[224:227], v[94:97]
	v_mfma_f32_16x16x32_bf16 v[90:93], v[164:167], v[224:227], v[90:93]
	v_mfma_f32_16x16x32_bf16 v[78:81], v[156:159], v[232:235], v[78:81]
	v_mfma_f32_16x16x32_bf16 v[74:77], v[164:167], v[232:235], v[74:77]
	v_mfma_f32_16x16x32_bf16 v[126:129], v[160:163], v[212:215], v[126:129]
	v_mfma_f32_16x16x32_bf16 v[122:125], v[178:181], v[212:215], v[122:125]
	v_mfma_f32_16x16x32_bf16 v[110:113], v[160:163], v[220:223], v[110:113]
	v_mfma_f32_16x16x32_bf16 v[106:109], v[178:181], v[220:223], v[106:109]
	v_mfma_f32_16x16x32_bf16 v[94:97], v[160:163], v[228:231], v[94:97]
	v_mfma_f32_16x16x32_bf16 v[90:93], v[178:181], v[228:231], v[90:93]
	v_mfma_f32_16x16x32_bf16 v[78:81], v[160:163], v[236:239], v[78:81]
	v_mfma_f32_16x16x32_bf16 v[74:77], v[178:181], v[236:239], v[74:77]
	v_mfma_f32_16x16x32_bf16 v[118:121], v[182:185], v[198:201], v[118:121]
	v_mfma_f32_16x16x32_bf16 v[114:117], v[190:193], v[198:201], v[114:117]
	v_mfma_f32_16x16x32_bf16 v[102:105], v[182:185], v[216:219], v[102:105]
	v_mfma_f32_16x16x32_bf16 v[98:101], v[190:193], v[216:219], v[98:101]
	v_mfma_f32_16x16x32_bf16 v[86:89], v[182:185], v[224:227], v[86:89]
	v_mfma_f32_16x16x32_bf16 v[82:85], v[190:193], v[224:227], v[82:85]
	v_mfma_f32_16x16x32_bf16 v[70:73], v[182:185], v[232:235], v[70:73]
	v_mfma_f32_16x16x32_bf16 v[66:69], v[190:193], v[232:235], v[66:69]
	v_mfma_f32_16x16x32_bf16 v[118:121], v[186:189], v[212:215], v[118:121]
	v_mfma_f32_16x16x32_bf16 v[114:117], v[194:197], v[212:215], v[114:117]
	v_mfma_f32_16x16x32_bf16 v[102:105], v[186:189], v[220:223], v[102:105]
	v_mfma_f32_16x16x32_bf16 v[98:101], v[194:197], v[220:223], v[98:101]
	v_mfma_f32_16x16x32_bf16 v[86:89], v[186:189], v[228:231], v[86:89]
	v_mfma_f32_16x16x32_bf16 v[82:85], v[194:197], v[228:231], v[82:85]
	v_mfma_f32_16x16x32_bf16 v[70:73], v[186:189], v[236:239], v[70:73]
	v_mfma_f32_16x16x32_bf16 v[66:69], v[194:197], v[236:239], v[66:69]
	s_barrier
	s_add_i32 s49, s49, s36
	v_lshl_add_u64 v[142:143], s[30:31], 0, v[0:1]
	s_mov_b32 m0, s49
	ds_read_b128 v[198:201], v154 offset:16384
	global_load_lds_dwordx4 v[142:143], off
	ds_read_b128 v[212:215], v154 offset:17408
	ds_read_b128 v[216:219], v154 offset:18432
	s_add_i32 m0, s49, 0x2000
	s_add_u32 s50, s30, 0x8000
	v_lshl_add_u64 v[168:169], s[30:31], 0, v[134:135]
	s_addc_u32 s51, s31, 0
	s_add_i32 s49, s52, s36
	global_load_lds_dwordx4 v[168:169], off
	ds_read_b128 v[220:223], v154 offset:19456
	ds_read_b128 v[224:227], v154 offset:20480
	v_lshl_add_u64 v[172:173], s[50:51], 0, v[0:1]
	s_mov_b32 m0, s49
	v_lshl_add_u64 v[174:175], s[34:35], 0, v[132:133]
	global_load_lds_dwordx4 v[172:173], off
	ds_read_b128 v[228:231], v154 offset:21504
	ds_read_b128 v[232:235], v154 offset:22528
	v_lshl_add_u64 v[172:173], s[50:51], 0, v[134:135]
	s_add_i32 m0, s49, 0x2000
	s_nop 0
	global_load_lds_dwordx4 v[172:173], off
	ds_read_b128 v[236:239], v154 offset:23552
	v_lshl_add_u64 v[172:173], s[34:35], 0, v[130:131]
	s_mov_b32 m0, s2
	s_nop 0
	global_load_lds_dwordx4 v[172:173], off
	s_mov_b32 m0, s27
	s_nop 0
	global_load_lds_dwordx4 v[174:175], off
	s_waitcnt vmcnt(8)
	s_waitcnt lgkmcnt(0)
	s_barrier
	s_waitcnt lgkmcnt(0)
	v_mfma_f32_16x16x32_bf16 v[62:65], v[156:159], v[198:201], v[62:65]
	v_mfma_f32_16x16x32_bf16 v[58:61], v[164:167], v[198:201], v[58:61]
	v_mfma_f32_16x16x32_bf16 v[46:49], v[156:159], v[216:219], v[46:49]
	v_mfma_f32_16x16x32_bf16 v[42:45], v[164:167], v[216:219], v[42:45]
	v_mfma_f32_16x16x32_bf16 v[30:33], v[156:159], v[224:227], v[30:33]
	v_mfma_f32_16x16x32_bf16 v[26:29], v[164:167], v[224:227], v[26:29]
	v_mfma_f32_16x16x32_bf16 v[14:17], v[156:159], v[232:235], v[14:17]
	v_mfma_f32_16x16x32_bf16 v[10:13], v[164:167], v[232:235], v[10:13]
	v_mfma_f32_16x16x32_bf16 v[62:65], v[160:163], v[212:215], v[62:65]
	v_mfma_f32_16x16x32_bf16 v[58:61], v[178:181], v[212:215], v[58:61]
	v_mfma_f32_16x16x32_bf16 v[46:49], v[160:163], v[220:223], v[46:49]
	v_mfma_f32_16x16x32_bf16 v[42:45], v[178:181], v[220:223], v[42:45]
	v_mfma_f32_16x16x32_bf16 v[30:33], v[160:163], v[228:231], v[30:33]
	v_mfma_f32_16x16x32_bf16 v[26:29], v[178:181], v[228:231], v[26:29]
	v_mfma_f32_16x16x32_bf16 v[14:17], v[160:163], v[236:239], v[14:17]
	v_mfma_f32_16x16x32_bf16 v[10:13], v[178:181], v[236:239], v[10:13]
	v_mfma_f32_16x16x32_bf16 v[54:57], v[182:185], v[198:201], v[54:57]
	v_mfma_f32_16x16x32_bf16 v[50:53], v[190:193], v[198:201], v[50:53]
	v_mfma_f32_16x16x32_bf16 v[38:41], v[182:185], v[216:219], v[38:41]
	v_mfma_f32_16x16x32_bf16 v[34:37], v[190:193], v[216:219], v[34:37]
	v_mfma_f32_16x16x32_bf16 v[22:25], v[182:185], v[224:227], v[22:25]
	v_mfma_f32_16x16x32_bf16 v[18:21], v[190:193], v[224:227], v[18:21]
	v_mfma_f32_16x16x32_bf16 v[6:9], v[182:185], v[232:235], v[6:9]
	v_mfma_f32_16x16x32_bf16 v[2:5], v[190:193], v[232:235], v[2:5]
	v_mfma_f32_16x16x32_bf16 v[54:57], v[186:189], v[212:215], v[54:57]
	v_mfma_f32_16x16x32_bf16 v[50:53], v[194:197], v[212:215], v[50:53]
	v_mfma_f32_16x16x32_bf16 v[38:41], v[186:189], v[220:223], v[38:41]
	v_mfma_f32_16x16x32_bf16 v[34:37], v[194:197], v[220:223], v[34:37]
	v_mfma_f32_16x16x32_bf16 v[22:25], v[186:189], v[228:231], v[22:25]
	v_mfma_f32_16x16x32_bf16 v[18:21], v[194:197], v[228:231], v[18:21]
	v_mfma_f32_16x16x32_bf16 v[6:9], v[186:189], v[236:239], v[6:9]
	v_mfma_f32_16x16x32_bf16 v[2:5], v[194:197], v[236:239], v[2:5]
	s_barrier
; #define PG8_STAGE(bufoff, gbase, voff) do { _Pragma("unroll") for (int _i = 0; _i < 2; ++_i) \
;         __builtin_amdgcn_global_load_lds((const unsigned*)((const char*)(gbase) + (voff)[_i]), (LAS unsigned*)(lds + (bufoff) + ldsw + _i * 8192), 16, 0, 0); } while (0)
; #define PG8_LDA(dst, b, h) do { _Pragma("unroll") for (int m = 0; m < 4; ++m) _Pragma("unroll") for (int k = 0; k < 2; ++k) dst[m][k] = *(const LAS bf16x8*)(lds + PG8_SA(b, h) + aoff + m * 2048 + k * 1024); } while (0)
; #define PG8_LDB(dst, b, h) do { _Pragma("unroll") for (int n = 0; n < 2; ++n) _Pragma("unroll") for (int k = 0; k < 2; ++k) dst[n][k] = *(const LAS bf16x8*)(lds + PG8_SB(b, h) + boff + n * 2048 + k * 1024); } while (0)
; #define PG8_MMA(ai, bj, At, Bt) do { __builtin_amdgcn_s_setprio(1); _Pragma("unroll") for (int m = 0; m < 4; ++m) _Pragma("unroll") for (int n = 0; n < 2; ++n) _Pragma("unroll") for (int k = 0; k < 2; ++k) \
;         acc[ai][bj][m][n] = __builtin_amdgcn_mfma_f32_16x16x32_bf16(Bt[n][k], At[m][k], acc[ai][bj][m][n], 0, 0, 0); __builtin_amdgcn_s_setprio(0); } while (0)
; #define PG8_WAIT_V(n) asm volatile("s_waitcnt vmcnt(" #n ")" ::: "memory")
; #define PG8_WAIT_L(n) asm volatile("s_waitcnt lgkmcnt(" #n ")" ::: "memory")
; #define PG8_BAR __builtin_amdgcn_s_barrier()
; #define PG8_SCHED __builtin_amdgcn_sched_barrier(0)
; template <class Epi>
; __device__ __forceinline__ void gemm_phase(LAS unsigned char* lds, const Gemm g, const StaticOrder& S, const Epi& E, const int tid) {
;     ...
;             PG8_LDB(B0, 1, 0); PG8_LDB(B1, 1, 1); PG8_SCHED; PG8_LDA(At, 1, 0); PG8_STAGE(PG8_SA(0, 1), a2 + hstep, voffA);
;             PG8_WAIT_V(8); PG8_WAIT_L(0); PG8_BAR; PG8_MMA(0, 0, At, B0); PG8_MMA(0, 1, At, B1); PG8_BAR; PG8_SCHED;
	s_add_i32 s49, 0, 0x18000
	v_add_u32_e32 v155, s49, v149
	s_add_i32 s50, 0, 0x1c000
	ds_read_b128 v[156:159], v155
	ds_read_b128 v[160:163], v155 offset:1024
	ds_read_b128 v[164:167], v155 offset:2048
	ds_read_b128 v[178:181], v155 offset:3072
	v_add_u32_e32 v155, s50, v149
	ds_read_b128 v[182:185], v155
	ds_read_b128 v[186:189], v155 offset:1024
	ds_read_b128 v[190:193], v155 offset:2048
	ds_read_b128 v[194:197], v155 offset:3072
	s_add_u32 s34, s34, 0x80000
	s_addc_u32 s35, s35, 0
	s_mov_b32 m0, s37
	v_lshl_add_u64 v[176:177], s[34:35], 0, v[130:131]
	ds_read_b128 v[198:201], v154 offset:32768
	global_load_lds_dwordx4 v[176:177], off
	ds_read_b128 v[212:215], v154 offset:33792
	ds_read_b128 v[216:219], v154 offset:34816
	v_lshl_add_u64 v[176:177], s[34:35], 0, v[132:133]
	s_mov_b32 m0, s38
	s_nop 0
	global_load_lds_dwordx4 v[176:177], off
	ds_read_b128 v[220:223], v154 offset:35840
	ds_read_b128 v[224:227], v154 offset:36864
	ds_read_b128 v[228:231], v154 offset:37888
	ds_read_b128 v[232:235], v154 offset:38912
	ds_read_b128 v[236:239], v154 offset:39936
	s_waitcnt vmcnt(8)
	s_waitcnt lgkmcnt(0)
	s_barrier
	s_waitcnt lgkmcnt(0)
	v_mfma_f32_16x16x32_bf16 v[126:129], v[156:159], v[198:201], v[126:129]
	v_mfma_f32_16x16x32_bf16 v[122:125], v[164:167], v[198:201], v[122:125]
	v_mfma_f32_16x16x32_bf16 v[110:113], v[156:159], v[216:219], v[110:113]
	v_mfma_f32_16x16x32_bf16 v[106:109], v[164:167], v[216:219], v[106:109]
	v_mfma_f32_16x16x32_bf16 v[94:97], v[156:159], v[224:227], v[94:97]
	v_mfma_f32_16x16x32_bf16 v[90:93], v[164:167], v[224:227], v[90:93]
	v_mfma_f32_16x16x32_bf16 v[78:81], v[156:159], v[232:235], v[78:81]
	v_mfma_f32_16x16x32_bf16 v[74:77], v[164:167], v[232:235], v[74:77]
	v_mfma_f32_16x16x32_bf16 v[126:129], v[160:163], v[212:215], v[126:129]
	v_mfma_f32_16x16x32_bf16 v[122:125], v[178:181], v[212:215], v[122:125]
	v_mfma_f32_16x16x32_bf16 v[110:113], v[160:163], v[220:223], v[110:113]
	v_mfma_f32_16x16x32_bf16 v[106:109], v[178:181], v[220:223], v[106:109]
	v_mfma_f32_16x16x32_bf16 v[94:97], v[160:163], v[228:231], v[94:97]
	v_mfma_f32_16x16x32_bf16 v[90:93], v[178:181], v[228:231], v[90:93]
	v_mfma_f32_16x16x32_bf16 v[78:81], v[160:163], v[236:239], v[78:81]
	v_mfma_f32_16x16x32_bf16 v[74:77], v[178:181], v[236:239], v[74:77]
	v_mfma_f32_16x16x32_bf16 v[118:121], v[182:185], v[198:201], v[118:121]
	v_mfma_f32_16x16x32_bf16 v[114:117], v[190:193], v[198:201], v[114:117]
	v_mfma_f32_16x16x32_bf16 v[102:105], v[182:185], v[216:219], v[102:105]
	v_mfma_f32_16x16x32_bf16 v[98:101], v[190:193], v[216:219], v[98:101]
	v_mfma_f32_16x16x32_bf16 v[86:89], v[182:185], v[224:227], v[86:89]
	v_mfma_f32_16x16x32_bf16 v[82:85], v[190:193], v[224:227], v[82:85]
	v_mfma_f32_16x16x32_bf16 v[70:73], v[182:185], v[232:235], v[70:73]
	v_mfma_f32_16x16x32_bf16 v[66:69], v[190:193], v[232:235], v[66:69]
	v_mfma_f32_16x16x32_bf16 v[118:121], v[186:189], v[212:215], v[118:121]
	v_mfma_f32_16x16x32_bf16 v[114:117], v[194:197], v[212:215], v[114:117]
	v_mfma_f32_16x16x32_bf16 v[102:105], v[186:189], v[220:223], v[102:105]
	v_mfma_f32_16x16x32_bf16 v[98:101], v[194:197], v[220:223], v[98:101]
	v_mfma_f32_16x16x32_bf16 v[86:89], v[186:189], v[228:231], v[86:89]
	v_mfma_f32_16x16x32_bf16 v[82:85], v[194:197], v[228:231], v[82:85]
	v_mfma_f32_16x16x32_bf16 v[70:73], v[186:189], v[236:239], v[70:73]
	v_mfma_f32_16x16x32_bf16 v[66:69], v[194:197], v[236:239], v[66:69]
	s_barrier
; #define PG8_STAGE(bufoff, gbase, voff) do { _Pragma("unroll") for (int _i = 0; _i < 2; ++_i) \
;         __builtin_amdgcn_global_load_lds((const unsigned*)((const char*)(gbase) + (voff)[_i]), (LAS unsigned*)(lds + (bufoff) + ldsw + _i * 8192), 16, 0, 0); } while (0)
; #define PG8_LDA(dst, b, h) do { _Pragma("unroll") for (int m = 0; m < 4; ++m) _Pragma("unroll") for (int k = 0; k < 2; ++k) dst[m][k] = *(const LAS bf16x8*)(lds + PG8_SA(b, h) + aoff + m * 2048 + k * 1024); } while (0)
; #define PG8_MMA(ai, bj, At, Bt) do { __builtin_amdgcn_s_setprio(1); _Pragma("unroll") for (int m = 0; m < 4; ++m) _Pragma("unroll") for (int n = 0; n < 2; ++n) _Pragma("unroll") for (int k = 0; k < 2; ++k) \
;         acc[ai][bj][m][n] = __builtin_amdgcn_mfma_f32_16x16x32_bf16(Bt[n][k], At[m][k], acc[ai][bj][m][n], 0, 0, 0); __builtin_amdgcn_s_setprio(0); } while (0)
; #define PG8_WAIT_V(n) asm volatile("s_waitcnt vmcnt(" #n ")" ::: "memory")
; #define PG8_WAIT_L(n) asm volatile("s_waitcnt lgkmcnt(" #n ")" ::: "memory")
; #define PG8_BAR __builtin_amdgcn_s_barrier()
; #define PG8_SCHED __builtin_amdgcn_sched_barrier(0)
; template <class Epi>
; __device__ __forceinline__ void gemm_phase(LAS unsigned char* lds, const Gemm g, const StaticOrder& S, const Epi& E, const int tid) {
;     ...
;             PG8_LDA(At, 1, 1); PG8_STAGE(PG8_SB(1, 0), b3, voffB); PG8_STAGE(PG8_SB(1, 1), b3 + bhs, voffB); PG8_STAGE(PG8_SA(1, 0), a3, voffA);
;             PG8_WAIT_V(8); PG8_WAIT_L(0); PG8_BAR; PG8_MMA(1, 0, At, B0); PG8_MMA(1, 1, At, B1); PG8_BAR; PG8_SCHED;
;     ...
;         if (ALIGN_EPI) { if (wr == 0) PG8_BAR; }
	s_add_i32 s34, s49, s36
	v_lshl_add_u64 v[142:143], v[142:143], 0, s[70:71]
	s_mov_b32 m0, s34
	ds_read_b128 v[198:201], v154 offset:49152
	global_load_lds_dwordx4 v[142:143], off
	ds_read_b128 v[212:215], v154 offset:50176
	ds_read_b128 v[216:219], v154 offset:51200
	s_add_i32 m0, s34, 0x2000
	s_add_u32 s30, s30, 0x8080
	v_lshl_add_u64 v[142:143], v[168:169], 0, s[70:71]
	s_addc_u32 s31, s31, 0
	s_add_i32 s34, s50, s36
	global_load_lds_dwordx4 v[142:143], off
	ds_read_b128 v[220:223], v154 offset:52224
	ds_read_b128 v[224:227], v154 offset:53248
	v_lshl_add_u64 v[142:143], s[30:31], 0, v[0:1]
	s_mov_b32 m0, s34
	s_nop 0
	global_load_lds_dwordx4 v[142:143], off
	ds_read_b128 v[228:231], v154 offset:54272
	ds_read_b128 v[232:235], v154 offset:55296
	v_lshl_add_u64 v[142:143], s[30:31], 0, v[134:135]
	s_add_i32 m0, s34, 0x2000
	s_nop 0
	global_load_lds_dwordx4 v[142:143], off
	ds_read_b128 v[236:239], v154 offset:56320
	v_lshl_add_u64 v[142:143], v[172:173], 0, s[70:71]
	s_mov_b32 m0, s39
	s_nop 0
	global_load_lds_dwordx4 v[142:143], off
	v_lshl_add_u64 v[142:143], v[174:175], 0, s[70:71]
	s_mov_b32 m0, s40
	s_nop 0
	global_load_lds_dwordx4 v[142:143], off
	s_waitcnt vmcnt(8)
	s_waitcnt lgkmcnt(0)
	s_barrier
	s_waitcnt lgkmcnt(0)
	v_mfma_f32_16x16x32_bf16 v[62:65], v[156:159], v[198:201], v[62:65]
	v_mfma_f32_16x16x32_bf16 v[58:61], v[164:167], v[198:201], v[58:61]
	v_mfma_f32_16x16x32_bf16 v[46:49], v[156:159], v[216:219], v[46:49]
	v_mfma_f32_16x16x32_bf16 v[42:45], v[164:167], v[216:219], v[42:45]
	v_mfma_f32_16x16x32_bf16 v[30:33], v[156:159], v[224:227], v[30:33]
	v_mfma_f32_16x16x32_bf16 v[26:29], v[164:167], v[224:227], v[26:29]
	v_mfma_f32_16x16x32_bf16 v[14:17], v[156:159], v[232:235], v[14:17]
	v_mfma_f32_16x16x32_bf16 v[10:13], v[164:167], v[232:235], v[10:13]
	v_mfma_f32_16x16x32_bf16 v[62:65], v[160:163], v[212:215], v[62:65]
	v_mfma_f32_16x16x32_bf16 v[58:61], v[178:181], v[212:215], v[58:61]
	v_mfma_f32_16x16x32_bf16 v[46:49], v[160:163], v[220:223], v[46:49]
	v_mfma_f32_16x16x32_bf16 v[42:45], v[178:181], v[220:223], v[42:45]
	v_mfma_f32_16x16x32_bf16 v[30:33], v[160:163], v[228:231], v[30:33]
	v_mfma_f32_16x16x32_bf16 v[26:29], v[178:181], v[228:231], v[26:29]
	v_mfma_f32_16x16x32_bf16 v[14:17], v[160:163], v[236:239], v[14:17]
	v_mfma_f32_16x16x32_bf16 v[10:13], v[178:181], v[236:239], v[10:13]
	v_mfma_f32_16x16x32_bf16 v[54:57], v[182:185], v[198:201], v[54:57]
	v_mfma_f32_16x16x32_bf16 v[50:53], v[190:193], v[198:201], v[50:53]
	v_mfma_f32_16x16x32_bf16 v[38:41], v[182:185], v[216:219], v[38:41]
	v_mfma_f32_16x16x32_bf16 v[34:37], v[190:193], v[216:219], v[34:37]
	v_mfma_f32_16x16x32_bf16 v[22:25], v[182:185], v[224:227], v[22:25]
	v_mfma_f32_16x16x32_bf16 v[18:21], v[190:193], v[224:227], v[18:21]
	v_mfma_f32_16x16x32_bf16 v[6:9], v[182:185], v[232:235], v[6:9]
	v_mfma_f32_16x16x32_bf16 v[2:5], v[190:193], v[232:235], v[2:5]
	v_mfma_f32_16x16x32_bf16 v[54:57], v[186:189], v[212:215], v[54:57]
	v_mfma_f32_16x16x32_bf16 v[50:53], v[194:197], v[212:215], v[50:53]
	v_mfma_f32_16x16x32_bf16 v[38:41], v[186:189], v[220:223], v[38:41]
	v_mfma_f32_16x16x32_bf16 v[34:37], v[194:197], v[220:223], v[34:37]
	v_mfma_f32_16x16x32_bf16 v[22:25], v[186:189], v[228:231], v[22:25]
	v_mfma_f32_16x16x32_bf16 v[18:21], v[194:197], v[228:231], v[18:21]
	v_mfma_f32_16x16x32_bf16 v[6:9], v[186:189], v[236:239], v[6:9]
	v_mfma_f32_16x16x32_bf16 v[2:5], v[194:197], v[236:239], v[2:5]
	s_barrier
	s_add_i32 s48, s48, 2
	s_add_u32 s46, s46, 0x100
	s_addc_u32 s47, s47, 0
	s_add_u32 s28, s28, 0x100
	s_addc_u32 s29, s29, 0
	s_cmp_gt_u32 s48, 29
	s_cbranch_scc0 .LBB0_261
	s_and_b64 vcc, exec, s[14:15]
	s_cbranch_vccz .LBB0_264
	s_barrier

; #define PG8_STAGE(bufoff, gbase, voff) do { _Pragma("unroll") for (int _i = 0; _i < 2; ++_i) \
;         __builtin_amdgcn_global_load_lds((const unsigned*)((const char*)(gbase) + (voff)[_i]), (LAS unsigned*)(lds + (bufoff) + ldsw + _i * 8192), 16, 0, 0); } while (0)
; #define PG8_LDA(dst, b, h) do { _Pragma("unroll") for (int m = 0; m < 4; ++m) _Pragma("unroll") for (int k = 0; k < 2; ++k) dst[m][k] = *(const LAS bf16x8*)(lds + PG8_SA(b, h) + aoff + m * 2048 + k * 1024); } while (0)
; #define PG8_LDB(dst, b, h) do { _Pragma("unroll") for (int n = 0; n < 2; ++n) _Pragma("unroll") for (int k = 0; k < 2; ++k) dst[n][k] = *(const LAS bf16x8*)(lds + PG8_SB(b, h) + boff + n * 2048 + k * 1024); } while (0)
; #define PG8_BAR __builtin_amdgcn_s_barrier()
; template <class Epi>
; __device__ __forceinline__ void gemm_phase(LAS unsigned char* lds, const Gemm g, const StaticOrder& S, const Epi& E, const int tid) {
;     ...
;         const bool has_next = S.next(ui + 1, nxt);
;         const char* nA = has_next ? (const char*)g.A + (size_t)nxt.pm * tstep : cA; const char* nB = has_next ? (const char*)g.Bt + (size_t)nxt.pn * tstep : cB;
;         for (int t = 0; t < ntt; t += 2) {
;             const bool last = (t == ntt - 2);
;             const bool s1 = Epi::TWO && (t >= nt), s2 = Epi::TWO && (t + 2 >= nt);
;             const char* a1 = (s1 ? cA2 + (size_t)(t - nt + 1) * kstep : cA + (size_t)(t + 1) * kstep);
;             const char* a2 = last ? nA : (s2 ? cA2 + (size_t)(t + 2 - nt) * kstep : cA + (size_t)(t + 2) * kstep);
;             const char* b2 = last ? nB : (s2 ? cB2 + (size_t)(t + 2 - nt) * kstep : cB + (size_t)(t + 2) * kstep);
;             const char* a3 = a2 + kstep; const char* b3 = b2 + kstep;
;             if constexpr (Epi::TWO) { if (t == nt) E.mid(acc, cur, wr, wc, fr, fq); }
;             if constexpr (SP2) {
;             PG8_LDB(B0, 0, 0); PG8_LDB(B1, 0, 1); PG8_SCHED; PG8_LDA(At, 0, 0); PG8_STAGE(PG8_SA(1, 1), a1 + hstep, voffA);
;             PG8_WAIT_V(8); PG8_WAIT_L(0); PG8_BAR; PG8_MMA(0, 0, At, B0); PG8_MMA(0, 1, At, B1); PG8_BAR; PG8_SCHED;
;     ...
; #pragma unroll
;         for (int a = 0; a < 2; ++a)
; #pragma unroll
;             for (int b = 0; b < 2; ++b)
; #pragma unroll
;                 for (int m = 0; m < 4; ++m)
; #pragma unroll
;                     for (int n = 0; n < 2; ++n) acc[a][b][m][n] = (f32x4){0.f, 0.f, 0.f, 0.f};
.LBB0_313:
	s_ashr_i32 s27, s26, 31
	s_lshl_b64 s[6:7], s[26:27], 20
	v_readlane_b32 s28, v251, 43
	v_readlane_b32 s29, v251, 44
	s_add_u32 s28, s28, s6
	s_addc_u32 s29, s29, s7
	s_and_b64 s[6:7], s[34:35], exec
	s_cselect_b32 s27, s29, s43
	s_cselect_b32 s39, s28, s42
	s_ashr_i32 s25, s24, 31
	s_lshl_b64 s[6:7], s[24:25], 20
	s_add_u32 s30, s52, s6
	s_addc_u32 s31, s53, s7
	s_and_b64 s[6:7], s[34:35], exec
	s_cselect_b32 s25, s31, s41
	s_cselect_b32 s52, s30, s40
	s_add_u32 s53, s40, 0x100
	s_addc_u32 s54, s41, 0
	s_add_u32 s6, s42, 0x80080
	v_mov_b32_e32 v2, 0
	s_addc_u32 s7, s43, 0
	s_mov_b32 s55, -2
	v_mov_b32_e32 v3, v2
	s_waitcnt lgkmcnt(0)
	v_mov_b32_e32 v4, v2
	v_mov_b32_e32 v5, v2
	v_mov_b32_e32 v6, v2
	v_mov_b32_e32 v7, v2
	v_mov_b32_e32 v8, v2
	v_mov_b32_e32 v9, v2
	v_mov_b32_e32 v18, v2
	v_mov_b32_e32 v19, v2
	v_mov_b32_e32 v20, v2
	v_mov_b32_e32 v21, v2
	v_mov_b32_e32 v22, v2
	v_mov_b32_e32 v23, v2
	v_mov_b32_e32 v24, v2
	v_mov_b32_e32 v25, v2
	v_mov_b32_e32 v50, v2
	v_mov_b32_e32 v51, v2
	v_mov_b32_e32 v52, v2
	v_mov_b32_e32 v53, v2
	v_mov_b32_e32 v54, v2
	v_mov_b32_e32 v55, v2
	v_mov_b32_e32 v56, v2
	v_mov_b32_e32 v57, v2
	v_mov_b32_e32 v82, v2
	v_mov_b32_e32 v83, v2
	v_mov_b32_e32 v84, v2
	v_mov_b32_e32 v85, v2
	v_mov_b32_e32 v86, v2
	v_mov_b32_e32 v87, v2
	v_mov_b32_e32 v88, v2
	v_mov_b32_e32 v89, v2
	v_mov_b32_e32 v10, v2
	v_mov_b32_e32 v11, v2
	v_mov_b32_e32 v12, v2
	v_mov_b32_e32 v13, v2
	v_mov_b32_e32 v14, v2
	v_mov_b32_e32 v15, v2
	v_mov_b32_e32 v16, v2
	v_mov_b32_e32 v17, v2
	v_mov_b32_e32 v26, v2
	v_mov_b32_e32 v27, v2
	v_mov_b32_e32 v28, v2
	v_mov_b32_e32 v29, v2
	v_mov_b32_e32 v30, v2
	v_mov_b32_e32 v31, v2
	v_mov_b32_e32 v32, v2
	v_mov_b32_e32 v33, v2
	v_mov_b32_e32 v74, v2
	v_mov_b32_e32 v75, v2
	v_mov_b32_e32 v76, v2
	v_mov_b32_e32 v77, v2
	v_mov_b32_e32 v78, v2
	v_mov_b32_e32 v79, v2
	v_mov_b32_e32 v80, v2
	v_mov_b32_e32 v81, v2
	v_mov_b32_e32 v90, v2
	v_mov_b32_e32 v91, v2
	v_mov_b32_e32 v92, v2
	v_mov_b32_e32 v93, v2
	v_mov_b32_e32 v94, v2
	v_mov_b32_e32 v95, v2
	v_mov_b32_e32 v96, v2
	v_mov_b32_e32 v97, v2
	v_mov_b32_e32 v98, v2
	v_mov_b32_e32 v99, v2
	v_mov_b32_e32 v100, v2
	v_mov_b32_e32 v101, v2
	v_mov_b32_e32 v102, v2
	v_mov_b32_e32 v103, v2
	v_mov_b32_e32 v104, v2
	v_mov_b32_e32 v105, v2
	v_mov_b32_e32 v114, v2
	v_mov_b32_e32 v115, v2
	v_mov_b32_e32 v116, v2
	v_mov_b32_e32 v117, v2
	v_mov_b32_e32 v118, v2
	v_mov_b32_e32 v119, v2
	v_mov_b32_e32 v120, v2
	v_mov_b32_e32 v121, v2
	v_mov_b32_e32 v130, v2
	v_mov_b32_e32 v131, v2
	v_mov_b32_e32 v132, v2
	v_mov_b32_e32 v133, v2
	v_mov_b32_e32 v134, v2
	v_mov_b32_e32 v135, v2
	v_mov_b32_e32 v136, v2
	v_mov_b32_e32 v137, v2
	v_mov_b32_e32 v146, v2
	v_mov_b32_e32 v147, v2
	v_mov_b32_e32 v148, v2
	v_mov_b32_e32 v149, v2
	v_mov_b32_e32 v150, v2
	v_mov_b32_e32 v151, v2
	v_mov_b32_e32 v152, v2
	v_mov_b32_e32 v153, v2
	v_mov_b32_e32 v106, v2
	v_mov_b32_e32 v107, v2
	v_mov_b32_e32 v108, v2
	v_mov_b32_e32 v109, v2
	v_mov_b32_e32 v110, v2
	v_mov_b32_e32 v111, v2
	v_mov_b32_e32 v112, v2
	v_mov_b32_e32 v113, v2
	v_mov_b32_e32 v122, v2
	v_mov_b32_e32 v123, v2
	v_mov_b32_e32 v124, v2
	v_mov_b32_e32 v125, v2
	v_mov_b32_e32 v126, v2
	v_mov_b32_e32 v127, v2
	v_mov_b32_e32 v128, v2
	v_mov_b32_e32 v129, v2
	v_mov_b32_e32 v138, v2
	v_mov_b32_e32 v139, v2
	v_mov_b32_e32 v140, v2
	v_mov_b32_e32 v141, v2
	v_mov_b32_e32 v142, v2
	v_mov_b32_e32 v143, v2
	v_mov_b32_e32 v144, v2
	v_mov_b32_e32 v145, v2
	v_mov_b32_e32 v154, v2
	v_mov_b32_e32 v155, v2
	v_mov_b32_e32 v156, v2
	v_mov_b32_e32 v157, v2
	v_mov_b32_e32 v158, v2
	v_mov_b32_e32 v159, v2
	v_mov_b32_e32 v160, v2
	v_mov_b32_e32 v161, v2
	s_and_b64 vcc, exec, s[22:23]
	s_cbranch_vccnz .Lprio_skip_314
	s_setprio 1
.Lprio_skip_314:
.LBB0_314:
	s_add_u32 s40, s6, 0xfff80080
	s_addc_u32 s41, s7, -1
	s_add_i32 s56, 0, 0x10000
	s_cmp_eq_u32 s55, 28
	s_cselect_b32 s43, s27, s41
	s_cselect_b32 s42, s39, s40
	s_cselect_b32 s41, s25, s54
	s_cselect_b32 s40, s52, s53
	s_add_i32 s58, 0, 0x14000
	v_add_u32_e32 v46, s56, v212
	v_add_u32_e32 v70, s58, v212
	ds_read_b128 v[34:37], v46
	ds_read_b128 v[38:41], v46 offset:1024
	ds_read_b128 v[42:45], v46 offset:2048
	ds_read_b128 v[46:49], v46 offset:3072
	ds_read_b128 v[58:61], v70
	ds_read_b128 v[62:65], v70 offset:1024
	ds_read_b128 v[66:69], v70 offset:2048
	ds_read_b128 v[70:73], v70 offset:3072
	v_lshl_add_u64 v[172:173], s[6:7], 0, v[188:189]
	s_add_i32 m0, s44, 0xc000
	ds_read_b128 v[162:165], v220
	global_load_lds_dwordx4 v[172:173], off
	ds_read_b128 v[166:169], v220 offset:1024
	ds_read_b128 v[190:193], v220 offset:2048
	v_lshl_add_u64 v[172:173], s[6:7], 0, v[186:187]
	s_add_i32 m0, s44, 0xe000
	s_nop 0
	global_load_lds_dwordx4 v[172:173], off
	ds_read_b128 v[194:197], v220 offset:3072
	ds_read_b128 v[198:201], v220 offset:4096
	ds_read_b128 v[222:225], v220 offset:5120
	ds_read_b128 v[226:229], v220 offset:6144
	ds_read_b128 v[230:233], v220 offset:7168
	s_waitcnt vmcnt(8)
	s_waitcnt lgkmcnt(0)
	s_barrier
; #define PG8_STAGE(bufoff, gbase, voff) do { _Pragma("unroll") for (int _i = 0; _i < 2; ++_i) \
;         __builtin_amdgcn_global_load_lds((const unsigned*)((const char*)(gbase) + (voff)[_i]), (LAS unsigned*)(lds + (bufoff) + ldsw + _i * 8192), 16, 0, 0); } while (0)
; #define PG8_LDA(dst, b, h) do { _Pragma("unroll") for (int m = 0; m < 4; ++m) _Pragma("unroll") for (int k = 0; k < 2; ++k) dst[m][k] = *(const LAS bf16x8*)(lds + PG8_SA(b, h) + aoff + m * 2048 + k * 1024); } while (0)
; #define PG8_MMA(ai, bj, At, Bt) do { __builtin_amdgcn_s_setprio(1); _Pragma("unroll") for (int m = 0; m < 4; ++m) _Pragma("unroll") for (int n = 0; n < 2; ++n) _Pragma("unroll") for (int k = 0; k < 2; ++k) \
;         acc[ai][bj][m][n] = __builtin_amdgcn_mfma_f32_16x16x32_bf16(Bt[n][k], At[m][k], acc[ai][bj][m][n], 0, 0, 0); __builtin_amdgcn_s_setprio(0); } while (0)
; #define PG8_WAIT_V(n) asm volatile("s_waitcnt vmcnt(" #n ")" ::: "memory")
; #define PG8_WAIT_L(n) asm volatile("s_waitcnt lgkmcnt(" #n ")" ::: "memory")
; #define PG8_BAR __builtin_amdgcn_s_barrier()
; #define PG8_SCHED __builtin_amdgcn_sched_barrier(0)
; template <class Epi>
; __device__ __forceinline__ void gemm_phase(LAS unsigned char* lds, const Gemm g, const StaticOrder& S, const Epi& E, const int tid) {
;     ...
;             PG8_WAIT_V(8); PG8_WAIT_L(0); PG8_BAR; PG8_MMA(0, 0, At, B0); PG8_MMA(0, 1, At, B1); PG8_BAR; PG8_SCHED;
;             PG8_LDA(At, 0, 1); PG8_STAGE(PG8_SB(0, 0), b2, voffB); PG8_STAGE(PG8_SB(0, 1), b2 + bhs, voffB); PG8_STAGE(PG8_SA(0, 0), a2, voffA);
;             PG8_WAIT_V(8); PG8_WAIT_L(0); PG8_BAR; PG8_MMA(1, 0, At, B0); PG8_MMA(1, 1, At, B1); PG8_BAR; PG8_SCHED;
	s_waitcnt lgkmcnt(0)
	v_mfma_f32_16x16x32_bf16 v[158:161], v[34:37], v[162:165], v[158:161]
	v_mfma_f32_16x16x32_bf16 v[154:157], v[42:45], v[162:165], v[154:157]
	v_mfma_f32_16x16x32_bf16 v[142:145], v[34:37], v[190:193], v[142:145]
	v_mfma_f32_16x16x32_bf16 v[138:141], v[42:45], v[190:193], v[138:141]
	v_mfma_f32_16x16x32_bf16 v[126:129], v[34:37], v[198:201], v[126:129]
	v_mfma_f32_16x16x32_bf16 v[122:125], v[42:45], v[198:201], v[122:125]
	v_mfma_f32_16x16x32_bf16 v[110:113], v[34:37], v[226:229], v[110:113]
	v_mfma_f32_16x16x32_bf16 v[106:109], v[42:45], v[226:229], v[106:109]
	v_mfma_f32_16x16x32_bf16 v[158:161], v[38:41], v[166:169], v[158:161]
	v_mfma_f32_16x16x32_bf16 v[154:157], v[46:49], v[166:169], v[154:157]
	v_mfma_f32_16x16x32_bf16 v[142:145], v[38:41], v[194:197], v[142:145]
	v_mfma_f32_16x16x32_bf16 v[138:141], v[46:49], v[194:197], v[138:141]
	v_mfma_f32_16x16x32_bf16 v[126:129], v[38:41], v[222:225], v[126:129]
	v_mfma_f32_16x16x32_bf16 v[122:125], v[46:49], v[222:225], v[122:125]
	v_mfma_f32_16x16x32_bf16 v[110:113], v[38:41], v[230:233], v[110:113]
	v_mfma_f32_16x16x32_bf16 v[106:109], v[46:49], v[230:233], v[106:109]
	v_mfma_f32_16x16x32_bf16 v[150:153], v[58:61], v[162:165], v[150:153]
	v_mfma_f32_16x16x32_bf16 v[146:149], v[66:69], v[162:165], v[146:149]
	v_mfma_f32_16x16x32_bf16 v[134:137], v[58:61], v[190:193], v[134:137]
	v_mfma_f32_16x16x32_bf16 v[130:133], v[66:69], v[190:193], v[130:133]
	v_mfma_f32_16x16x32_bf16 v[118:121], v[58:61], v[198:201], v[118:121]
	v_mfma_f32_16x16x32_bf16 v[114:117], v[66:69], v[198:201], v[114:117]
	v_mfma_f32_16x16x32_bf16 v[102:105], v[58:61], v[226:229], v[102:105]
	v_mfma_f32_16x16x32_bf16 v[98:101], v[66:69], v[226:229], v[98:101]
	v_mfma_f32_16x16x32_bf16 v[150:153], v[62:65], v[166:169], v[150:153]
	v_mfma_f32_16x16x32_bf16 v[146:149], v[70:73], v[166:169], v[146:149]
	v_mfma_f32_16x16x32_bf16 v[134:137], v[62:65], v[194:197], v[134:137]
	v_mfma_f32_16x16x32_bf16 v[130:133], v[70:73], v[194:197], v[130:133]
	v_mfma_f32_16x16x32_bf16 v[118:121], v[62:65], v[222:225], v[118:121]
	v_mfma_f32_16x16x32_bf16 v[114:117], v[70:73], v[222:225], v[114:117]
	v_mfma_f32_16x16x32_bf16 v[102:105], v[62:65], v[230:233], v[102:105]
	v_mfma_f32_16x16x32_bf16 v[98:101], v[70:73], v[230:233], v[98:101]
	s_barrier
	s_add_i32 s56, s56, s33
	v_lshl_add_u64 v[172:173], s[40:41], 0, v[0:1]
	s_mov_b32 m0, s56
	ds_read_b128 v[162:165], v220 offset:16384
	global_load_lds_dwordx4 v[172:173], off
	ds_read_b128 v[166:169], v220 offset:17408
	ds_read_b128 v[190:193], v220 offset:18432
	s_add_i32 m0, s56, 0x2000
	s_add_u32 s56, s40, 0x8000
	v_lshl_add_u64 v[174:175], s[40:41], 0, v[182:183]
	s_addc_u32 s57, s41, 0
	s_add_i32 s58, s58, s33
	global_load_lds_dwordx4 v[174:175], off
	ds_read_b128 v[194:197], v220 offset:19456
	ds_read_b128 v[198:201], v220 offset:20480
	v_lshl_add_u64 v[176:177], s[56:57], 0, v[0:1]
	s_mov_b32 m0, s58
	v_lshl_add_u64 v[238:239], s[42:43], 0, v[180:181]
	global_load_lds_dwordx4 v[176:177], off
	ds_read_b128 v[222:225], v220 offset:21504
	ds_read_b128 v[226:229], v220 offset:22528
	v_lshl_add_u64 v[176:177], s[56:57], 0, v[182:183]
	s_add_i32 m0, s58, 0x2000
	s_nop 0
	global_load_lds_dwordx4 v[176:177], off
	ds_read_b128 v[230:233], v220 offset:23552
	v_lshl_add_u64 v[176:177], s[42:43], 0, v[178:179]
	s_mov_b32 m0, s44
	s_nop 0
	global_load_lds_dwordx4 v[176:177], off
	s_mov_b32 m0, s45
	s_nop 0
	global_load_lds_dwordx4 v[238:239], off
	s_waitcnt vmcnt(8)
	s_waitcnt lgkmcnt(0)
	s_barrier
	s_waitcnt lgkmcnt(0)
	v_mfma_f32_16x16x32_bf16 v[94:97], v[34:37], v[162:165], v[94:97]
	v_mfma_f32_16x16x32_bf16 v[90:93], v[42:45], v[162:165], v[90:93]
	v_mfma_f32_16x16x32_bf16 v[78:81], v[34:37], v[190:193], v[78:81]
	v_mfma_f32_16x16x32_bf16 v[74:77], v[42:45], v[190:193], v[74:77]
	v_mfma_f32_16x16x32_bf16 v[30:33], v[34:37], v[198:201], v[30:33]
	v_mfma_f32_16x16x32_bf16 v[26:29], v[42:45], v[198:201], v[26:29]
	v_mfma_f32_16x16x32_bf16 v[14:17], v[34:37], v[226:229], v[14:17]
	v_mfma_f32_16x16x32_bf16 v[10:13], v[42:45], v[226:229], v[10:13]
	v_mfma_f32_16x16x32_bf16 v[94:97], v[38:41], v[166:169], v[94:97]
	v_mfma_f32_16x16x32_bf16 v[90:93], v[46:49], v[166:169], v[90:93]
	v_mfma_f32_16x16x32_bf16 v[78:81], v[38:41], v[194:197], v[78:81]
	v_mfma_f32_16x16x32_bf16 v[74:77], v[46:49], v[194:197], v[74:77]
	v_mfma_f32_16x16x32_bf16 v[30:33], v[38:41], v[222:225], v[30:33]
	v_mfma_f32_16x16x32_bf16 v[26:29], v[46:49], v[222:225], v[26:29]
	v_mfma_f32_16x16x32_bf16 v[14:17], v[38:41], v[230:233], v[14:17]
	v_mfma_f32_16x16x32_bf16 v[10:13], v[46:49], v[230:233], v[10:13]
	v_mfma_f32_16x16x32_bf16 v[22:25], v[58:61], v[198:201], v[22:25]
	v_mfma_f32_16x16x32_bf16 v[18:21], v[66:69], v[198:201], v[18:21]
	v_mfma_f32_16x16x32_bf16 v[6:9], v[58:61], v[226:229], v[6:9]
	v_mfma_f32_16x16x32_bf16 v[2:5], v[66:69], v[226:229], v[2:5]
	v_mfma_f32_16x16x32_bf16 v[34:37], v[58:61], v[162:165], v[86:89]
	v_mfma_f32_16x16x32_bf16 v[38:41], v[66:69], v[162:165], v[82:85]
	v_mfma_f32_16x16x32_bf16 v[42:45], v[58:61], v[190:193], v[54:57]
	v_mfma_f32_16x16x32_bf16 v[46:49], v[66:69], v[190:193], v[50:53]
	v_mfma_f32_16x16x32_bf16 v[22:25], v[62:65], v[222:225], v[22:25]
	v_mfma_f32_16x16x32_bf16 v[18:21], v[70:73], v[222:225], v[18:21]
	v_mfma_f32_16x16x32_bf16 v[6:9], v[62:65], v[230:233], v[6:9]
	v_mfma_f32_16x16x32_bf16 v[2:5], v[70:73], v[230:233], v[2:5]
	v_mfma_f32_16x16x32_bf16 v[34:37], v[62:65], v[166:169], v[34:37]
	v_mfma_f32_16x16x32_bf16 v[38:41], v[70:73], v[166:169], v[38:41]
	v_mfma_f32_16x16x32_bf16 v[42:45], v[62:65], v[194:197], v[42:45]
	v_mfma_f32_16x16x32_bf16 v[46:49], v[70:73], v[194:197], v[46:49]
	s_barrier
; #define PG8_STAGE(bufoff, gbase, voff) do { _Pragma("unroll") for (int _i = 0; _i < 2; ++_i) \
;         __builtin_amdgcn_global_load_lds((const unsigned*)((const char*)(gbase) + (voff)[_i]), (LAS unsigned*)(lds + (bufoff) + ldsw + _i * 8192), 16, 0, 0); } while (0)
; #define PG8_LDA(dst, b, h) do { _Pragma("unroll") for (int m = 0; m < 4; ++m) _Pragma("unroll") for (int k = 0; k < 2; ++k) dst[m][k] = *(const LAS bf16x8*)(lds + PG8_SA(b, h) + aoff + m * 2048 + k * 1024); } while (0)
; #define PG8_LDB(dst, b, h) do { _Pragma("unroll") for (int n = 0; n < 2; ++n) _Pragma("unroll") for (int k = 0; k < 2; ++k) dst[n][k] = *(const LAS bf16x8*)(lds + PG8_SB(b, h) + boff + n * 2048 + k * 1024); } while (0)
; #define PG8_MMA(ai, bj, At, Bt) do { __builtin_amdgcn_s_setprio(1); _Pragma("unroll") for (int m = 0; m < 4; ++m) _Pragma("unroll") for (int n = 0; n < 2; ++n) _Pragma("unroll") for (int k = 0; k < 2; ++k) \
;         acc[ai][bj][m][n] = __builtin_amdgcn_mfma_f32_16x16x32_bf16(Bt[n][k], At[m][k], acc[ai][bj][m][n], 0, 0, 0); __builtin_amdgcn_s_setprio(0); } while (0)
; #define PG8_WAIT_V(n) asm volatile("s_waitcnt vmcnt(" #n ")" ::: "memory")
; #define PG8_WAIT_L(n) asm volatile("s_waitcnt lgkmcnt(" #n ")" ::: "memory")
; #define PG8_BAR __builtin_amdgcn_s_barrier()
; #define PG8_SCHED __builtin_amdgcn_sched_barrier(0)
; template <class Epi>
; __device__ __forceinline__ void gemm_phase(LAS unsigned char* lds, const Gemm g, const StaticOrder& S, const Epi& E, const int tid) {
;     ...
;             PG8_LDB(B0, 1, 0); PG8_LDB(B1, 1, 1); PG8_SCHED; PG8_LDA(At, 1, 0); PG8_STAGE(PG8_SA(0, 1), a2 + hstep, voffA);
;             PG8_WAIT_V(8); PG8_WAIT_L(0); PG8_BAR; PG8_MMA(0, 0, At, B0); PG8_MMA(0, 1, At, B1); PG8_BAR; PG8_SCHED;
;             PG8_LDA(At, 1, 1); PG8_STAGE(PG8_SB(1, 0), b3, voffB); PG8_STAGE(PG8_SB(1, 1), b3 + bhs, voffB); PG8_STAGE(PG8_SA(1, 0), a3, voffA);
;             PG8_WAIT_V(8); PG8_WAIT_L(0); PG8_BAR; PG8_MMA(1, 0, At, B0); PG8_MMA(1, 1, At, B1); PG8_BAR; PG8_SCHED;
;     ...
;         if (ALIGN_EPI) { if (wr == 0) PG8_BAR; }
	s_add_i32 s56, 0, 0x18000
	s_add_i32 s57, 0, 0x1c000
	v_add_u32_e32 v62, s56, v212
	v_add_u32_e32 v82, s57, v212
	ds_read_b128 v[50:53], v62
	ds_read_b128 v[54:57], v62 offset:1024
	ds_read_b128 v[58:61], v62 offset:2048
	ds_read_b128 v[62:65], v62 offset:3072
	ds_read_b128 v[66:69], v82
	ds_read_b128 v[70:73], v82 offset:1024
	ds_read_b128 v[162:165], v82 offset:2048
	ds_read_b128 v[166:169], v82 offset:3072
	s_add_u32 s42, s42, 0x80000
	s_addc_u32 s43, s43, 0
	s_mov_b32 m0, s46
	v_lshl_add_u64 v[234:235], s[42:43], 0, v[178:179]
	ds_read_b128 v[82:85], v220 offset:32768
	global_load_lds_dwordx4 v[234:235], off
	ds_read_b128 v[86:89], v220 offset:33792
	ds_read_b128 v[190:193], v220 offset:34816
	v_lshl_add_u64 v[234:235], s[42:43], 0, v[180:181]
	s_mov_b32 m0, s47
	s_nop 0
	global_load_lds_dwordx4 v[234:235], off
	ds_read_b128 v[194:197], v220 offset:35840
	ds_read_b128 v[198:201], v220 offset:36864
	ds_read_b128 v[222:225], v220 offset:37888
	ds_read_b128 v[226:229], v220 offset:38912
	ds_read_b128 v[230:233], v220 offset:39936
	s_waitcnt vmcnt(8)
	s_waitcnt lgkmcnt(0)
	s_barrier
	s_waitcnt lgkmcnt(0)
	v_mfma_f32_16x16x32_bf16 v[158:161], v[50:53], v[82:85], v[158:161]
	v_mfma_f32_16x16x32_bf16 v[154:157], v[58:61], v[82:85], v[154:157]
	v_mfma_f32_16x16x32_bf16 v[142:145], v[50:53], v[190:193], v[142:145]
	v_mfma_f32_16x16x32_bf16 v[138:141], v[58:61], v[190:193], v[138:141]
	v_mfma_f32_16x16x32_bf16 v[126:129], v[50:53], v[198:201], v[126:129]
	v_mfma_f32_16x16x32_bf16 v[122:125], v[58:61], v[198:201], v[122:125]
	v_mfma_f32_16x16x32_bf16 v[110:113], v[50:53], v[226:229], v[110:113]
	v_mfma_f32_16x16x32_bf16 v[106:109], v[58:61], v[226:229], v[106:109]
	v_mfma_f32_16x16x32_bf16 v[158:161], v[54:57], v[86:89], v[158:161]
	v_mfma_f32_16x16x32_bf16 v[154:157], v[62:65], v[86:89], v[154:157]
	v_mfma_f32_16x16x32_bf16 v[142:145], v[54:57], v[194:197], v[142:145]
	v_mfma_f32_16x16x32_bf16 v[138:141], v[62:65], v[194:197], v[138:141]
	v_mfma_f32_16x16x32_bf16 v[126:129], v[54:57], v[222:225], v[126:129]
	v_mfma_f32_16x16x32_bf16 v[122:125], v[62:65], v[222:225], v[122:125]
	v_mfma_f32_16x16x32_bf16 v[110:113], v[54:57], v[230:233], v[110:113]
	v_mfma_f32_16x16x32_bf16 v[106:109], v[62:65], v[230:233], v[106:109]
	v_mfma_f32_16x16x32_bf16 v[150:153], v[66:69], v[82:85], v[150:153]
	v_mfma_f32_16x16x32_bf16 v[82:85], v[162:165], v[82:85], v[146:149]
	v_mfma_f32_16x16x32_bf16 v[146:149], v[166:169], v[86:89], v[82:85]
	v_mfma_f32_16x16x32_bf16 v[82:85], v[66:69], v[190:193], v[134:137]
	v_mfma_f32_16x16x32_bf16 v[134:137], v[70:73], v[194:197], v[82:85]
	v_mfma_f32_16x16x32_bf16 v[82:85], v[162:165], v[190:193], v[130:133]
	v_mfma_f32_16x16x32_bf16 v[130:133], v[166:169], v[194:197], v[82:85]
	v_mfma_f32_16x16x32_bf16 v[82:85], v[66:69], v[198:201], v[118:121]
	v_mfma_f32_16x16x32_bf16 v[118:121], v[70:73], v[222:225], v[82:85]
	v_mfma_f32_16x16x32_bf16 v[82:85], v[162:165], v[198:201], v[114:117]
	v_mfma_f32_16x16x32_bf16 v[114:117], v[166:169], v[222:225], v[82:85]
	v_mfma_f32_16x16x32_bf16 v[82:85], v[66:69], v[226:229], v[102:105]
	v_mfma_f32_16x16x32_bf16 v[102:105], v[70:73], v[230:233], v[82:85]
	v_mfma_f32_16x16x32_bf16 v[82:85], v[162:165], v[226:229], v[98:101]
	v_mfma_f32_16x16x32_bf16 v[150:153], v[70:73], v[86:89], v[150:153]
	v_mfma_f32_16x16x32_bf16 v[98:101], v[166:169], v[230:233], v[82:85]
	s_barrier
	s_add_i32 s42, s56, s33
	v_lshl_add_u64 v[86:87], v[172:173], 0, s[70:71]
	s_mov_b32 m0, s42
	s_nop 0
	ds_read_b128 v[82:85], v220 offset:49152
	global_load_lds_dwordx4 v[86:87], off
	ds_read_b128 v[190:193], v220 offset:50176
	ds_read_b128 v[194:197], v220 offset:51200
	s_add_i32 m0, s42, 0x2000
	s_add_u32 s40, s40, 0x8080
	v_lshl_add_u64 v[86:87], v[174:175], 0, s[70:71]
	s_addc_u32 s41, s41, 0
	s_add_i32 s42, s57, s33
	global_load_lds_dwordx4 v[86:87], off
	ds_read_b128 v[198:201], v220 offset:52224
	ds_read_b128 v[222:225], v220 offset:53248
	v_lshl_add_u64 v[86:87], s[40:41], 0, v[0:1]
	s_mov_b32 m0, s42
	s_nop 0
	global_load_lds_dwordx4 v[86:87], off
	ds_read_b128 v[226:229], v220 offset:54272
	ds_read_b128 v[230:233], v220 offset:55296
	v_lshl_add_u64 v[86:87], s[40:41], 0, v[182:183]
	s_add_i32 m0, s42, 0x2000
	s_nop 0
	global_load_lds_dwordx4 v[86:87], off
	ds_read_b128 v[234:237], v220 offset:56320
	v_lshl_add_u64 v[86:87], v[176:177], 0, s[70:71]
	s_mov_b32 m0, s48
	s_nop 0
	global_load_lds_dwordx4 v[86:87], off
	v_lshl_add_u64 v[86:87], v[238:239], 0, s[70:71]
	s_mov_b32 m0, s49
	s_nop 0
	global_load_lds_dwordx4 v[86:87], off
	s_waitcnt vmcnt(8)
	s_waitcnt lgkmcnt(0)
	s_barrier
	s_waitcnt lgkmcnt(0)
	v_mfma_f32_16x16x32_bf16 v[86:89], v[50:53], v[82:85], v[94:97]
	v_mfma_f32_16x16x32_bf16 v[94:97], v[54:57], v[190:193], v[86:89]
	v_mfma_f32_16x16x32_bf16 v[86:89], v[58:61], v[82:85], v[90:93]
	v_mfma_f32_16x16x32_bf16 v[78:81], v[50:53], v[194:197], v[78:81]
	v_mfma_f32_16x16x32_bf16 v[74:77], v[58:61], v[194:197], v[74:77]
	v_mfma_f32_16x16x32_bf16 v[30:33], v[50:53], v[222:225], v[30:33]
	v_mfma_f32_16x16x32_bf16 v[26:29], v[58:61], v[222:225], v[26:29]
	v_mfma_f32_16x16x32_bf16 v[14:17], v[50:53], v[230:233], v[14:17]
	v_mfma_f32_16x16x32_bf16 v[10:13], v[58:61], v[230:233], v[10:13]
	v_mfma_f32_16x16x32_bf16 v[90:93], v[62:65], v[190:193], v[86:89]
	v_mfma_f32_16x16x32_bf16 v[78:81], v[54:57], v[198:201], v[78:81]
	v_mfma_f32_16x16x32_bf16 v[74:77], v[62:65], v[198:201], v[74:77]
	v_mfma_f32_16x16x32_bf16 v[30:33], v[54:57], v[226:229], v[30:33]
	v_mfma_f32_16x16x32_bf16 v[26:29], v[62:65], v[226:229], v[26:29]
	v_mfma_f32_16x16x32_bf16 v[14:17], v[54:57], v[234:237], v[14:17]
	v_mfma_f32_16x16x32_bf16 v[10:13], v[62:65], v[234:237], v[10:13]
	v_mfma_f32_16x16x32_bf16 v[34:37], v[66:69], v[82:85], v[34:37]
	v_mfma_f32_16x16x32_bf16 v[86:89], v[70:73], v[190:193], v[34:37]
	v_mfma_f32_16x16x32_bf16 v[34:37], v[162:165], v[82:85], v[38:41]
	v_mfma_f32_16x16x32_bf16 v[82:85], v[166:169], v[190:193], v[34:37]
	v_mfma_f32_16x16x32_bf16 v[34:37], v[66:69], v[194:197], v[42:45]
	v_mfma_f32_16x16x32_bf16 v[54:57], v[70:73], v[198:201], v[34:37]
	v_mfma_f32_16x16x32_bf16 v[34:37], v[162:165], v[194:197], v[46:49]
	v_mfma_f32_16x16x32_bf16 v[22:25], v[66:69], v[222:225], v[22:25]
	v_mfma_f32_16x16x32_bf16 v[18:21], v[162:165], v[222:225], v[18:21]
	v_mfma_f32_16x16x32_bf16 v[6:9], v[66:69], v[230:233], v[6:9]
	v_mfma_f32_16x16x32_bf16 v[2:5], v[162:165], v[230:233], v[2:5]
	v_mfma_f32_16x16x32_bf16 v[50:53], v[166:169], v[198:201], v[34:37]
	v_mfma_f32_16x16x32_bf16 v[22:25], v[70:73], v[226:229], v[22:25]
	v_mfma_f32_16x16x32_bf16 v[18:21], v[166:169], v[226:229], v[18:21]
	v_mfma_f32_16x16x32_bf16 v[6:9], v[70:73], v[234:237], v[6:9]
	v_mfma_f32_16x16x32_bf16 v[2:5], v[166:169], v[234:237], v[2:5]
	s_barrier
	s_add_i32 s55, s55, 2
	s_add_u32 s53, s53, 0x100
	s_addc_u32 s54, s54, 0
	s_add_u32 s6, s6, 0x100
	s_addc_u32 s7, s7, 0
	s_cmp_gt_u32 s55, 29
	s_cbranch_scc0 .LBB0_314
	s_and_b64 vcc, exec, s[22:23]
	s_cbranch_vccz .LBB0_317
	s_barrier

; #define PG8_STAGE(bufoff, gbase, voff) do { _Pragma("unroll") for (int _i = 0; _i < 2; ++_i) \
;         __builtin_amdgcn_global_load_lds((const unsigned*)((const char*)(gbase) + (voff)[_i]), (LAS unsigned*)(lds + (bufoff) + ldsw + _i * 8192), 16, 0, 0); } while (0)
; #define PG8_LDA(dst, b, h) do { _Pragma("unroll") for (int m = 0; m < 4; ++m) _Pragma("unroll") for (int k = 0; k < 2; ++k) dst[m][k] = *(const LAS bf16x8*)(lds + PG8_SA(b, h) + aoff + m * 2048 + k * 1024); } while (0)
; #define PG8_LDB(dst, b, h) do { _Pragma("unroll") for (int n = 0; n < 2; ++n) _Pragma("unroll") for (int k = 0; k < 2; ++k) dst[n][k] = *(const LAS bf16x8*)(lds + PG8_SB(b, h) + boff + n * 2048 + k * 1024); } while (0)
; #define PG8_BAR __builtin_amdgcn_s_barrier()
; template <class Epi>
; __device__ __forceinline__ void gemm_phase(LAS unsigned char* lds, const Gemm g, const StaticOrder& S, const Epi& E, const int tid) {
;     ...
;         const bool has_next = S.next(ui + 1, nxt);
;         const char* nA = has_next ? (const char*)g.A + (size_t)nxt.pm * tstep : cA; const char* nB = has_next ? (const char*)g.Bt + (size_t)nxt.pn * tstep : cB;
;         for (int t = 0; t < ntt; t += 2) {
;             const bool last = (t == ntt - 2);
;             const bool s1 = Epi::TWO && (t >= nt), s2 = Epi::TWO && (t + 2 >= nt);
;             const char* a1 = (s1 ? cA2 + (size_t)(t - nt + 1) * kstep : cA + (size_t)(t + 1) * kstep);
;             const char* a2 = last ? nA : (s2 ? cA2 + (size_t)(t + 2 - nt) * kstep : cA + (size_t)(t + 2) * kstep);
;             const char* b2 = last ? nB : (s2 ? cB2 + (size_t)(t + 2 - nt) * kstep : cB + (size_t)(t + 2) * kstep);
;             const char* a3 = a2 + kstep; const char* b3 = b2 + kstep;
;             if constexpr (Epi::TWO) { if (t == nt) E.mid(acc, cur, wr, wc, fr, fq); }
;             if constexpr (SP2) {
;             PG8_LDB(B0, 0, 0); PG8_LDB(B1, 0, 1); PG8_SCHED; PG8_LDA(At, 0, 0); PG8_STAGE(PG8_SA(1, 1), a1 + hstep, voffA);
;             PG8_WAIT_V(8); PG8_WAIT_L(0); PG8_BAR; PG8_MMA(0, 0, At, B0); PG8_MMA(0, 1, At, B1); PG8_BAR; PG8_SCHED;
;     ...
; #pragma unroll
;         for (int a = 0; a < 2; ++a)
; #pragma unroll
;             for (int b = 0; b < 2; ++b)
; #pragma unroll
;                 for (int m = 0; m < 4; ++m)
; #pragma unroll
;                     for (int n = 0; n < 2; ++n) acc[a][b][m][n] = (f32x4){0.f, 0.f, 0.f, 0.f};
.LBB0_545:
	s_ashr_i32 s19, s18, 31
	s_lshl_b64 s[20:21], s[18:19], 20
	v_readlane_b32 s22, v251, 31
	v_readlane_b32 s23, v251, 32
	s_add_u32 s20, s22, s20
	s_addc_u32 s21, s23, s21
	s_and_b64 s[22:23], s[24:25], exec
	s_cselect_b32 s19, s21, s29
	s_cselect_b32 s31, s20, s28
	s_ashr_i32 s17, s16, 31
	s_lshl_b64 s[22:23], s[16:17], 20
	v_readlane_b32 s34, v251, 53
	v_readlane_b32 s35, v251, 54
	s_add_u32 s22, s34, s22
	s_addc_u32 s23, s35, s23
	s_and_b64 s[34:35], s[24:25], exec
	s_cselect_b32 s17, s23, s27
	s_cselect_b32 s33, s22, s26
	s_add_u32 s37, s26, 0x100
	s_addc_u32 s38, s27, 0
	s_add_u32 s26, s28, 0x80080
	v_mov_b32_e32 v2, 0
	s_addc_u32 s27, s29, 0
	s_mov_b32 s39, -2
	v_mov_b32_e32 v3, v2
	s_waitcnt lgkmcnt(0)
	v_mov_b32_e32 v4, v2
	v_mov_b32_e32 v5, v2
	v_mov_b32_e32 v6, v2
	v_mov_b32_e32 v7, v2
	v_mov_b32_e32 v8, v2
	v_mov_b32_e32 v9, v2
	v_mov_b32_e32 v18, v2
	v_mov_b32_e32 v19, v2
	v_mov_b32_e32 v20, v2
	v_mov_b32_e32 v21, v2
	v_mov_b32_e32 v22, v2
	v_mov_b32_e32 v23, v2
	v_mov_b32_e32 v24, v2
	v_mov_b32_e32 v25, v2
	v_mov_b32_e32 v34, v2
	v_mov_b32_e32 v35, v2
	v_mov_b32_e32 v36, v2
	v_mov_b32_e32 v37, v2
	v_mov_b32_e32 v38, v2
	v_mov_b32_e32 v39, v2
	v_mov_b32_e32 v40, v2
	v_mov_b32_e32 v41, v2
	v_mov_b32_e32 v50, v2
	v_mov_b32_e32 v51, v2
	v_mov_b32_e32 v52, v2
	v_mov_b32_e32 v53, v2
	v_mov_b32_e32 v54, v2
	v_mov_b32_e32 v55, v2
	v_mov_b32_e32 v56, v2
	v_mov_b32_e32 v57, v2
	v_mov_b32_e32 v10, v2
	v_mov_b32_e32 v11, v2
	v_mov_b32_e32 v12, v2
	v_mov_b32_e32 v13, v2
	v_mov_b32_e32 v14, v2
	v_mov_b32_e32 v15, v2
	v_mov_b32_e32 v16, v2
	v_mov_b32_e32 v17, v2
	v_mov_b32_e32 v26, v2
	v_mov_b32_e32 v27, v2
	v_mov_b32_e32 v28, v2
	v_mov_b32_e32 v29, v2
	v_mov_b32_e32 v30, v2
	v_mov_b32_e32 v31, v2
	v_mov_b32_e32 v32, v2
	v_mov_b32_e32 v33, v2
	v_mov_b32_e32 v42, v2
	v_mov_b32_e32 v43, v2
	v_mov_b32_e32 v44, v2
	v_mov_b32_e32 v45, v2
	v_mov_b32_e32 v46, v2
	v_mov_b32_e32 v47, v2
	v_mov_b32_e32 v48, v2
	v_mov_b32_e32 v49, v2
	v_mov_b32_e32 v58, v2
	v_mov_b32_e32 v59, v2
	v_mov_b32_e32 v60, v2
	v_mov_b32_e32 v61, v2
	v_mov_b32_e32 v62, v2
	v_mov_b32_e32 v63, v2
	v_mov_b32_e32 v64, v2
	v_mov_b32_e32 v65, v2
	v_mov_b32_e32 v66, v2
	v_mov_b32_e32 v67, v2
	v_mov_b32_e32 v68, v2
	v_mov_b32_e32 v69, v2
	v_mov_b32_e32 v70, v2
	v_mov_b32_e32 v71, v2
	v_mov_b32_e32 v72, v2
	v_mov_b32_e32 v73, v2
	v_mov_b32_e32 v82, v2
	v_mov_b32_e32 v83, v2
	v_mov_b32_e32 v84, v2
	v_mov_b32_e32 v85, v2
	v_mov_b32_e32 v86, v2
	v_mov_b32_e32 v87, v2
	v_mov_b32_e32 v88, v2
	v_mov_b32_e32 v89, v2
	v_mov_b32_e32 v98, v2
	v_mov_b32_e32 v99, v2
	v_mov_b32_e32 v100, v2
	v_mov_b32_e32 v101, v2
	v_mov_b32_e32 v102, v2
	v_mov_b32_e32 v103, v2
	v_mov_b32_e32 v104, v2
	v_mov_b32_e32 v105, v2
	v_mov_b32_e32 v114, v2
	v_mov_b32_e32 v115, v2
	v_mov_b32_e32 v116, v2
	v_mov_b32_e32 v117, v2
	v_mov_b32_e32 v118, v2
	v_mov_b32_e32 v119, v2
	v_mov_b32_e32 v120, v2
	v_mov_b32_e32 v121, v2
	v_mov_b32_e32 v74, v2
	v_mov_b32_e32 v75, v2
	v_mov_b32_e32 v76, v2
	v_mov_b32_e32 v77, v2
	v_mov_b32_e32 v78, v2
	v_mov_b32_e32 v79, v2
	v_mov_b32_e32 v80, v2
	v_mov_b32_e32 v81, v2
	v_mov_b32_e32 v90, v2
	v_mov_b32_e32 v91, v2
	v_mov_b32_e32 v92, v2
	v_mov_b32_e32 v93, v2
	v_mov_b32_e32 v94, v2
	v_mov_b32_e32 v95, v2
	v_mov_b32_e32 v96, v2
	v_mov_b32_e32 v97, v2
	v_mov_b32_e32 v106, v2
	v_mov_b32_e32 v107, v2
	v_mov_b32_e32 v108, v2
	v_mov_b32_e32 v109, v2
	v_mov_b32_e32 v110, v2
	v_mov_b32_e32 v111, v2
	v_mov_b32_e32 v112, v2
	v_mov_b32_e32 v113, v2
	v_mov_b32_e32 v122, v2
	v_mov_b32_e32 v123, v2
	v_mov_b32_e32 v124, v2
	v_mov_b32_e32 v125, v2
	v_mov_b32_e32 v126, v2
	v_mov_b32_e32 v127, v2
	v_mov_b32_e32 v128, v2
	v_mov_b32_e32 v129, v2
	s_and_b64 vcc, exec, s[14:15]
	s_cbranch_vccnz .Lprio_skip_546
	s_setprio 1
.Lprio_skip_546:
.LBB0_546:
	s_add_u32 s28, s26, 0xfff80080
	s_addc_u32 s29, s27, -1
	s_add_i32 s44, 0, 0x10000
	s_cmp_eq_u32 s39, 28
	s_cselect_b32 s35, s19, s29
	s_cselect_b32 s34, s31, s28
	v_add_u32_e32 v0, s44, v149
	s_cselect_b32 s29, s17, s38
	s_cselect_b32 s28, s33, s37
	s_add_i32 s46, 0, 0x14000
	ds_read_b128 v[150:153], v0
	ds_read_b128 v[154:157], v0 offset:1024
	ds_read_b128 v[158:161], v0 offset:2048
	ds_read_b128 v[186:189], v0 offset:3072
	v_add_u32_e32 v0, s46, v149
	ds_read_b128 v[190:193], v0
	ds_read_b128 v[194:197], v0 offset:1024
	ds_read_b128 v[198:201], v0 offset:2048
	ds_read_b128 v[212:215], v0 offset:3072
	v_lshl_add_u64 v[162:163], s[26:27], 0, v[146:147]
	s_add_i32 m0, s57, 0xc000
	ds_read_b128 v[216:219], v184
	global_load_lds_dwordx4 v[162:163], off
	ds_read_b128 v[220:223], v184 offset:1024
	ds_read_b128 v[224:227], v184 offset:2048
	v_lshl_add_u64 v[162:163], s[26:27], 0, v[144:145]
	s_add_i32 m0, s57, 0xe000
	s_nop 0
	global_load_lds_dwordx4 v[162:163], off
	ds_read_b128 v[228:231], v184 offset:3072
	ds_read_b128 v[232:235], v184 offset:4096
	ds_read_b128 v[236:239], v184 offset:5120
	ds_read_b128 v[240:243], v184 offset:6144
	ds_read_b128 v[244:247], v184 offset:7168
	s_waitcnt vmcnt(8)
	s_waitcnt lgkmcnt(0)
	s_barrier
; #define PG8_STAGE(bufoff, gbase, voff) do { _Pragma("unroll") for (int _i = 0; _i < 2; ++_i) \
;         __builtin_amdgcn_global_load_lds((const unsigned*)((const char*)(gbase) + (voff)[_i]), (LAS unsigned*)(lds + (bufoff) + ldsw + _i * 8192), 16, 0, 0); } while (0)
; #define PG8_LDA(dst, b, h) do { _Pragma("unroll") for (int m = 0; m < 4; ++m) _Pragma("unroll") for (int k = 0; k < 2; ++k) dst[m][k] = *(const LAS bf16x8*)(lds + PG8_SA(b, h) + aoff + m * 2048 + k * 1024); } while (0)
; #define PG8_MMA(ai, bj, At, Bt) do { __builtin_amdgcn_s_setprio(1); _Pragma("unroll") for (int m = 0; m < 4; ++m) _Pragma("unroll") for (int n = 0; n < 2; ++n) _Pragma("unroll") for (int k = 0; k < 2; ++k) \
;         acc[ai][bj][m][n] = __builtin_amdgcn_mfma_f32_16x16x32_bf16(Bt[n][k], At[m][k], acc[ai][bj][m][n], 0, 0, 0); __builtin_amdgcn_s_setprio(0); } while (0)
; #define PG8_WAIT_V(n) asm volatile("s_waitcnt vmcnt(" #n ")" ::: "memory")
; #define PG8_WAIT_L(n) asm volatile("s_waitcnt lgkmcnt(" #n ")" ::: "memory")
; #define PG8_BAR __builtin_amdgcn_s_barrier()
; #define PG8_SCHED __builtin_amdgcn_sched_barrier(0)
; template <class Epi>
; __device__ __forceinline__ void gemm_phase(LAS unsigned char* lds, const Gemm g, const StaticOrder& S, const Epi& E, const int tid) {
;     ...
;             PG8_WAIT_V(8); PG8_WAIT_L(0); PG8_BAR; PG8_MMA(0, 0, At, B0); PG8_MMA(0, 1, At, B1); PG8_BAR; PG8_SCHED;
;             PG8_LDA(At, 0, 1); PG8_STAGE(PG8_SB(0, 0), b2, voffB); PG8_STAGE(PG8_SB(0, 1), b2 + bhs, voffB); PG8_STAGE(PG8_SA(0, 0), a2, voffA);
;             PG8_WAIT_V(8); PG8_WAIT_L(0); PG8_BAR; PG8_MMA(1, 0, At, B0); PG8_MMA(1, 1, At, B1); PG8_BAR; PG8_SCHED;
	s_waitcnt lgkmcnt(0)
	v_mfma_f32_16x16x32_bf16 v[126:129], v[150:153], v[216:219], v[126:129]
	v_mfma_f32_16x16x32_bf16 v[122:125], v[158:161], v[216:219], v[122:125]
	v_mfma_f32_16x16x32_bf16 v[110:113], v[150:153], v[224:227], v[110:113]
	v_mfma_f32_16x16x32_bf16 v[106:109], v[158:161], v[224:227], v[106:109]
	v_mfma_f32_16x16x32_bf16 v[94:97], v[150:153], v[232:235], v[94:97]
	v_mfma_f32_16x16x32_bf16 v[90:93], v[158:161], v[232:235], v[90:93]
	v_mfma_f32_16x16x32_bf16 v[78:81], v[150:153], v[240:243], v[78:81]
	v_mfma_f32_16x16x32_bf16 v[74:77], v[158:161], v[240:243], v[74:77]
	v_mfma_f32_16x16x32_bf16 v[126:129], v[154:157], v[220:223], v[126:129]
	v_mfma_f32_16x16x32_bf16 v[122:125], v[186:189], v[220:223], v[122:125]
	v_mfma_f32_16x16x32_bf16 v[110:113], v[154:157], v[228:231], v[110:113]
	v_mfma_f32_16x16x32_bf16 v[106:109], v[186:189], v[228:231], v[106:109]
	v_mfma_f32_16x16x32_bf16 v[94:97], v[154:157], v[236:239], v[94:97]
	v_mfma_f32_16x16x32_bf16 v[90:93], v[186:189], v[236:239], v[90:93]
	v_mfma_f32_16x16x32_bf16 v[78:81], v[154:157], v[244:247], v[78:81]
	v_mfma_f32_16x16x32_bf16 v[74:77], v[186:189], v[244:247], v[74:77]
	v_mfma_f32_16x16x32_bf16 v[118:121], v[190:193], v[216:219], v[118:121]
	v_mfma_f32_16x16x32_bf16 v[114:117], v[198:201], v[216:219], v[114:117]
	v_mfma_f32_16x16x32_bf16 v[102:105], v[190:193], v[224:227], v[102:105]
	v_mfma_f32_16x16x32_bf16 v[98:101], v[198:201], v[224:227], v[98:101]
	v_mfma_f32_16x16x32_bf16 v[86:89], v[190:193], v[232:235], v[86:89]
	v_mfma_f32_16x16x32_bf16 v[82:85], v[198:201], v[232:235], v[82:85]
	v_mfma_f32_16x16x32_bf16 v[70:73], v[190:193], v[240:243], v[70:73]
	v_mfma_f32_16x16x32_bf16 v[66:69], v[198:201], v[240:243], v[66:69]
	v_mfma_f32_16x16x32_bf16 v[118:121], v[194:197], v[220:223], v[118:121]
	v_mfma_f32_16x16x32_bf16 v[114:117], v[212:215], v[220:223], v[114:117]
	v_mfma_f32_16x16x32_bf16 v[102:105], v[194:197], v[228:231], v[102:105]
	v_mfma_f32_16x16x32_bf16 v[98:101], v[212:215], v[228:231], v[98:101]
	v_mfma_f32_16x16x32_bf16 v[86:89], v[194:197], v[236:239], v[86:89]
	v_mfma_f32_16x16x32_bf16 v[82:85], v[212:215], v[236:239], v[82:85]
	v_mfma_f32_16x16x32_bf16 v[70:73], v[194:197], v[244:247], v[70:73]
	v_mfma_f32_16x16x32_bf16 v[66:69], v[212:215], v[244:247], v[66:69]
	s_barrier
	s_add_i32 s44, s44, s56
	v_lshl_add_u64 v[162:163], s[28:29], 0, v[132:133]
	s_mov_b32 m0, s44
	ds_read_b128 v[216:219], v184 offset:16384
	global_load_lds_dwordx4 v[162:163], off
	ds_read_b128 v[220:223], v184 offset:17408
	ds_read_b128 v[224:227], v184 offset:18432
	s_add_i32 m0, s44, 0x2000
	s_add_u32 s44, s28, 0x8000
	v_lshl_add_u64 v[248:249], s[28:29], 0, v[136:137]
	s_addc_u32 s45, s29, 0
	s_add_i32 s46, s46, s56
	global_load_lds_dwordx4 v[248:249], off
	ds_read_b128 v[228:231], v184 offset:19456
	ds_read_b128 v[232:235], v184 offset:20480
	v_lshl_add_u64 v[172:173], s[44:45], 0, v[132:133]
	s_mov_b32 m0, s46
	v_lshl_add_u64 v[174:175], s[34:35], 0, v[134:135]
	global_load_lds_dwordx4 v[172:173], off
	ds_read_b128 v[236:239], v184 offset:21504
	ds_read_b128 v[240:243], v184 offset:22528
	v_lshl_add_u64 v[172:173], s[44:45], 0, v[136:137]
	s_add_i32 m0, s46, 0x2000
	s_nop 0
	global_load_lds_dwordx4 v[172:173], off
	ds_read_b128 v[244:247], v184 offset:23552
	v_lshl_add_u64 v[172:173], s[34:35], 0, v[130:131]
	s_mov_b32 m0, s57
	s_nop 0
	global_load_lds_dwordx4 v[172:173], off
	s_mov_b32 m0, s58
	s_nop 0
	global_load_lds_dwordx4 v[174:175], off
	s_waitcnt vmcnt(8)
	s_waitcnt lgkmcnt(0)
	s_barrier
	s_waitcnt lgkmcnt(0)
	v_mfma_f32_16x16x32_bf16 v[62:65], v[150:153], v[216:219], v[62:65]
	v_mfma_f32_16x16x32_bf16 v[58:61], v[158:161], v[216:219], v[58:61]
	v_mfma_f32_16x16x32_bf16 v[46:49], v[150:153], v[224:227], v[46:49]
	v_mfma_f32_16x16x32_bf16 v[42:45], v[158:161], v[224:227], v[42:45]
	v_mfma_f32_16x16x32_bf16 v[30:33], v[150:153], v[232:235], v[30:33]
	v_mfma_f32_16x16x32_bf16 v[26:29], v[158:161], v[232:235], v[26:29]
	v_mfma_f32_16x16x32_bf16 v[14:17], v[150:153], v[240:243], v[14:17]
	v_mfma_f32_16x16x32_bf16 v[10:13], v[158:161], v[240:243], v[10:13]
	v_mfma_f32_16x16x32_bf16 v[62:65], v[154:157], v[220:223], v[62:65]
	v_mfma_f32_16x16x32_bf16 v[58:61], v[186:189], v[220:223], v[58:61]
	v_mfma_f32_16x16x32_bf16 v[46:49], v[154:157], v[228:231], v[46:49]
	v_mfma_f32_16x16x32_bf16 v[42:45], v[186:189], v[228:231], v[42:45]
	v_mfma_f32_16x16x32_bf16 v[30:33], v[154:157], v[236:239], v[30:33]
	v_mfma_f32_16x16x32_bf16 v[26:29], v[186:189], v[236:239], v[26:29]
	v_mfma_f32_16x16x32_bf16 v[14:17], v[154:157], v[244:247], v[14:17]
	v_mfma_f32_16x16x32_bf16 v[10:13], v[186:189], v[244:247], v[10:13]
	v_mfma_f32_16x16x32_bf16 v[54:57], v[190:193], v[216:219], v[54:57]
	v_mfma_f32_16x16x32_bf16 v[50:53], v[198:201], v[216:219], v[50:53]
	v_mfma_f32_16x16x32_bf16 v[38:41], v[190:193], v[224:227], v[38:41]
	v_mfma_f32_16x16x32_bf16 v[34:37], v[198:201], v[224:227], v[34:37]
	v_mfma_f32_16x16x32_bf16 v[22:25], v[190:193], v[232:235], v[22:25]
	v_mfma_f32_16x16x32_bf16 v[18:21], v[198:201], v[232:235], v[18:21]
	v_mfma_f32_16x16x32_bf16 v[6:9], v[190:193], v[240:243], v[6:9]
	v_mfma_f32_16x16x32_bf16 v[2:5], v[198:201], v[240:243], v[2:5]
	v_mfma_f32_16x16x32_bf16 v[54:57], v[194:197], v[220:223], v[54:57]
	v_mfma_f32_16x16x32_bf16 v[50:53], v[212:215], v[220:223], v[50:53]
	v_mfma_f32_16x16x32_bf16 v[38:41], v[194:197], v[228:231], v[38:41]
	v_mfma_f32_16x16x32_bf16 v[34:37], v[212:215], v[228:231], v[34:37]
	v_mfma_f32_16x16x32_bf16 v[22:25], v[194:197], v[236:239], v[22:25]
	v_mfma_f32_16x16x32_bf16 v[18:21], v[212:215], v[236:239], v[18:21]
	v_mfma_f32_16x16x32_bf16 v[6:9], v[194:197], v[244:247], v[6:9]
	v_mfma_f32_16x16x32_bf16 v[2:5], v[212:215], v[244:247], v[2:5]
	s_barrier
; #define PG8_STAGE(bufoff, gbase, voff) do { _Pragma("unroll") for (int _i = 0; _i < 2; ++_i) \
;         __builtin_amdgcn_global_load_lds((const unsigned*)((const char*)(gbase) + (voff)[_i]), (LAS unsigned*)(lds + (bufoff) + ldsw + _i * 8192), 16, 0, 0); } while (0)
; #define PG8_LDA(dst, b, h) do { _Pragma("unroll") for (int m = 0; m < 4; ++m) _Pragma("unroll") for (int k = 0; k < 2; ++k) dst[m][k] = *(const LAS bf16x8*)(lds + PG8_SA(b, h) + aoff + m * 2048 + k * 1024); } while (0)
; #define PG8_LDB(dst, b, h) do { _Pragma("unroll") for (int n = 0; n < 2; ++n) _Pragma("unroll") for (int k = 0; k < 2; ++k) dst[n][k] = *(const LAS bf16x8*)(lds + PG8_SB(b, h) + boff + n * 2048 + k * 1024); } while (0)
; #define PG8_MMA(ai, bj, At, Bt) do { __builtin_amdgcn_s_setprio(1); _Pragma("unroll") for (int m = 0; m < 4; ++m) _Pragma("unroll") for (int n = 0; n < 2; ++n) _Pragma("unroll") for (int k = 0; k < 2; ++k) \
;         acc[ai][bj][m][n] = __builtin_amdgcn_mfma_f32_16x16x32_bf16(Bt[n][k], At[m][k], acc[ai][bj][m][n], 0, 0, 0); __builtin_amdgcn_s_setprio(0); } while (0)
; #define PG8_WAIT_V(n) asm volatile("s_waitcnt vmcnt(" #n ")" ::: "memory")
; #define PG8_WAIT_L(n) asm volatile("s_waitcnt lgkmcnt(" #n ")" ::: "memory")
; #define PG8_BAR __builtin_amdgcn_s_barrier()
; #define PG8_SCHED __builtin_amdgcn_sched_barrier(0)
; template <class Epi>
; __device__ __forceinline__ void gemm_phase(LAS unsigned char* lds, const Gemm g, const StaticOrder& S, const Epi& E, const int tid) {
;     ...
;             PG8_LDB(B0, 1, 0); PG8_LDB(B1, 1, 1); PG8_SCHED; PG8_LDA(At, 1, 0); PG8_STAGE(PG8_SA(0, 1), a2 + hstep, voffA);
;             PG8_WAIT_V(8); PG8_WAIT_L(0); PG8_BAR; PG8_MMA(0, 0, At, B0); PG8_MMA(0, 1, At, B1); PG8_BAR; PG8_SCHED;
	s_add_i32 s44, 0, 0x18000
	v_add_u32_e32 v0, s44, v149
	s_add_i32 s45, 0, 0x1c000
	ds_read_b128 v[150:153], v0
	ds_read_b128 v[154:157], v0 offset:1024
	ds_read_b128 v[158:161], v0 offset:2048
	ds_read_b128 v[186:189], v0 offset:3072
	v_add_u32_e32 v0, s45, v149
	ds_read_b128 v[190:193], v0
	ds_read_b128 v[194:197], v0 offset:1024
	ds_read_b128 v[198:201], v0 offset:2048
	ds_read_b128 v[212:215], v0 offset:3072
	s_add_u32 s34, s34, 0x80000
	s_addc_u32 s35, s35, 0
	s_mov_b32 m0, s59
	v_lshl_add_u64 v[176:177], s[34:35], 0, v[130:131]
	ds_read_b128 v[216:219], v184 offset:32768
	global_load_lds_dwordx4 v[176:177], off
	ds_read_b128 v[220:223], v184 offset:33792
	ds_read_b128 v[224:227], v184 offset:34816
	v_lshl_add_u64 v[176:177], s[34:35], 0, v[134:135]
	s_mov_b32 m0, s60
	s_nop 0
	global_load_lds_dwordx4 v[176:177], off
	ds_read_b128 v[228:231], v184 offset:35840
	ds_read_b128 v[232:235], v184 offset:36864
	ds_read_b128 v[236:239], v184 offset:37888
	ds_read_b128 v[240:243], v184 offset:38912
	ds_read_b128 v[244:247], v184 offset:39936
	s_waitcnt vmcnt(8)
	s_waitcnt lgkmcnt(0)
	s_barrier
	s_waitcnt lgkmcnt(0)
	v_mfma_f32_16x16x32_bf16 v[126:129], v[150:153], v[216:219], v[126:129]
	v_mfma_f32_16x16x32_bf16 v[122:125], v[158:161], v[216:219], v[122:125]
	v_mfma_f32_16x16x32_bf16 v[110:113], v[150:153], v[224:227], v[110:113]
	v_mfma_f32_16x16x32_bf16 v[106:109], v[158:161], v[224:227], v[106:109]
	v_mfma_f32_16x16x32_bf16 v[94:97], v[150:153], v[232:235], v[94:97]
	v_mfma_f32_16x16x32_bf16 v[90:93], v[158:161], v[232:235], v[90:93]
	v_mfma_f32_16x16x32_bf16 v[78:81], v[150:153], v[240:243], v[78:81]
	v_mfma_f32_16x16x32_bf16 v[74:77], v[158:161], v[240:243], v[74:77]
	v_mfma_f32_16x16x32_bf16 v[126:129], v[154:157], v[220:223], v[126:129]
	v_mfma_f32_16x16x32_bf16 v[122:125], v[186:189], v[220:223], v[122:125]
	v_mfma_f32_16x16x32_bf16 v[110:113], v[154:157], v[228:231], v[110:113]
	v_mfma_f32_16x16x32_bf16 v[106:109], v[186:189], v[228:231], v[106:109]
	v_mfma_f32_16x16x32_bf16 v[94:97], v[154:157], v[236:239], v[94:97]
	v_mfma_f32_16x16x32_bf16 v[90:93], v[186:189], v[236:239], v[90:93]
	v_mfma_f32_16x16x32_bf16 v[78:81], v[154:157], v[244:247], v[78:81]
	v_mfma_f32_16x16x32_bf16 v[74:77], v[186:189], v[244:247], v[74:77]
	v_mfma_f32_16x16x32_bf16 v[118:121], v[190:193], v[216:219], v[118:121]
	v_mfma_f32_16x16x32_bf16 v[114:117], v[198:201], v[216:219], v[114:117]
	v_mfma_f32_16x16x32_bf16 v[102:105], v[190:193], v[224:227], v[102:105]
	v_mfma_f32_16x16x32_bf16 v[98:101], v[198:201], v[224:227], v[98:101]
	v_mfma_f32_16x16x32_bf16 v[86:89], v[190:193], v[232:235], v[86:89]
	v_mfma_f32_16x16x32_bf16 v[82:85], v[198:201], v[232:235], v[82:85]
	v_mfma_f32_16x16x32_bf16 v[70:73], v[190:193], v[240:243], v[70:73]
	v_mfma_f32_16x16x32_bf16 v[66:69], v[198:201], v[240:243], v[66:69]
	v_mfma_f32_16x16x32_bf16 v[118:121], v[194:197], v[220:223], v[118:121]
	v_mfma_f32_16x16x32_bf16 v[114:117], v[212:215], v[220:223], v[114:117]
	v_mfma_f32_16x16x32_bf16 v[102:105], v[194:197], v[228:231], v[102:105]
	v_mfma_f32_16x16x32_bf16 v[98:101], v[212:215], v[228:231], v[98:101]
	v_mfma_f32_16x16x32_bf16 v[86:89], v[194:197], v[236:239], v[86:89]
	v_mfma_f32_16x16x32_bf16 v[82:85], v[212:215], v[236:239], v[82:85]
	v_mfma_f32_16x16x32_bf16 v[70:73], v[194:197], v[244:247], v[70:73]
	v_mfma_f32_16x16x32_bf16 v[66:69], v[212:215], v[244:247], v[66:69]
	s_barrier
; #define PG8_STAGE(bufoff, gbase, voff) do { _Pragma("unroll") for (int _i = 0; _i < 2; ++_i) \
;         __builtin_amdgcn_global_load_lds((const unsigned*)((const char*)(gbase) + (voff)[_i]), (LAS unsigned*)(lds + (bufoff) + ldsw + _i * 8192), 16, 0, 0); } while (0)
; #define PG8_LDA(dst, b, h) do { _Pragma("unroll") for (int m = 0; m < 4; ++m) _Pragma("unroll") for (int k = 0; k < 2; ++k) dst[m][k] = *(const LAS bf16x8*)(lds + PG8_SA(b, h) + aoff + m * 2048 + k * 1024); } while (0)
; #define PG8_MMA(ai, bj, At, Bt) do { __builtin_amdgcn_s_setprio(1); _Pragma("unroll") for (int m = 0; m < 4; ++m) _Pragma("unroll") for (int n = 0; n < 2; ++n) _Pragma("unroll") for (int k = 0; k < 2; ++k) \
;         acc[ai][bj][m][n] = __builtin_amdgcn_mfma_f32_16x16x32_bf16(Bt[n][k], At[m][k], acc[ai][bj][m][n], 0, 0, 0); __builtin_amdgcn_s_setprio(0); } while (0)
; #define PG8_WAIT_V(n) asm volatile("s_waitcnt vmcnt(" #n ")" ::: "memory")
; #define PG8_WAIT_L(n) asm volatile("s_waitcnt lgkmcnt(" #n ")" ::: "memory")
; #define PG8_BAR __builtin_amdgcn_s_barrier()
; #define PG8_SCHED __builtin_amdgcn_sched_barrier(0)
; template <class Epi>
; __device__ __forceinline__ void gemm_phase(LAS unsigned char* lds, const Gemm g, const StaticOrder& S, const Epi& E, const int tid) {
;     ...
;             PG8_LDA(At, 1, 1); PG8_STAGE(PG8_SB(1, 0), b3, voffB); PG8_STAGE(PG8_SB(1, 1), b3 + bhs, voffB); PG8_STAGE(PG8_SA(1, 0), a3, voffA);
;             PG8_WAIT_V(8); PG8_WAIT_L(0); PG8_BAR; PG8_MMA(1, 0, At, B0); PG8_MMA(1, 1, At, B1); PG8_BAR; PG8_SCHED;
;     ...
;         if (ALIGN_EPI) { if (wr == 0) PG8_BAR; }
	s_add_i32 s34, s44, s56
	v_lshl_add_u64 v[162:163], v[162:163], 0, s[70:71]
	s_mov_b32 m0, s34
	ds_read_b128 v[216:219], v184 offset:49152
	global_load_lds_dwordx4 v[162:163], off
	ds_read_b128 v[220:223], v184 offset:50176
	ds_read_b128 v[224:227], v184 offset:51200
	s_add_i32 m0, s34, 0x2000
	s_add_u32 s28, s28, 0x8080
	v_lshl_add_u64 v[162:163], v[248:249], 0, s[70:71]
	s_addc_u32 s29, s29, 0
	s_add_i32 s34, s45, s56
	global_load_lds_dwordx4 v[162:163], off
	ds_read_b128 v[228:231], v184 offset:52224
	ds_read_b128 v[232:235], v184 offset:53248
	v_lshl_add_u64 v[162:163], s[28:29], 0, v[132:133]
	s_mov_b32 m0, s34
	s_nop 0
	global_load_lds_dwordx4 v[162:163], off
	ds_read_b128 v[236:239], v184 offset:54272
	ds_read_b128 v[240:243], v184 offset:55296
	v_lshl_add_u64 v[162:163], s[28:29], 0, v[136:137]
	s_add_i32 m0, s34, 0x2000
	s_nop 0
	global_load_lds_dwordx4 v[162:163], off
	ds_read_b128 v[244:247], v184 offset:56320
	v_lshl_add_u64 v[162:163], v[172:173], 0, s[70:71]
	s_mov_b32 m0, s61
	s_nop 0
	global_load_lds_dwordx4 v[162:163], off
	v_lshl_add_u64 v[162:163], v[174:175], 0, s[70:71]
	s_mov_b32 m0, s62
	s_nop 0
	global_load_lds_dwordx4 v[162:163], off
	s_waitcnt vmcnt(8)
	s_waitcnt lgkmcnt(0)
	s_barrier
	s_waitcnt lgkmcnt(0)
	v_mfma_f32_16x16x32_bf16 v[62:65], v[150:153], v[216:219], v[62:65]
	v_mfma_f32_16x16x32_bf16 v[58:61], v[158:161], v[216:219], v[58:61]
	v_mfma_f32_16x16x32_bf16 v[46:49], v[150:153], v[224:227], v[46:49]
	v_mfma_f32_16x16x32_bf16 v[42:45], v[158:161], v[224:227], v[42:45]
	v_mfma_f32_16x16x32_bf16 v[30:33], v[150:153], v[232:235], v[30:33]
	v_mfma_f32_16x16x32_bf16 v[26:29], v[158:161], v[232:235], v[26:29]
	v_mfma_f32_16x16x32_bf16 v[14:17], v[150:153], v[240:243], v[14:17]
	v_mfma_f32_16x16x32_bf16 v[10:13], v[158:161], v[240:243], v[10:13]
	v_mfma_f32_16x16x32_bf16 v[62:65], v[154:157], v[220:223], v[62:65]
	v_mfma_f32_16x16x32_bf16 v[58:61], v[186:189], v[220:223], v[58:61]
	v_mfma_f32_16x16x32_bf16 v[46:49], v[154:157], v[228:231], v[46:49]
	v_mfma_f32_16x16x32_bf16 v[42:45], v[186:189], v[228:231], v[42:45]
	v_mfma_f32_16x16x32_bf16 v[30:33], v[154:157], v[236:239], v[30:33]
	v_mfma_f32_16x16x32_bf16 v[26:29], v[186:189], v[236:239], v[26:29]
	v_mfma_f32_16x16x32_bf16 v[14:17], v[154:157], v[244:247], v[14:17]
	v_mfma_f32_16x16x32_bf16 v[10:13], v[186:189], v[244:247], v[10:13]
	v_mfma_f32_16x16x32_bf16 v[54:57], v[190:193], v[216:219], v[54:57]
	v_mfma_f32_16x16x32_bf16 v[50:53], v[198:201], v[216:219], v[50:53]
	v_mfma_f32_16x16x32_bf16 v[38:41], v[190:193], v[224:227], v[38:41]
	v_mfma_f32_16x16x32_bf16 v[34:37], v[198:201], v[224:227], v[34:37]
	v_mfma_f32_16x16x32_bf16 v[22:25], v[190:193], v[232:235], v[22:25]
	v_mfma_f32_16x16x32_bf16 v[18:21], v[198:201], v[232:235], v[18:21]
	v_mfma_f32_16x16x32_bf16 v[6:9], v[190:193], v[240:243], v[6:9]
	v_mfma_f32_16x16x32_bf16 v[2:5], v[198:201], v[240:243], v[2:5]
	v_mfma_f32_16x16x32_bf16 v[54:57], v[194:197], v[220:223], v[54:57]
	v_mfma_f32_16x16x32_bf16 v[50:53], v[212:215], v[220:223], v[50:53]
	v_mfma_f32_16x16x32_bf16 v[38:41], v[194:197], v[228:231], v[38:41]
	v_mfma_f32_16x16x32_bf16 v[34:37], v[212:215], v[228:231], v[34:37]
	v_mfma_f32_16x16x32_bf16 v[22:25], v[194:197], v[236:239], v[22:25]
	v_mfma_f32_16x16x32_bf16 v[18:21], v[212:215], v[236:239], v[18:21]
	v_mfma_f32_16x16x32_bf16 v[6:9], v[194:197], v[244:247], v[6:9]
	v_mfma_f32_16x16x32_bf16 v[2:5], v[212:215], v[244:247], v[2:5]
	s_barrier
	s_add_i32 s39, s39, 2
	s_add_u32 s37, s37, 0x100
	s_addc_u32 s38, s38, 0
	s_add_u32 s26, s26, 0x100
	s_addc_u32 s27, s27, 0
	s_cmp_gt_u32 s39, 29
	s_cbranch_scc0 .LBB0_546
	s_and_b64 vcc, exec, s[14:15]
	s_cbranch_vccz .LBB0_549
	s_barrier

; #define PG8_STAGE(bufoff, gbase, voff) do { _Pragma("unroll") for (int _i = 0; _i < 2; ++_i) \
;         __builtin_amdgcn_global_load_lds((const unsigned*)((const char*)(gbase) + (voff)[_i]), (LAS unsigned*)(lds + (bufoff) + ldsw + _i * 8192), 16, 0, 0); } while (0)
; #define PG8_LDA(dst, b, h) do { _Pragma("unroll") for (int m = 0; m < 4; ++m) _Pragma("unroll") for (int k = 0; k < 2; ++k) dst[m][k] = *(const LAS bf16x8*)(lds + PG8_SA(b, h) + aoff + m * 2048 + k * 1024); } while (0)
; #define PG8_LDB(dst, b, h) do { _Pragma("unroll") for (int n = 0; n < 2; ++n) _Pragma("unroll") for (int k = 0; k < 2; ++k) dst[n][k] = *(const LAS bf16x8*)(lds + PG8_SB(b, h) + boff + n * 2048 + k * 1024); } while (0)
; #define PG8_BAR __builtin_amdgcn_s_barrier()
; template <class Epi>
; __device__ __forceinline__ void gemm_phase(LAS unsigned char* lds, const Gemm g, const StaticOrder& S, const Epi& E, const int tid) {
;     ...
;         const bool has_next = S.next(ui + 1, nxt);
;         const char* nA = has_next ? (const char*)g.A + (size_t)nxt.pm * tstep : cA; const char* nB = has_next ? (const char*)g.Bt + (size_t)nxt.pn * tstep : cB;
;         for (int t = 0; t < ntt; t += 2) {
;             const bool last = (t == ntt - 2);
;             const bool s1 = Epi::TWO && (t >= nt), s2 = Epi::TWO && (t + 2 >= nt);
;             const char* a1 = (s1 ? cA2 + (size_t)(t - nt + 1) * kstep : cA + (size_t)(t + 1) * kstep);
;             const char* a2 = last ? nA : (s2 ? cA2 + (size_t)(t + 2 - nt) * kstep : cA + (size_t)(t + 2) * kstep);
;             const char* b2 = last ? nB : (s2 ? cB2 + (size_t)(t + 2 - nt) * kstep : cB + (size_t)(t + 2) * kstep);
;             const char* a3 = a2 + kstep; const char* b3 = b2 + kstep;
;             if constexpr (Epi::TWO) { if (t == nt) E.mid(acc, cur, wr, wc, fr, fq); }
;             if constexpr (SP2) {
;             PG8_LDB(B0, 0, 0); PG8_LDB(B1, 0, 1); PG8_SCHED; PG8_LDA(At, 0, 0); PG8_STAGE(PG8_SA(1, 1), a1 + hstep, voffA);
;             PG8_WAIT_V(8); PG8_WAIT_L(0); PG8_BAR; PG8_MMA(0, 0, At, B0); PG8_MMA(0, 1, At, B1); PG8_BAR; PG8_SCHED;
;     ...
; #pragma unroll
;         for (int a = 0; a < 2; ++a)
; #pragma unroll
;             for (int b = 0; b < 2; ++b)
; #pragma unroll
;                 for (int m = 0; m < 4; ++m)
; #pragma unroll
;                     for (int n = 0; n < 2; ++n) acc[a][b][m][n] = (f32x4){0.f, 0.f, 0.f, 0.f};
.LBB0_843:
	s_ashr_i32 s15, s14, 31
	s_lshl_b64 s[18:19], s[14:15], 20
	s_add_u32 s18, s2, s18
	s_addc_u32 s19, s33, s19
	s_and_b64 s[20:21], s[16:17], exec
	s_cselect_b32 s15, s19, s29
	s_cselect_b32 s43, s18, s28
	s_ashr_i32 s13, s12, 31
	s_lshl_b64 s[20:21], s[12:13], 20
	s_add_u32 s20, s8, s20
	s_addc_u32 s21, s9, s21
	s_and_b64 s[30:31], s[16:17], exec
	s_cselect_b32 s13, s21, s27
	s_cselect_b32 s44, s20, s26
	s_add_u32 s45, s26, 0x100
	s_addc_u32 s46, s27, 0
	s_add_u32 s26, s28, 0x80080
	v_mov_b32_e32 v2, 0
	s_addc_u32 s27, s29, 0
	s_mov_b32 s47, -2
	v_mov_b32_e32 v3, v2
	v_mov_b32_e32 v4, v2
	v_mov_b32_e32 v5, v2
	v_mov_b32_e32 v6, v2
	v_mov_b32_e32 v7, v2
	v_mov_b32_e32 v8, v2
	v_mov_b32_e32 v9, v2
	v_mov_b32_e32 v10, v2
	v_mov_b32_e32 v11, v2
	v_mov_b32_e32 v12, v2
	v_mov_b32_e32 v13, v2
	v_mov_b32_e32 v18, v2
	v_mov_b32_e32 v19, v2
	v_mov_b32_e32 v20, v2
	v_mov_b32_e32 v21, v2
	v_mov_b32_e32 v26, v2
	v_mov_b32_e32 v27, v2
	v_mov_b32_e32 v28, v2
	v_mov_b32_e32 v29, v2
	v_mov_b32_e32 v34, v2
	v_mov_b32_e32 v35, v2
	v_mov_b32_e32 v36, v2
	v_mov_b32_e32 v37, v2
	v_mov_b32_e32 v42, v2
	v_mov_b32_e32 v43, v2
	v_mov_b32_e32 v44, v2
	v_mov_b32_e32 v45, v2
	v_mov_b32_e32 v50, v2
	v_mov_b32_e32 v51, v2
	v_mov_b32_e32 v52, v2
	v_mov_b32_e32 v53, v2
	v_mov_b32_e32 v14, v2
	v_mov_b32_e32 v15, v2
	v_mov_b32_e32 v16, v2
	v_mov_b32_e32 v17, v2
	v_mov_b32_e32 v22, v2
	v_mov_b32_e32 v23, v2
	v_mov_b32_e32 v24, v2
	v_mov_b32_e32 v25, v2
	v_mov_b32_e32 v30, v2
	v_mov_b32_e32 v31, v2
	v_mov_b32_e32 v32, v2
	v_mov_b32_e32 v33, v2
	v_mov_b32_e32 v38, v2
	v_mov_b32_e32 v39, v2
	v_mov_b32_e32 v40, v2
	v_mov_b32_e32 v41, v2
	v_mov_b32_e32 v46, v2
	v_mov_b32_e32 v47, v2
	v_mov_b32_e32 v48, v2
	v_mov_b32_e32 v49, v2
	v_mov_b32_e32 v54, v2
	v_mov_b32_e32 v55, v2
	v_mov_b32_e32 v56, v2
	v_mov_b32_e32 v57, v2
	v_mov_b32_e32 v58, v2
	v_mov_b32_e32 v59, v2
	v_mov_b32_e32 v60, v2
	v_mov_b32_e32 v61, v2
	v_mov_b32_e32 v62, v2
	v_mov_b32_e32 v63, v2
	v_mov_b32_e32 v64, v2
	v_mov_b32_e32 v65, v2
	v_mov_b32_e32 v66, v2
	v_mov_b32_e32 v67, v2
	v_mov_b32_e32 v68, v2
	v_mov_b32_e32 v69, v2
	v_mov_b32_e32 v70, v2
	v_mov_b32_e32 v71, v2
	v_mov_b32_e32 v72, v2
	v_mov_b32_e32 v73, v2
	v_mov_b32_e32 v74, v2
	v_mov_b32_e32 v75, v2
	v_mov_b32_e32 v76, v2
	v_mov_b32_e32 v77, v2
	v_mov_b32_e32 v82, v2
	v_mov_b32_e32 v83, v2
	v_mov_b32_e32 v84, v2
	v_mov_b32_e32 v85, v2
	v_mov_b32_e32 v90, v2
	v_mov_b32_e32 v91, v2
	v_mov_b32_e32 v92, v2
	v_mov_b32_e32 v93, v2
	v_mov_b32_e32 v98, v2
	v_mov_b32_e32 v99, v2
	v_mov_b32_e32 v100, v2
	v_mov_b32_e32 v101, v2
	v_mov_b32_e32 v106, v2
	v_mov_b32_e32 v107, v2
	v_mov_b32_e32 v108, v2
	v_mov_b32_e32 v109, v2
	v_mov_b32_e32 v114, v2
	v_mov_b32_e32 v115, v2
	v_mov_b32_e32 v116, v2
	v_mov_b32_e32 v117, v2
	v_mov_b32_e32 v78, v2
	v_mov_b32_e32 v79, v2
	v_mov_b32_e32 v80, v2
	v_mov_b32_e32 v81, v2
	v_mov_b32_e32 v86, v2
	v_mov_b32_e32 v87, v2
	v_mov_b32_e32 v88, v2
	v_mov_b32_e32 v89, v2
	v_mov_b32_e32 v94, v2
	v_mov_b32_e32 v95, v2
	v_mov_b32_e32 v96, v2
	v_mov_b32_e32 v97, v2
	v_mov_b32_e32 v102, v2
	v_mov_b32_e32 v103, v2
	v_mov_b32_e32 v104, v2
	v_mov_b32_e32 v105, v2
	v_mov_b32_e32 v110, v2
	v_mov_b32_e32 v111, v2
	v_mov_b32_e32 v112, v2
	v_mov_b32_e32 v113, v2
	v_mov_b32_e32 v118, v2
	v_mov_b32_e32 v119, v2
	v_mov_b32_e32 v120, v2
	v_mov_b32_e32 v121, v2
	v_mov_b32_e32 v122, v2
	v_mov_b32_e32 v123, v2
	v_mov_b32_e32 v124, v2
	v_mov_b32_e32 v125, v2
	v_mov_b32_e32 v126, v2
	v_mov_b32_e32 v127, v2
	v_mov_b32_e32 v128, v2
	v_mov_b32_e32 v129, v2
	s_and_b64 vcc, exec, s[10:11]
	s_cbranch_vccnz .Lprio_skip_844
	s_setprio 1
.Lprio_skip_844:
.LBB0_844:
	s_add_u32 s28, s26, 0xfff80080
	s_addc_u32 s29, s27, -1
	s_add_i32 s48, 0, 0x10000
	s_cmp_eq_u32 s47, 28
	s_cselect_b32 s31, s15, s29
	s_cselect_b32 s30, s43, s28
	v_add_u32_e32 v145, s48, v142
	s_cselect_b32 s29, s13, s46
	s_cselect_b32 s28, s44, s45
	s_add_i32 s50, 0, 0x14000
	ds_read_b128 v[146:149], v145
	ds_read_b128 v[150:153], v145 offset:1024
	ds_read_b128 v[154:157], v145 offset:2048
	ds_read_b128 v[158:161], v145 offset:3072
	v_add_u32_e32 v145, s50, v142
	ds_read_b128 v[162:165], v145
	ds_read_b128 v[166:169], v145 offset:1024
	ds_read_b128 v[178:181], v145 offset:2048
	ds_read_b128 v[182:185], v145 offset:3072
	v_lshl_add_u64 v[172:173], s[26:27], 0, v[138:139]
	s_add_i32 m0, s23, 0xc000
	ds_read_b128 v[186:189], v144
	global_load_lds_dwordx4 v[172:173], off
	ds_read_b128 v[190:193], v144 offset:1024
	ds_read_b128 v[194:197], v144 offset:2048
	v_lshl_add_u64 v[172:173], s[26:27], 0, v[136:137]
	s_add_i32 m0, s23, 0xe000
	s_nop 0
	global_load_lds_dwordx4 v[172:173], off
	ds_read_b128 v[198:201], v144 offset:3072
	ds_read_b128 v[212:215], v144 offset:4096
	ds_read_b128 v[216:219], v144 offset:5120
	ds_read_b128 v[220:223], v144 offset:6144
	ds_read_b128 v[224:227], v144 offset:7168
	s_waitcnt vmcnt(8)
	s_waitcnt lgkmcnt(0)
	s_barrier
; #define PG8_STAGE(bufoff, gbase, voff) do { _Pragma("unroll") for (int _i = 0; _i < 2; ++_i) \
;         __builtin_amdgcn_global_load_lds((const unsigned*)((const char*)(gbase) + (voff)[_i]), (LAS unsigned*)(lds + (bufoff) + ldsw + _i * 8192), 16, 0, 0); } while (0)
; #define PG8_LDA(dst, b, h) do { _Pragma("unroll") for (int m = 0; m < 4; ++m) _Pragma("unroll") for (int k = 0; k < 2; ++k) dst[m][k] = *(const LAS bf16x8*)(lds + PG8_SA(b, h) + aoff + m * 2048 + k * 1024); } while (0)
; #define PG8_MMA(ai, bj, At, Bt) do { __builtin_amdgcn_s_setprio(1); _Pragma("unroll") for (int m = 0; m < 4; ++m) _Pragma("unroll") for (int n = 0; n < 2; ++n) _Pragma("unroll") for (int k = 0; k < 2; ++k) \
;         acc[ai][bj][m][n] = __builtin_amdgcn_mfma_f32_16x16x32_bf16(Bt[n][k], At[m][k], acc[ai][bj][m][n], 0, 0, 0); __builtin_amdgcn_s_setprio(0); } while (0)
; #define PG8_WAIT_V(n) asm volatile("s_waitcnt vmcnt(" #n ")" ::: "memory")
; #define PG8_WAIT_L(n) asm volatile("s_waitcnt lgkmcnt(" #n ")" ::: "memory")
; #define PG8_BAR __builtin_amdgcn_s_barrier()
; #define PG8_SCHED __builtin_amdgcn_sched_barrier(0)
; template <class Epi>
; __device__ __forceinline__ void gemm_phase(LAS unsigned char* lds, const Gemm g, const StaticOrder& S, const Epi& E, const int tid) {
;     ...
;             PG8_WAIT_V(8); PG8_WAIT_L(0); PG8_BAR; PG8_MMA(0, 0, At, B0); PG8_MMA(0, 1, At, B1); PG8_BAR; PG8_SCHED;
;             PG8_LDA(At, 0, 1); PG8_STAGE(PG8_SB(0, 0), b2, voffB); PG8_STAGE(PG8_SB(0, 1), b2 + bhs, voffB); PG8_STAGE(PG8_SA(0, 0), a2, voffA);
;             PG8_WAIT_V(8); PG8_WAIT_L(0); PG8_BAR; PG8_MMA(1, 0, At, B0); PG8_MMA(1, 1, At, B1); PG8_BAR; PG8_SCHED;
	s_waitcnt lgkmcnt(0)
	v_mfma_f32_16x16x32_bf16 v[126:129], v[146:149], v[186:189], v[126:129]
	v_mfma_f32_16x16x32_bf16 v[122:125], v[154:157], v[186:189], v[122:125]
	v_mfma_f32_16x16x32_bf16 v[118:121], v[146:149], v[194:197], v[118:121]
	v_mfma_f32_16x16x32_bf16 v[110:113], v[154:157], v[194:197], v[110:113]
	v_mfma_f32_16x16x32_bf16 v[102:105], v[146:149], v[212:215], v[102:105]
	v_mfma_f32_16x16x32_bf16 v[94:97], v[154:157], v[212:215], v[94:97]
	v_mfma_f32_16x16x32_bf16 v[86:89], v[146:149], v[220:223], v[86:89]
	v_mfma_f32_16x16x32_bf16 v[78:81], v[154:157], v[220:223], v[78:81]
	v_mfma_f32_16x16x32_bf16 v[126:129], v[150:153], v[190:193], v[126:129]
	v_mfma_f32_16x16x32_bf16 v[122:125], v[158:161], v[190:193], v[122:125]
	v_mfma_f32_16x16x32_bf16 v[118:121], v[150:153], v[198:201], v[118:121]
	v_mfma_f32_16x16x32_bf16 v[110:113], v[158:161], v[198:201], v[110:113]
	v_mfma_f32_16x16x32_bf16 v[102:105], v[150:153], v[216:219], v[102:105]
	v_mfma_f32_16x16x32_bf16 v[94:97], v[158:161], v[216:219], v[94:97]
	v_mfma_f32_16x16x32_bf16 v[86:89], v[150:153], v[224:227], v[86:89]
	v_mfma_f32_16x16x32_bf16 v[78:81], v[158:161], v[224:227], v[78:81]
	v_mfma_f32_16x16x32_bf16 v[114:117], v[162:165], v[186:189], v[114:117]
	v_mfma_f32_16x16x32_bf16 v[106:109], v[178:181], v[186:189], v[106:109]
	v_mfma_f32_16x16x32_bf16 v[98:101], v[162:165], v[194:197], v[98:101]
	v_mfma_f32_16x16x32_bf16 v[90:93], v[178:181], v[194:197], v[90:93]
	v_mfma_f32_16x16x32_bf16 v[82:85], v[162:165], v[212:215], v[82:85]
	v_mfma_f32_16x16x32_bf16 v[74:77], v[178:181], v[212:215], v[74:77]
	v_mfma_f32_16x16x32_bf16 v[70:73], v[162:165], v[220:223], v[70:73]
	v_mfma_f32_16x16x32_bf16 v[66:69], v[178:181], v[220:223], v[66:69]
	v_mfma_f32_16x16x32_bf16 v[114:117], v[166:169], v[190:193], v[114:117]
	v_mfma_f32_16x16x32_bf16 v[106:109], v[182:185], v[190:193], v[106:109]
	v_mfma_f32_16x16x32_bf16 v[98:101], v[166:169], v[198:201], v[98:101]
	v_mfma_f32_16x16x32_bf16 v[90:93], v[182:185], v[198:201], v[90:93]
	v_mfma_f32_16x16x32_bf16 v[82:85], v[166:169], v[216:219], v[82:85]
	v_mfma_f32_16x16x32_bf16 v[74:77], v[182:185], v[216:219], v[74:77]
	v_mfma_f32_16x16x32_bf16 v[70:73], v[166:169], v[224:227], v[70:73]
	v_mfma_f32_16x16x32_bf16 v[66:69], v[182:185], v[224:227], v[66:69]
	s_barrier
	s_add_i32 s48, s48, s37
	v_lshl_add_u64 v[172:173], s[28:29], 0, v[0:1]
	s_mov_b32 m0, s48
	ds_read_b128 v[186:189], v144 offset:16384
	global_load_lds_dwordx4 v[172:173], off
	ds_read_b128 v[190:193], v144 offset:17408
	ds_read_b128 v[194:197], v144 offset:18432
	s_add_i32 m0, s48, 0x2000
	s_add_u32 s48, s28, 0x8000
	v_lshl_add_u64 v[174:175], s[28:29], 0, v[134:135]
	s_addc_u32 s49, s29, 0
	s_add_i32 s50, s50, s37
	global_load_lds_dwordx4 v[174:175], off
	ds_read_b128 v[198:201], v144 offset:19456
	ds_read_b128 v[212:215], v144 offset:20480
	v_lshl_add_u64 v[176:177], s[48:49], 0, v[0:1]
	s_mov_b32 m0, s50
	v_lshl_add_u64 v[228:229], s[30:31], 0, v[132:133]
	global_load_lds_dwordx4 v[176:177], off
	ds_read_b128 v[216:219], v144 offset:21504
	ds_read_b128 v[220:223], v144 offset:22528
	v_lshl_add_u64 v[176:177], s[48:49], 0, v[134:135]
	s_add_i32 m0, s50, 0x2000
	s_nop 0
	global_load_lds_dwordx4 v[176:177], off
	ds_read_b128 v[224:227], v144 offset:23552
	v_lshl_add_u64 v[176:177], s[30:31], 0, v[130:131]
	s_mov_b32 m0, s23
	s_nop 0
	global_load_lds_dwordx4 v[176:177], off
	s_mov_b32 m0, s25
	s_nop 0
	global_load_lds_dwordx4 v[228:229], off
	s_waitcnt vmcnt(8)
	s_waitcnt lgkmcnt(0)
	s_barrier
	s_waitcnt lgkmcnt(0)
	v_mfma_f32_16x16x32_bf16 v[62:65], v[146:149], v[186:189], v[62:65]
	v_mfma_f32_16x16x32_bf16 v[58:61], v[154:157], v[186:189], v[58:61]
	v_mfma_f32_16x16x32_bf16 v[54:57], v[146:149], v[194:197], v[54:57]
	v_mfma_f32_16x16x32_bf16 v[46:49], v[154:157], v[194:197], v[46:49]
	v_mfma_f32_16x16x32_bf16 v[38:41], v[146:149], v[212:215], v[38:41]
	v_mfma_f32_16x16x32_bf16 v[30:33], v[154:157], v[212:215], v[30:33]
	v_mfma_f32_16x16x32_bf16 v[22:25], v[146:149], v[220:223], v[22:25]
	v_mfma_f32_16x16x32_bf16 v[14:17], v[154:157], v[220:223], v[14:17]
	v_mfma_f32_16x16x32_bf16 v[62:65], v[150:153], v[190:193], v[62:65]
	v_mfma_f32_16x16x32_bf16 v[58:61], v[158:161], v[190:193], v[58:61]
	v_mfma_f32_16x16x32_bf16 v[54:57], v[150:153], v[198:201], v[54:57]
	v_mfma_f32_16x16x32_bf16 v[46:49], v[158:161], v[198:201], v[46:49]
	v_mfma_f32_16x16x32_bf16 v[38:41], v[150:153], v[216:219], v[38:41]
	v_mfma_f32_16x16x32_bf16 v[30:33], v[158:161], v[216:219], v[30:33]
	v_mfma_f32_16x16x32_bf16 v[22:25], v[150:153], v[224:227], v[22:25]
	v_mfma_f32_16x16x32_bf16 v[14:17], v[158:161], v[224:227], v[14:17]
	v_mfma_f32_16x16x32_bf16 v[50:53], v[162:165], v[186:189], v[50:53]
	v_mfma_f32_16x16x32_bf16 v[42:45], v[178:181], v[186:189], v[42:45]
	v_mfma_f32_16x16x32_bf16 v[34:37], v[162:165], v[194:197], v[34:37]
	v_mfma_f32_16x16x32_bf16 v[26:29], v[178:181], v[194:197], v[26:29]
	v_mfma_f32_16x16x32_bf16 v[18:21], v[162:165], v[212:215], v[18:21]
	v_mfma_f32_16x16x32_bf16 v[10:13], v[178:181], v[212:215], v[10:13]
	v_mfma_f32_16x16x32_bf16 v[6:9], v[162:165], v[220:223], v[6:9]
	v_mfma_f32_16x16x32_bf16 v[2:5], v[178:181], v[220:223], v[2:5]
	v_mfma_f32_16x16x32_bf16 v[50:53], v[166:169], v[190:193], v[50:53]
	v_mfma_f32_16x16x32_bf16 v[42:45], v[182:185], v[190:193], v[42:45]
	v_mfma_f32_16x16x32_bf16 v[34:37], v[166:169], v[198:201], v[34:37]
	v_mfma_f32_16x16x32_bf16 v[26:29], v[182:185], v[198:201], v[26:29]
	v_mfma_f32_16x16x32_bf16 v[18:21], v[166:169], v[216:219], v[18:21]
	v_mfma_f32_16x16x32_bf16 v[10:13], v[182:185], v[216:219], v[10:13]
	v_mfma_f32_16x16x32_bf16 v[6:9], v[166:169], v[224:227], v[6:9]
	v_mfma_f32_16x16x32_bf16 v[2:5], v[182:185], v[224:227], v[2:5]
	s_barrier
; #define PG8_STAGE(bufoff, gbase, voff) do { _Pragma("unroll") for (int _i = 0; _i < 2; ++_i) \
;         __builtin_amdgcn_global_load_lds((const unsigned*)((const char*)(gbase) + (voff)[_i]), (LAS unsigned*)(lds + (bufoff) + ldsw + _i * 8192), 16, 0, 0); } while (0)
; #define PG8_LDA(dst, b, h) do { _Pragma("unroll") for (int m = 0; m < 4; ++m) _Pragma("unroll") for (int k = 0; k < 2; ++k) dst[m][k] = *(const LAS bf16x8*)(lds + PG8_SA(b, h) + aoff + m * 2048 + k * 1024); } while (0)
; #define PG8_LDB(dst, b, h) do { _Pragma("unroll") for (int n = 0; n < 2; ++n) _Pragma("unroll") for (int k = 0; k < 2; ++k) dst[n][k] = *(const LAS bf16x8*)(lds + PG8_SB(b, h) + boff + n * 2048 + k * 1024); } while (0)
; #define PG8_MMA(ai, bj, At, Bt) do { __builtin_amdgcn_s_setprio(1); _Pragma("unroll") for (int m = 0; m < 4; ++m) _Pragma("unroll") for (int n = 0; n < 2; ++n) _Pragma("unroll") for (int k = 0; k < 2; ++k) \
;         acc[ai][bj][m][n] = __builtin_amdgcn_mfma_f32_16x16x32_bf16(Bt[n][k], At[m][k], acc[ai][bj][m][n], 0, 0, 0); __builtin_amdgcn_s_setprio(0); } while (0)
; #define PG8_WAIT_V(n) asm volatile("s_waitcnt vmcnt(" #n ")" ::: "memory")
; #define PG8_WAIT_L(n) asm volatile("s_waitcnt lgkmcnt(" #n ")" ::: "memory")
; #define PG8_BAR __builtin_amdgcn_s_barrier()
; #define PG8_SCHED __builtin_amdgcn_sched_barrier(0)
; template <class Epi>
; __device__ __forceinline__ void gemm_phase(LAS unsigned char* lds, const Gemm g, const StaticOrder& S, const Epi& E, const int tid) {
;     ...
;             PG8_LDB(B0, 1, 0); PG8_LDB(B1, 1, 1); PG8_SCHED; PG8_LDA(At, 1, 0); PG8_STAGE(PG8_SA(0, 1), a2 + hstep, voffA);
;             PG8_WAIT_V(8); PG8_WAIT_L(0); PG8_BAR; PG8_MMA(0, 0, At, B0); PG8_MMA(0, 1, At, B1); PG8_BAR; PG8_SCHED;
	s_add_i32 s48, 0, 0x18000
	v_add_u32_e32 v145, s48, v142
	s_add_i32 s49, 0, 0x1c000
	ds_read_b128 v[146:149], v145
	ds_read_b128 v[150:153], v145 offset:1024
	ds_read_b128 v[154:157], v145 offset:2048
	ds_read_b128 v[158:161], v145 offset:3072
	v_add_u32_e32 v145, s49, v142
	ds_read_b128 v[162:165], v145
	ds_read_b128 v[166:169], v145 offset:1024
	ds_read_b128 v[178:181], v145 offset:2048
	ds_read_b128 v[182:185], v145 offset:3072
	s_add_u32 s30, s30, 0x80000
	s_addc_u32 s31, s31, 0
	s_mov_b32 m0, s38
	v_lshl_add_u64 v[230:231], s[30:31], 0, v[130:131]
	ds_read_b128 v[186:189], v144 offset:32768
	global_load_lds_dwordx4 v[230:231], off
	ds_read_b128 v[190:193], v144 offset:33792
	ds_read_b128 v[194:197], v144 offset:34816
	v_lshl_add_u64 v[230:231], s[30:31], 0, v[132:133]
	s_mov_b32 m0, s39
	s_nop 0
	global_load_lds_dwordx4 v[230:231], off
	ds_read_b128 v[198:201], v144 offset:35840
	ds_read_b128 v[212:215], v144 offset:36864
	ds_read_b128 v[216:219], v144 offset:37888
	ds_read_b128 v[220:223], v144 offset:38912
	ds_read_b128 v[224:227], v144 offset:39936
	s_waitcnt vmcnt(8)
	s_waitcnt lgkmcnt(0)
	s_barrier
	s_waitcnt lgkmcnt(0)
	v_mfma_f32_16x16x32_bf16 v[126:129], v[146:149], v[186:189], v[126:129]
	v_mfma_f32_16x16x32_bf16 v[122:125], v[154:157], v[186:189], v[122:125]
	v_mfma_f32_16x16x32_bf16 v[118:121], v[146:149], v[194:197], v[118:121]
	v_mfma_f32_16x16x32_bf16 v[110:113], v[154:157], v[194:197], v[110:113]
	v_mfma_f32_16x16x32_bf16 v[102:105], v[146:149], v[212:215], v[102:105]
	v_mfma_f32_16x16x32_bf16 v[94:97], v[154:157], v[212:215], v[94:97]
	v_mfma_f32_16x16x32_bf16 v[86:89], v[146:149], v[220:223], v[86:89]
	v_mfma_f32_16x16x32_bf16 v[78:81], v[154:157], v[220:223], v[78:81]
	v_mfma_f32_16x16x32_bf16 v[126:129], v[150:153], v[190:193], v[126:129]
	v_mfma_f32_16x16x32_bf16 v[122:125], v[158:161], v[190:193], v[122:125]
	v_mfma_f32_16x16x32_bf16 v[118:121], v[150:153], v[198:201], v[118:121]
	v_mfma_f32_16x16x32_bf16 v[110:113], v[158:161], v[198:201], v[110:113]
	v_mfma_f32_16x16x32_bf16 v[102:105], v[150:153], v[216:219], v[102:105]
	v_mfma_f32_16x16x32_bf16 v[94:97], v[158:161], v[216:219], v[94:97]
	v_mfma_f32_16x16x32_bf16 v[86:89], v[150:153], v[224:227], v[86:89]
	v_mfma_f32_16x16x32_bf16 v[78:81], v[158:161], v[224:227], v[78:81]
	v_mfma_f32_16x16x32_bf16 v[114:117], v[162:165], v[186:189], v[114:117]
	v_mfma_f32_16x16x32_bf16 v[106:109], v[178:181], v[186:189], v[106:109]
	v_mfma_f32_16x16x32_bf16 v[98:101], v[162:165], v[194:197], v[98:101]
	v_mfma_f32_16x16x32_bf16 v[90:93], v[178:181], v[194:197], v[90:93]
	v_mfma_f32_16x16x32_bf16 v[82:85], v[162:165], v[212:215], v[82:85]
	v_mfma_f32_16x16x32_bf16 v[74:77], v[178:181], v[212:215], v[74:77]
	v_mfma_f32_16x16x32_bf16 v[70:73], v[162:165], v[220:223], v[70:73]
	v_mfma_f32_16x16x32_bf16 v[66:69], v[178:181], v[220:223], v[66:69]
	v_mfma_f32_16x16x32_bf16 v[114:117], v[166:169], v[190:193], v[114:117]
	v_mfma_f32_16x16x32_bf16 v[106:109], v[182:185], v[190:193], v[106:109]
	v_mfma_f32_16x16x32_bf16 v[98:101], v[166:169], v[198:201], v[98:101]
	v_mfma_f32_16x16x32_bf16 v[90:93], v[182:185], v[198:201], v[90:93]
	v_mfma_f32_16x16x32_bf16 v[82:85], v[166:169], v[216:219], v[82:85]
	v_mfma_f32_16x16x32_bf16 v[74:77], v[182:185], v[216:219], v[74:77]
	v_mfma_f32_16x16x32_bf16 v[70:73], v[166:169], v[224:227], v[70:73]
	v_mfma_f32_16x16x32_bf16 v[66:69], v[182:185], v[224:227], v[66:69]
	s_barrier
; #define PG8_STAGE(bufoff, gbase, voff) do { _Pragma("unroll") for (int _i = 0; _i < 2; ++_i) \
;         __builtin_amdgcn_global_load_lds((const unsigned*)((const char*)(gbase) + (voff)[_i]), (LAS unsigned*)(lds + (bufoff) + ldsw + _i * 8192), 16, 0, 0); } while (0)
; #define PG8_LDA(dst, b, h) do { _Pragma("unroll") for (int m = 0; m < 4; ++m) _Pragma("unroll") for (int k = 0; k < 2; ++k) dst[m][k] = *(const LAS bf16x8*)(lds + PG8_SA(b, h) + aoff + m * 2048 + k * 1024); } while (0)
; #define PG8_MMA(ai, bj, At, Bt) do { __builtin_amdgcn_s_setprio(1); _Pragma("unroll") for (int m = 0; m < 4; ++m) _Pragma("unroll") for (int n = 0; n < 2; ++n) _Pragma("unroll") for (int k = 0; k < 2; ++k) \
;         acc[ai][bj][m][n] = __builtin_amdgcn_mfma_f32_16x16x32_bf16(Bt[n][k], At[m][k], acc[ai][bj][m][n], 0, 0, 0); __builtin_amdgcn_s_setprio(0); } while (0)
; #define PG8_WAIT_V(n) asm volatile("s_waitcnt vmcnt(" #n ")" ::: "memory")
; #define PG8_WAIT_L(n) asm volatile("s_waitcnt lgkmcnt(" #n ")" ::: "memory")
; #define PG8_BAR __builtin_amdgcn_s_barrier()
; #define PG8_SCHED __builtin_amdgcn_sched_barrier(0)
; template <class Epi>
; __device__ __forceinline__ void gemm_phase(LAS unsigned char* lds, const Gemm g, const StaticOrder& S, const Epi& E, const int tid) {
;     ...
;             PG8_LDA(At, 1, 1); PG8_STAGE(PG8_SB(1, 0), b3, voffB); PG8_STAGE(PG8_SB(1, 1), b3 + bhs, voffB); PG8_STAGE(PG8_SA(1, 0), a3, voffA);
;             PG8_WAIT_V(8); PG8_WAIT_L(0); PG8_BAR; PG8_MMA(1, 0, At, B0); PG8_MMA(1, 1, At, B1); PG8_BAR; PG8_SCHED;
;     ...
;         if (ALIGN_EPI) { if (wr == 0) PG8_BAR; }
	s_add_i32 s30, s48, s37
	v_lshl_add_u64 v[172:173], v[172:173], 0, s[70:71]
	s_mov_b32 m0, s30
	ds_read_b128 v[186:189], v144 offset:49152
	global_load_lds_dwordx4 v[172:173], off
	ds_read_b128 v[190:193], v144 offset:50176
	ds_read_b128 v[194:197], v144 offset:51200
	s_add_i32 m0, s30, 0x2000
	s_add_u32 s28, s28, 0x8080
	v_lshl_add_u64 v[172:173], v[174:175], 0, s[70:71]
	s_addc_u32 s29, s29, 0
	s_add_i32 s30, s49, s37
	global_load_lds_dwordx4 v[172:173], off
	ds_read_b128 v[198:201], v144 offset:52224
	ds_read_b128 v[212:215], v144 offset:53248
	v_lshl_add_u64 v[172:173], s[28:29], 0, v[0:1]
	s_mov_b32 m0, s30
	s_nop 0
	global_load_lds_dwordx4 v[172:173], off
	ds_read_b128 v[216:219], v144 offset:54272
	ds_read_b128 v[220:223], v144 offset:55296
	v_lshl_add_u64 v[172:173], s[28:29], 0, v[134:135]
	s_add_i32 m0, s30, 0x2000
	s_nop 0
	global_load_lds_dwordx4 v[172:173], off
	ds_read_b128 v[224:227], v144 offset:56320
	v_lshl_add_u64 v[172:173], v[176:177], 0, s[70:71]
	s_mov_b32 m0, s40
	s_nop 0
	global_load_lds_dwordx4 v[172:173], off
	v_lshl_add_u64 v[172:173], v[228:229], 0, s[70:71]
	s_mov_b32 m0, s41
	s_nop 0
	global_load_lds_dwordx4 v[172:173], off
	s_waitcnt vmcnt(8)
	s_waitcnt lgkmcnt(0)
	s_barrier
	s_waitcnt lgkmcnt(0)
	v_mfma_f32_16x16x32_bf16 v[62:65], v[146:149], v[186:189], v[62:65]
	v_mfma_f32_16x16x32_bf16 v[58:61], v[154:157], v[186:189], v[58:61]
	v_mfma_f32_16x16x32_bf16 v[54:57], v[146:149], v[194:197], v[54:57]
	v_mfma_f32_16x16x32_bf16 v[46:49], v[154:157], v[194:197], v[46:49]
	v_mfma_f32_16x16x32_bf16 v[38:41], v[146:149], v[212:215], v[38:41]
	v_mfma_f32_16x16x32_bf16 v[30:33], v[154:157], v[212:215], v[30:33]
	v_mfma_f32_16x16x32_bf16 v[22:25], v[146:149], v[220:223], v[22:25]
	v_mfma_f32_16x16x32_bf16 v[14:17], v[154:157], v[220:223], v[14:17]
	v_mfma_f32_16x16x32_bf16 v[62:65], v[150:153], v[190:193], v[62:65]
	v_mfma_f32_16x16x32_bf16 v[58:61], v[158:161], v[190:193], v[58:61]
	v_mfma_f32_16x16x32_bf16 v[54:57], v[150:153], v[198:201], v[54:57]
	v_mfma_f32_16x16x32_bf16 v[46:49], v[158:161], v[198:201], v[46:49]
	v_mfma_f32_16x16x32_bf16 v[38:41], v[150:153], v[216:219], v[38:41]
	v_mfma_f32_16x16x32_bf16 v[30:33], v[158:161], v[216:219], v[30:33]
	v_mfma_f32_16x16x32_bf16 v[22:25], v[150:153], v[224:227], v[22:25]
	v_mfma_f32_16x16x32_bf16 v[14:17], v[158:161], v[224:227], v[14:17]
	v_mfma_f32_16x16x32_bf16 v[50:53], v[162:165], v[186:189], v[50:53]
	v_mfma_f32_16x16x32_bf16 v[42:45], v[178:181], v[186:189], v[42:45]
	v_mfma_f32_16x16x32_bf16 v[34:37], v[162:165], v[194:197], v[34:37]
	v_mfma_f32_16x16x32_bf16 v[26:29], v[178:181], v[194:197], v[26:29]
	v_mfma_f32_16x16x32_bf16 v[18:21], v[162:165], v[212:215], v[18:21]
	v_mfma_f32_16x16x32_bf16 v[10:13], v[178:181], v[212:215], v[10:13]
	v_mfma_f32_16x16x32_bf16 v[6:9], v[162:165], v[220:223], v[6:9]
	v_mfma_f32_16x16x32_bf16 v[2:5], v[178:181], v[220:223], v[2:5]
	v_mfma_f32_16x16x32_bf16 v[50:53], v[166:169], v[190:193], v[50:53]
	v_mfma_f32_16x16x32_bf16 v[42:45], v[182:185], v[190:193], v[42:45]
	v_mfma_f32_16x16x32_bf16 v[34:37], v[166:169], v[198:201], v[34:37]
	v_mfma_f32_16x16x32_bf16 v[26:29], v[182:185], v[198:201], v[26:29]
	v_mfma_f32_16x16x32_bf16 v[18:21], v[166:169], v[216:219], v[18:21]
	v_mfma_f32_16x16x32_bf16 v[10:13], v[182:185], v[216:219], v[10:13]
	v_mfma_f32_16x16x32_bf16 v[6:9], v[166:169], v[224:227], v[6:9]
	v_mfma_f32_16x16x32_bf16 v[2:5], v[182:185], v[224:227], v[2:5]
	s_barrier
	s_add_i32 s47, s47, 2
	s_add_u32 s45, s45, 0x100
	s_addc_u32 s46, s46, 0
	s_add_u32 s26, s26, 0x100
	s_addc_u32 s27, s27, 0
	s_cmp_gt_u32 s47, 29
	s_cbranch_scc0 .LBB0_844
	s_and_b64 vcc, exec, s[10:11]
	s_cbranch_vccz .LBB0_847
	s_barrier

; #define PG8_STAGE(bufoff, gbase, voff) do { _Pragma("unroll") for (int _i = 0; _i < 2; ++_i) \
;         __builtin_amdgcn_global_load_lds((const unsigned*)((const char*)(gbase) + (voff)[_i]), (LAS unsigned*)(lds + (bufoff) + ldsw + _i * 8192), 16, 0, 0); } while (0)
; #define PG8_LDA(dst, b, h) do { _Pragma("unroll") for (int m = 0; m < 4; ++m) _Pragma("unroll") for (int k = 0; k < 2; ++k) dst[m][k] = *(const LAS bf16x8*)(lds + PG8_SA(b, h) + aoff + m * 2048 + k * 1024); } while (0)
; #define PG8_LDB(dst, b, h) do { _Pragma("unroll") for (int n = 0; n < 2; ++n) _Pragma("unroll") for (int k = 0; k < 2; ++k) dst[n][k] = *(const LAS bf16x8*)(lds + PG8_SB(b, h) + boff + n * 2048 + k * 1024); } while (0)
; #define PG8_BAR __builtin_amdgcn_s_barrier()
; template <class Epi>
; __device__ __forceinline__ void gemm_phase(LAS unsigned char* lds, const Gemm g, const StaticOrder& S, const Epi& E, const int tid) {
;     ...
;         const bool has_next = S.next(ui + 1, nxt);
;         const char* nA = has_next ? (const char*)g.A + (size_t)nxt.pm * tstep : cA; const char* nB = has_next ? (const char*)g.Bt + (size_t)nxt.pn * tstep : cB;
;         for (int t = 0; t < ntt; t += 2) {
;             const bool last = (t == ntt - 2);
;             const bool s1 = Epi::TWO && (t >= nt), s2 = Epi::TWO && (t + 2 >= nt);
;             const char* a1 = (s1 ? cA2 + (size_t)(t - nt + 1) * kstep : cA + (size_t)(t + 1) * kstep);
;             const char* a2 = last ? nA : (s2 ? cA2 + (size_t)(t + 2 - nt) * kstep : cA + (size_t)(t + 2) * kstep);
;             const char* b2 = last ? nB : (s2 ? cB2 + (size_t)(t + 2 - nt) * kstep : cB + (size_t)(t + 2) * kstep);
;             const char* a3 = a2 + kstep; const char* b3 = b2 + kstep;
;             if constexpr (Epi::TWO) { if (t == nt) E.mid(acc, cur, wr, wc, fr, fq); }
;             if constexpr (SP2) {
;             PG8_LDB(B0, 0, 0); PG8_LDB(B1, 0, 1); PG8_SCHED; PG8_LDA(At, 0, 0); PG8_STAGE(PG8_SA(1, 1), a1 + hstep, voffA);
;             PG8_WAIT_V(8); PG8_WAIT_L(0); PG8_BAR; PG8_MMA(0, 0, At, B0); PG8_MMA(0, 1, At, B1); PG8_BAR; PG8_SCHED;
;     ...
; #pragma unroll
;         for (int a = 0; a < 2; ++a)
; #pragma unroll
;             for (int b = 0; b < 2; ++b)
; #pragma unroll
;                 for (int m = 0; m < 4; ++m)
; #pragma unroll
;                     for (int n = 0; n < 2; ++n) acc[a][b][m][n] = (f32x4){0.f, 0.f, 0.f, 0.f};
.LBB0_860:
	s_ashr_i32 s17, s16, 31
	s_lshl_b64 s[20:21], s[16:17], 20
	s_add_u32 s20, s37, s20
	s_addc_u32 s21, s38, s21
	s_and_b64 s[22:23], s[18:19], exec
	s_cselect_b32 s17, s21, s31
	s_cselect_b32 s46, s20, s30
	s_ashr_i32 s15, s14, 31
	s_lshl_b64 s[22:23], s[14:15], 20
	s_add_u32 s22, s2, s22
	s_addc_u32 s23, s33, s23
	s_and_b64 s[34:35], s[18:19], exec
	s_cselect_b32 s15, s23, s29
	s_cselect_b32 s47, s22, s28
	s_add_u32 s48, s28, 0x100
	s_addc_u32 s49, s29, 0
	s_add_u32 s28, s30, 0x80080
	v_mov_b32_e32 v2, 0
	s_addc_u32 s29, s31, 0
	s_mov_b32 s50, -2
	v_mov_b32_e32 v3, v2
	v_mov_b32_e32 v4, v2
	v_mov_b32_e32 v5, v2
	v_mov_b32_e32 v6, v2
	v_mov_b32_e32 v7, v2
	v_mov_b32_e32 v8, v2
	v_mov_b32_e32 v9, v2
	v_mov_b32_e32 v10, v2
	v_mov_b32_e32 v11, v2
	v_mov_b32_e32 v12, v2
	v_mov_b32_e32 v13, v2
	v_mov_b32_e32 v18, v2
	v_mov_b32_e32 v19, v2
	v_mov_b32_e32 v20, v2
	v_mov_b32_e32 v21, v2
	v_mov_b32_e32 v26, v2
	v_mov_b32_e32 v27, v2
	v_mov_b32_e32 v28, v2
	v_mov_b32_e32 v29, v2
	v_mov_b32_e32 v34, v2
	v_mov_b32_e32 v35, v2
	v_mov_b32_e32 v36, v2
	v_mov_b32_e32 v37, v2
	v_mov_b32_e32 v42, v2
	v_mov_b32_e32 v43, v2
	v_mov_b32_e32 v44, v2
	v_mov_b32_e32 v45, v2
	v_mov_b32_e32 v50, v2
	v_mov_b32_e32 v51, v2
	v_mov_b32_e32 v52, v2
	v_mov_b32_e32 v53, v2
	v_mov_b32_e32 v14, v2
	v_mov_b32_e32 v15, v2
	v_mov_b32_e32 v16, v2
	v_mov_b32_e32 v17, v2
	v_mov_b32_e32 v22, v2
	v_mov_b32_e32 v23, v2
	v_mov_b32_e32 v24, v2
	v_mov_b32_e32 v25, v2
	v_mov_b32_e32 v30, v2
	v_mov_b32_e32 v31, v2
	v_mov_b32_e32 v32, v2
	v_mov_b32_e32 v33, v2
	v_mov_b32_e32 v38, v2
	v_mov_b32_e32 v39, v2
	v_mov_b32_e32 v40, v2
	v_mov_b32_e32 v41, v2
	v_mov_b32_e32 v46, v2
	v_mov_b32_e32 v47, v2
	v_mov_b32_e32 v48, v2
	v_mov_b32_e32 v49, v2
	v_mov_b32_e32 v54, v2
	v_mov_b32_e32 v55, v2
	v_mov_b32_e32 v56, v2
	v_mov_b32_e32 v57, v2
	v_mov_b32_e32 v58, v2
	v_mov_b32_e32 v59, v2
	v_mov_b32_e32 v60, v2
	v_mov_b32_e32 v61, v2
	v_mov_b32_e32 v62, v2
	v_mov_b32_e32 v63, v2
	v_mov_b32_e32 v64, v2
	v_mov_b32_e32 v65, v2
	v_mov_b32_e32 v66, v2
	v_mov_b32_e32 v67, v2
	v_mov_b32_e32 v68, v2
	v_mov_b32_e32 v69, v2
	v_mov_b32_e32 v70, v2
	v_mov_b32_e32 v71, v2
	v_mov_b32_e32 v72, v2
	v_mov_b32_e32 v73, v2
	v_mov_b32_e32 v74, v2
	v_mov_b32_e32 v75, v2
	v_mov_b32_e32 v76, v2
	v_mov_b32_e32 v77, v2
	v_mov_b32_e32 v82, v2
	v_mov_b32_e32 v83, v2
	v_mov_b32_e32 v84, v2
	v_mov_b32_e32 v85, v2
	v_mov_b32_e32 v90, v2
	v_mov_b32_e32 v91, v2
	v_mov_b32_e32 v92, v2
	v_mov_b32_e32 v93, v2
	v_mov_b32_e32 v98, v2
	v_mov_b32_e32 v99, v2
	v_mov_b32_e32 v100, v2
	v_mov_b32_e32 v101, v2
	v_mov_b32_e32 v106, v2
	v_mov_b32_e32 v107, v2
	v_mov_b32_e32 v108, v2
	v_mov_b32_e32 v109, v2
	v_mov_b32_e32 v114, v2
	v_mov_b32_e32 v115, v2
	v_mov_b32_e32 v116, v2
	v_mov_b32_e32 v117, v2
	v_mov_b32_e32 v78, v2
	v_mov_b32_e32 v79, v2
	v_mov_b32_e32 v80, v2
	v_mov_b32_e32 v81, v2
	v_mov_b32_e32 v86, v2
	v_mov_b32_e32 v87, v2
	v_mov_b32_e32 v88, v2
	v_mov_b32_e32 v89, v2
	v_mov_b32_e32 v94, v2
	v_mov_b32_e32 v95, v2
	v_mov_b32_e32 v96, v2
	v_mov_b32_e32 v97, v2
	v_mov_b32_e32 v102, v2
	v_mov_b32_e32 v103, v2
	v_mov_b32_e32 v104, v2
	v_mov_b32_e32 v105, v2
	v_mov_b32_e32 v110, v2
	v_mov_b32_e32 v111, v2
	v_mov_b32_e32 v112, v2
	v_mov_b32_e32 v113, v2
	v_mov_b32_e32 v118, v2
	v_mov_b32_e32 v119, v2
	v_mov_b32_e32 v120, v2
	v_mov_b32_e32 v121, v2
	v_mov_b32_e32 v122, v2
	v_mov_b32_e32 v123, v2
	v_mov_b32_e32 v124, v2
	v_mov_b32_e32 v125, v2
	v_mov_b32_e32 v126, v2
	v_mov_b32_e32 v127, v2
	v_mov_b32_e32 v128, v2
	v_mov_b32_e32 v129, v2
	s_and_b64 vcc, exec, s[12:13]
	s_cbranch_vccnz .Lprio_skip_861
	s_setprio 1
.Lprio_skip_861:
.LBB0_861:
	s_add_u32 s30, s28, 0xfff80080
	s_addc_u32 s31, s29, -1
	s_add_i32 s51, 0, 0x10000
	s_cmp_eq_u32 s50, 28
	s_cselect_b32 s35, s17, s31
	s_cselect_b32 s34, s46, s30
	v_add_u32_e32 v145, s51, v142
	s_cselect_b32 s31, s15, s49
	s_cselect_b32 s30, s47, s48
	s_add_i32 s54, 0, 0x14000
	ds_read_b128 v[146:149], v145
	ds_read_b128 v[150:153], v145 offset:1024
	ds_read_b128 v[154:157], v145 offset:2048
	ds_read_b128 v[158:161], v145 offset:3072
	v_add_u32_e32 v145, s54, v142
	ds_read_b128 v[162:165], v145
	ds_read_b128 v[166:169], v145 offset:1024
	ds_read_b128 v[178:181], v145 offset:2048
	ds_read_b128 v[182:185], v145 offset:3072
	v_lshl_add_u64 v[172:173], s[28:29], 0, v[138:139]
	s_add_i32 m0, s25, 0xc000
	ds_read_b128 v[186:189], v144
	global_load_lds_dwordx4 v[172:173], off
	ds_read_b128 v[190:193], v144 offset:1024
	ds_read_b128 v[194:197], v144 offset:2048
	v_lshl_add_u64 v[172:173], s[28:29], 0, v[136:137]
	s_add_i32 m0, s25, 0xe000
	s_nop 0
	global_load_lds_dwordx4 v[172:173], off
	ds_read_b128 v[198:201], v144 offset:3072
	ds_read_b128 v[212:215], v144 offset:4096
	ds_read_b128 v[216:219], v144 offset:5120
	ds_read_b128 v[220:223], v144 offset:6144
	ds_read_b128 v[224:227], v144 offset:7168
	s_waitcnt vmcnt(8)
	s_waitcnt lgkmcnt(0)
	s_barrier
; #define PG8_STAGE(bufoff, gbase, voff) do { _Pragma("unroll") for (int _i = 0; _i < 2; ++_i) \
;         __builtin_amdgcn_global_load_lds((const unsigned*)((const char*)(gbase) + (voff)[_i]), (LAS unsigned*)(lds + (bufoff) + ldsw + _i * 8192), 16, 0, 0); } while (0)
; #define PG8_LDA(dst, b, h) do { _Pragma("unroll") for (int m = 0; m < 4; ++m) _Pragma("unroll") for (int k = 0; k < 2; ++k) dst[m][k] = *(const LAS bf16x8*)(lds + PG8_SA(b, h) + aoff + m * 2048 + k * 1024); } while (0)
; #define PG8_MMA(ai, bj, At, Bt) do { __builtin_amdgcn_s_setprio(1); _Pragma("unroll") for (int m = 0; m < 4; ++m) _Pragma("unroll") for (int n = 0; n < 2; ++n) _Pragma("unroll") for (int k = 0; k < 2; ++k) \
;         acc[ai][bj][m][n] = __builtin_amdgcn_mfma_f32_16x16x32_bf16(Bt[n][k], At[m][k], acc[ai][bj][m][n], 0, 0, 0); __builtin_amdgcn_s_setprio(0); } while (0)
; #define PG8_WAIT_V(n) asm volatile("s_waitcnt vmcnt(" #n ")" ::: "memory")
; #define PG8_WAIT_L(n) asm volatile("s_waitcnt lgkmcnt(" #n ")" ::: "memory")
; #define PG8_BAR __builtin_amdgcn_s_barrier()
; #define PG8_SCHED __builtin_amdgcn_sched_barrier(0)
; template <class Epi>
; __device__ __forceinline__ void gemm_phase(LAS unsigned char* lds, const Gemm g, const StaticOrder& S, const Epi& E, const int tid) {
;     ...
;             PG8_WAIT_V(8); PG8_WAIT_L(0); PG8_BAR; PG8_MMA(0, 0, At, B0); PG8_MMA(0, 1, At, B1); PG8_BAR; PG8_SCHED;
;             PG8_LDA(At, 0, 1); PG8_STAGE(PG8_SB(0, 0), b2, voffB); PG8_STAGE(PG8_SB(0, 1), b2 + bhs, voffB); PG8_STAGE(PG8_SA(0, 0), a2, voffA);
;             PG8_WAIT_V(8); PG8_WAIT_L(0); PG8_BAR; PG8_MMA(1, 0, At, B0); PG8_MMA(1, 1, At, B1); PG8_BAR; PG8_SCHED;
	s_waitcnt lgkmcnt(0)
	v_mfma_f32_16x16x32_bf16 v[126:129], v[146:149], v[186:189], v[126:129]
	v_mfma_f32_16x16x32_bf16 v[122:125], v[154:157], v[186:189], v[122:125]
	v_mfma_f32_16x16x32_bf16 v[118:121], v[146:149], v[194:197], v[118:121]
	v_mfma_f32_16x16x32_bf16 v[110:113], v[154:157], v[194:197], v[110:113]
	v_mfma_f32_16x16x32_bf16 v[102:105], v[146:149], v[212:215], v[102:105]
	v_mfma_f32_16x16x32_bf16 v[94:97], v[154:157], v[212:215], v[94:97]
	v_mfma_f32_16x16x32_bf16 v[86:89], v[146:149], v[220:223], v[86:89]
	v_mfma_f32_16x16x32_bf16 v[78:81], v[154:157], v[220:223], v[78:81]
	v_mfma_f32_16x16x32_bf16 v[126:129], v[150:153], v[190:193], v[126:129]
	v_mfma_f32_16x16x32_bf16 v[122:125], v[158:161], v[190:193], v[122:125]
	v_mfma_f32_16x16x32_bf16 v[118:121], v[150:153], v[198:201], v[118:121]
	v_mfma_f32_16x16x32_bf16 v[110:113], v[158:161], v[198:201], v[110:113]
	v_mfma_f32_16x16x32_bf16 v[102:105], v[150:153], v[216:219], v[102:105]
	v_mfma_f32_16x16x32_bf16 v[94:97], v[158:161], v[216:219], v[94:97]
	v_mfma_f32_16x16x32_bf16 v[86:89], v[150:153], v[224:227], v[86:89]
	v_mfma_f32_16x16x32_bf16 v[78:81], v[158:161], v[224:227], v[78:81]
	v_mfma_f32_16x16x32_bf16 v[114:117], v[162:165], v[186:189], v[114:117]
	v_mfma_f32_16x16x32_bf16 v[106:109], v[178:181], v[186:189], v[106:109]
	v_mfma_f32_16x16x32_bf16 v[98:101], v[162:165], v[194:197], v[98:101]
	v_mfma_f32_16x16x32_bf16 v[90:93], v[178:181], v[194:197], v[90:93]
	v_mfma_f32_16x16x32_bf16 v[82:85], v[162:165], v[212:215], v[82:85]
	v_mfma_f32_16x16x32_bf16 v[74:77], v[178:181], v[212:215], v[74:77]
	v_mfma_f32_16x16x32_bf16 v[70:73], v[162:165], v[220:223], v[70:73]
	v_mfma_f32_16x16x32_bf16 v[66:69], v[178:181], v[220:223], v[66:69]
	v_mfma_f32_16x16x32_bf16 v[114:117], v[166:169], v[190:193], v[114:117]
	v_mfma_f32_16x16x32_bf16 v[106:109], v[182:185], v[190:193], v[106:109]
	v_mfma_f32_16x16x32_bf16 v[98:101], v[166:169], v[198:201], v[98:101]
	v_mfma_f32_16x16x32_bf16 v[90:93], v[182:185], v[198:201], v[90:93]
	v_mfma_f32_16x16x32_bf16 v[82:85], v[166:169], v[216:219], v[82:85]
	v_mfma_f32_16x16x32_bf16 v[74:77], v[182:185], v[216:219], v[74:77]
	v_mfma_f32_16x16x32_bf16 v[70:73], v[166:169], v[224:227], v[70:73]
	v_mfma_f32_16x16x32_bf16 v[66:69], v[182:185], v[224:227], v[66:69]
	s_barrier
	s_add_i32 s51, s51, s40
	v_lshl_add_u64 v[172:173], s[30:31], 0, v[0:1]
	s_mov_b32 m0, s51
	ds_read_b128 v[186:189], v144 offset:16384
	global_load_lds_dwordx4 v[172:173], off
	ds_read_b128 v[190:193], v144 offset:17408
	ds_read_b128 v[194:197], v144 offset:18432
	s_add_i32 m0, s51, 0x2000
	s_add_u32 s52, s30, 0x8000
	v_lshl_add_u64 v[174:175], s[30:31], 0, v[134:135]
	s_addc_u32 s53, s31, 0
	s_add_i32 s51, s54, s40
	global_load_lds_dwordx4 v[174:175], off
	ds_read_b128 v[198:201], v144 offset:19456
	ds_read_b128 v[212:215], v144 offset:20480
	v_lshl_add_u64 v[176:177], s[52:53], 0, v[0:1]
	s_mov_b32 m0, s51
	v_lshl_add_u64 v[228:229], s[34:35], 0, v[132:133]
	global_load_lds_dwordx4 v[176:177], off
	ds_read_b128 v[216:219], v144 offset:21504
	ds_read_b128 v[220:223], v144 offset:22528
	v_lshl_add_u64 v[176:177], s[52:53], 0, v[134:135]
	s_add_i32 m0, s51, 0x2000
	s_nop 0
	global_load_lds_dwordx4 v[176:177], off
	ds_read_b128 v[224:227], v144 offset:23552
	v_lshl_add_u64 v[176:177], s[34:35], 0, v[130:131]
	s_mov_b32 m0, s25
	s_nop 0
	global_load_lds_dwordx4 v[176:177], off
	s_mov_b32 m0, s27
	s_nop 0
	global_load_lds_dwordx4 v[228:229], off
	s_waitcnt vmcnt(8)
	s_waitcnt lgkmcnt(0)
	s_barrier
	s_waitcnt lgkmcnt(0)
	v_mfma_f32_16x16x32_bf16 v[62:65], v[146:149], v[186:189], v[62:65]
	v_mfma_f32_16x16x32_bf16 v[58:61], v[154:157], v[186:189], v[58:61]
	v_mfma_f32_16x16x32_bf16 v[54:57], v[146:149], v[194:197], v[54:57]
	v_mfma_f32_16x16x32_bf16 v[46:49], v[154:157], v[194:197], v[46:49]
	v_mfma_f32_16x16x32_bf16 v[38:41], v[146:149], v[212:215], v[38:41]
	v_mfma_f32_16x16x32_bf16 v[30:33], v[154:157], v[212:215], v[30:33]
	v_mfma_f32_16x16x32_bf16 v[22:25], v[146:149], v[220:223], v[22:25]
	v_mfma_f32_16x16x32_bf16 v[14:17], v[154:157], v[220:223], v[14:17]
	v_mfma_f32_16x16x32_bf16 v[62:65], v[150:153], v[190:193], v[62:65]
	v_mfma_f32_16x16x32_bf16 v[58:61], v[158:161], v[190:193], v[58:61]
	v_mfma_f32_16x16x32_bf16 v[54:57], v[150:153], v[198:201], v[54:57]
	v_mfma_f32_16x16x32_bf16 v[46:49], v[158:161], v[198:201], v[46:49]
	v_mfma_f32_16x16x32_bf16 v[38:41], v[150:153], v[216:219], v[38:41]
	v_mfma_f32_16x16x32_bf16 v[30:33], v[158:161], v[216:219], v[30:33]
	v_mfma_f32_16x16x32_bf16 v[22:25], v[150:153], v[224:227], v[22:25]
	v_mfma_f32_16x16x32_bf16 v[14:17], v[158:161], v[224:227], v[14:17]
	v_mfma_f32_16x16x32_bf16 v[50:53], v[162:165], v[186:189], v[50:53]
	v_mfma_f32_16x16x32_bf16 v[42:45], v[178:181], v[186:189], v[42:45]
	v_mfma_f32_16x16x32_bf16 v[34:37], v[162:165], v[194:197], v[34:37]
	v_mfma_f32_16x16x32_bf16 v[26:29], v[178:181], v[194:197], v[26:29]
	v_mfma_f32_16x16x32_bf16 v[18:21], v[162:165], v[212:215], v[18:21]
	v_mfma_f32_16x16x32_bf16 v[10:13], v[178:181], v[212:215], v[10:13]
	v_mfma_f32_16x16x32_bf16 v[6:9], v[162:165], v[220:223], v[6:9]
	v_mfma_f32_16x16x32_bf16 v[2:5], v[178:181], v[220:223], v[2:5]
	v_mfma_f32_16x16x32_bf16 v[50:53], v[166:169], v[190:193], v[50:53]
	v_mfma_f32_16x16x32_bf16 v[42:45], v[182:185], v[190:193], v[42:45]
	v_mfma_f32_16x16x32_bf16 v[34:37], v[166:169], v[198:201], v[34:37]
	v_mfma_f32_16x16x32_bf16 v[26:29], v[182:185], v[198:201], v[26:29]
	v_mfma_f32_16x16x32_bf16 v[18:21], v[166:169], v[216:219], v[18:21]
	v_mfma_f32_16x16x32_bf16 v[10:13], v[182:185], v[216:219], v[10:13]
	v_mfma_f32_16x16x32_bf16 v[6:9], v[166:169], v[224:227], v[6:9]
	v_mfma_f32_16x16x32_bf16 v[2:5], v[182:185], v[224:227], v[2:5]
	s_barrier
; #define PG8_STAGE(bufoff, gbase, voff) do { _Pragma("unroll") for (int _i = 0; _i < 2; ++_i) \
;         __builtin_amdgcn_global_load_lds((const unsigned*)((const char*)(gbase) + (voff)[_i]), (LAS unsigned*)(lds + (bufoff) + ldsw + _i * 8192), 16, 0, 0); } while (0)
; #define PG8_LDA(dst, b, h) do { _Pragma("unroll") for (int m = 0; m < 4; ++m) _Pragma("unroll") for (int k = 0; k < 2; ++k) dst[m][k] = *(const LAS bf16x8*)(lds + PG8_SA(b, h) + aoff + m * 2048 + k * 1024); } while (0)
; #define PG8_LDB(dst, b, h) do { _Pragma("unroll") for (int n = 0; n < 2; ++n) _Pragma("unroll") for (int k = 0; k < 2; ++k) dst[n][k] = *(const LAS bf16x8*)(lds + PG8_SB(b, h) + boff + n * 2048 + k * 1024); } while (0)
; #define PG8_MMA(ai, bj, At, Bt) do { __builtin_amdgcn_s_setprio(1); _Pragma("unroll") for (int m = 0; m < 4; ++m) _Pragma("unroll") for (int n = 0; n < 2; ++n) _Pragma("unroll") for (int k = 0; k < 2; ++k) \
;         acc[ai][bj][m][n] = __builtin_amdgcn_mfma_f32_16x16x32_bf16(Bt[n][k], At[m][k], acc[ai][bj][m][n], 0, 0, 0); __builtin_amdgcn_s_setprio(0); } while (0)
; #define PG8_WAIT_V(n) asm volatile("s_waitcnt vmcnt(" #n ")" ::: "memory")
; #define PG8_WAIT_L(n) asm volatile("s_waitcnt lgkmcnt(" #n ")" ::: "memory")
; #define PG8_BAR __builtin_amdgcn_s_barrier()
; #define PG8_SCHED __builtin_amdgcn_sched_barrier(0)
; template <class Epi>
; __device__ __forceinline__ void gemm_phase(LAS unsigned char* lds, const Gemm g, const StaticOrder& S, const Epi& E, const int tid) {
;     ...
;             PG8_LDB(B0, 1, 0); PG8_LDB(B1, 1, 1); PG8_SCHED; PG8_LDA(At, 1, 0); PG8_STAGE(PG8_SA(0, 1), a2 + hstep, voffA);
;             PG8_WAIT_V(8); PG8_WAIT_L(0); PG8_BAR; PG8_MMA(0, 0, At, B0); PG8_MMA(0, 1, At, B1); PG8_BAR; PG8_SCHED;
	s_add_i32 s51, 0, 0x18000
	v_add_u32_e32 v145, s51, v142
	s_add_i32 s52, 0, 0x1c000
	ds_read_b128 v[146:149], v145
	ds_read_b128 v[150:153], v145 offset:1024
	ds_read_b128 v[154:157], v145 offset:2048
	ds_read_b128 v[158:161], v145 offset:3072
	v_add_u32_e32 v145, s52, v142
	ds_read_b128 v[162:165], v145
	ds_read_b128 v[166:169], v145 offset:1024
	ds_read_b128 v[178:181], v145 offset:2048
	ds_read_b128 v[182:185], v145 offset:3072
	s_add_u32 s34, s34, 0x80000
	s_addc_u32 s35, s35, 0
	s_mov_b32 m0, s41
	v_lshl_add_u64 v[230:231], s[34:35], 0, v[130:131]
	ds_read_b128 v[186:189], v144 offset:32768
	global_load_lds_dwordx4 v[230:231], off
	ds_read_b128 v[190:193], v144 offset:33792
	ds_read_b128 v[194:197], v144 offset:34816
	v_lshl_add_u64 v[230:231], s[34:35], 0, v[132:133]
	s_mov_b32 m0, s42
	s_nop 0
	global_load_lds_dwordx4 v[230:231], off
	ds_read_b128 v[198:201], v144 offset:35840
	ds_read_b128 v[212:215], v144 offset:36864
	ds_read_b128 v[216:219], v144 offset:37888
	ds_read_b128 v[220:223], v144 offset:38912
	ds_read_b128 v[224:227], v144 offset:39936
	s_waitcnt vmcnt(8)
	s_waitcnt lgkmcnt(0)
	s_barrier
	s_waitcnt lgkmcnt(0)
	v_mfma_f32_16x16x32_bf16 v[126:129], v[146:149], v[186:189], v[126:129]
	v_mfma_f32_16x16x32_bf16 v[122:125], v[154:157], v[186:189], v[122:125]
	v_mfma_f32_16x16x32_bf16 v[118:121], v[146:149], v[194:197], v[118:121]
	v_mfma_f32_16x16x32_bf16 v[110:113], v[154:157], v[194:197], v[110:113]
	v_mfma_f32_16x16x32_bf16 v[102:105], v[146:149], v[212:215], v[102:105]
	v_mfma_f32_16x16x32_bf16 v[94:97], v[154:157], v[212:215], v[94:97]
	v_mfma_f32_16x16x32_bf16 v[86:89], v[146:149], v[220:223], v[86:89]
	v_mfma_f32_16x16x32_bf16 v[78:81], v[154:157], v[220:223], v[78:81]
	v_mfma_f32_16x16x32_bf16 v[126:129], v[150:153], v[190:193], v[126:129]
	v_mfma_f32_16x16x32_bf16 v[122:125], v[158:161], v[190:193], v[122:125]
	v_mfma_f32_16x16x32_bf16 v[118:121], v[150:153], v[198:201], v[118:121]
	v_mfma_f32_16x16x32_bf16 v[110:113], v[158:161], v[198:201], v[110:113]
	v_mfma_f32_16x16x32_bf16 v[102:105], v[150:153], v[216:219], v[102:105]
	v_mfma_f32_16x16x32_bf16 v[94:97], v[158:161], v[216:219], v[94:97]
	v_mfma_f32_16x16x32_bf16 v[86:89], v[150:153], v[224:227], v[86:89]
	v_mfma_f32_16x16x32_bf16 v[78:81], v[158:161], v[224:227], v[78:81]
	v_mfma_f32_16x16x32_bf16 v[114:117], v[162:165], v[186:189], v[114:117]
	v_mfma_f32_16x16x32_bf16 v[106:109], v[178:181], v[186:189], v[106:109]
	v_mfma_f32_16x16x32_bf16 v[98:101], v[162:165], v[194:197], v[98:101]
	v_mfma_f32_16x16x32_bf16 v[90:93], v[178:181], v[194:197], v[90:93]
	v_mfma_f32_16x16x32_bf16 v[82:85], v[162:165], v[212:215], v[82:85]
	v_mfma_f32_16x16x32_bf16 v[74:77], v[178:181], v[212:215], v[74:77]
	v_mfma_f32_16x16x32_bf16 v[70:73], v[162:165], v[220:223], v[70:73]
	v_mfma_f32_16x16x32_bf16 v[66:69], v[178:181], v[220:223], v[66:69]
	v_mfma_f32_16x16x32_bf16 v[114:117], v[166:169], v[190:193], v[114:117]
	v_mfma_f32_16x16x32_bf16 v[106:109], v[182:185], v[190:193], v[106:109]
	v_mfma_f32_16x16x32_bf16 v[98:101], v[166:169], v[198:201], v[98:101]
	v_mfma_f32_16x16x32_bf16 v[90:93], v[182:185], v[198:201], v[90:93]
	v_mfma_f32_16x16x32_bf16 v[82:85], v[166:169], v[216:219], v[82:85]
	v_mfma_f32_16x16x32_bf16 v[74:77], v[182:185], v[216:219], v[74:77]
	v_mfma_f32_16x16x32_bf16 v[70:73], v[166:169], v[224:227], v[70:73]
	v_mfma_f32_16x16x32_bf16 v[66:69], v[182:185], v[224:227], v[66:69]
	s_barrier
; #define PG8_STAGE(bufoff, gbase, voff) do { _Pragma("unroll") for (int _i = 0; _i < 2; ++_i) \
;         __builtin_amdgcn_global_load_lds((const unsigned*)((const char*)(gbase) + (voff)[_i]), (LAS unsigned*)(lds + (bufoff) + ldsw + _i * 8192), 16, 0, 0); } while (0)
; #define PG8_LDA(dst, b, h) do { _Pragma("unroll") for (int m = 0; m < 4; ++m) _Pragma("unroll") for (int k = 0; k < 2; ++k) dst[m][k] = *(const LAS bf16x8*)(lds + PG8_SA(b, h) + aoff + m * 2048 + k * 1024); } while (0)
; #define PG8_MMA(ai, bj, At, Bt) do { __builtin_amdgcn_s_setprio(1); _Pragma("unroll") for (int m = 0; m < 4; ++m) _Pragma("unroll") for (int n = 0; n < 2; ++n) _Pragma("unroll") for (int k = 0; k < 2; ++k) \
;         acc[ai][bj][m][n] = __builtin_amdgcn_mfma_f32_16x16x32_bf16(Bt[n][k], At[m][k], acc[ai][bj][m][n], 0, 0, 0); __builtin_amdgcn_s_setprio(0); } while (0)
; #define PG8_WAIT_V(n) asm volatile("s_waitcnt vmcnt(" #n ")" ::: "memory")
; #define PG8_WAIT_L(n) asm volatile("s_waitcnt lgkmcnt(" #n ")" ::: "memory")
; #define PG8_BAR __builtin_amdgcn_s_barrier()
; #define PG8_SCHED __builtin_amdgcn_sched_barrier(0)
; template <class Epi>
; __device__ __forceinline__ void gemm_phase(LAS unsigned char* lds, const Gemm g, const StaticOrder& S, const Epi& E, const int tid) {
;     ...
;             PG8_LDA(At, 1, 1); PG8_STAGE(PG8_SB(1, 0), b3, voffB); PG8_STAGE(PG8_SB(1, 1), b3 + bhs, voffB); PG8_STAGE(PG8_SA(1, 0), a3, voffA);
;             PG8_WAIT_V(8); PG8_WAIT_L(0); PG8_BAR; PG8_MMA(1, 0, At, B0); PG8_MMA(1, 1, At, B1); PG8_BAR; PG8_SCHED;
;     ...
;         if (ALIGN_EPI) { if (wr == 0) PG8_BAR; }
	s_add_i32 s34, s51, s40
	v_lshl_add_u64 v[172:173], v[172:173], 0, s[70:71]
	s_mov_b32 m0, s34
	ds_read_b128 v[186:189], v144 offset:49152
	global_load_lds_dwordx4 v[172:173], off
	ds_read_b128 v[190:193], v144 offset:50176
	ds_read_b128 v[194:197], v144 offset:51200
	s_add_i32 m0, s34, 0x2000
	s_add_u32 s30, s30, 0x8080
	v_lshl_add_u64 v[172:173], v[174:175], 0, s[70:71]
	s_addc_u32 s31, s31, 0
	s_add_i32 s34, s52, s40
	global_load_lds_dwordx4 v[172:173], off
	ds_read_b128 v[198:201], v144 offset:52224
	ds_read_b128 v[212:215], v144 offset:53248
	v_lshl_add_u64 v[172:173], s[30:31], 0, v[0:1]
	s_mov_b32 m0, s34
	s_nop 0
	global_load_lds_dwordx4 v[172:173], off
	ds_read_b128 v[216:219], v144 offset:54272
	ds_read_b128 v[220:223], v144 offset:55296
	v_lshl_add_u64 v[172:173], s[30:31], 0, v[134:135]
	s_add_i32 m0, s34, 0x2000
	s_nop 0
	global_load_lds_dwordx4 v[172:173], off
	ds_read_b128 v[224:227], v144 offset:56320
	v_lshl_add_u64 v[172:173], v[176:177], 0, s[70:71]
	s_mov_b32 m0, s43
	s_nop 0
	global_load_lds_dwordx4 v[172:173], off
	v_lshl_add_u64 v[172:173], v[228:229], 0, s[70:71]
	s_mov_b32 m0, s44
	s_nop 0
	global_load_lds_dwordx4 v[172:173], off
	s_waitcnt vmcnt(8)
	s_waitcnt lgkmcnt(0)
	s_barrier
	s_waitcnt lgkmcnt(0)
	v_mfma_f32_16x16x32_bf16 v[62:65], v[146:149], v[186:189], v[62:65]
	v_mfma_f32_16x16x32_bf16 v[58:61], v[154:157], v[186:189], v[58:61]
	v_mfma_f32_16x16x32_bf16 v[54:57], v[146:149], v[194:197], v[54:57]
	v_mfma_f32_16x16x32_bf16 v[46:49], v[154:157], v[194:197], v[46:49]
	v_mfma_f32_16x16x32_bf16 v[38:41], v[146:149], v[212:215], v[38:41]
	v_mfma_f32_16x16x32_bf16 v[30:33], v[154:157], v[212:215], v[30:33]
	v_mfma_f32_16x16x32_bf16 v[22:25], v[146:149], v[220:223], v[22:25]
	v_mfma_f32_16x16x32_bf16 v[14:17], v[154:157], v[220:223], v[14:17]
	v_mfma_f32_16x16x32_bf16 v[62:65], v[150:153], v[190:193], v[62:65]
	v_mfma_f32_16x16x32_bf16 v[58:61], v[158:161], v[190:193], v[58:61]
	v_mfma_f32_16x16x32_bf16 v[54:57], v[150:153], v[198:201], v[54:57]
	v_mfma_f32_16x16x32_bf16 v[46:49], v[158:161], v[198:201], v[46:49]
	v_mfma_f32_16x16x32_bf16 v[38:41], v[150:153], v[216:219], v[38:41]
	v_mfma_f32_16x16x32_bf16 v[30:33], v[158:161], v[216:219], v[30:33]
	v_mfma_f32_16x16x32_bf16 v[22:25], v[150:153], v[224:227], v[22:25]
	v_mfma_f32_16x16x32_bf16 v[14:17], v[158:161], v[224:227], v[14:17]
	v_mfma_f32_16x16x32_bf16 v[50:53], v[162:165], v[186:189], v[50:53]
	v_mfma_f32_16x16x32_bf16 v[42:45], v[178:181], v[186:189], v[42:45]
	v_mfma_f32_16x16x32_bf16 v[34:37], v[162:165], v[194:197], v[34:37]
	v_mfma_f32_16x16x32_bf16 v[26:29], v[178:181], v[194:197], v[26:29]
	v_mfma_f32_16x16x32_bf16 v[18:21], v[162:165], v[212:215], v[18:21]
	v_mfma_f32_16x16x32_bf16 v[10:13], v[178:181], v[212:215], v[10:13]
	v_mfma_f32_16x16x32_bf16 v[6:9], v[162:165], v[220:223], v[6:9]
	v_mfma_f32_16x16x32_bf16 v[2:5], v[178:181], v[220:223], v[2:5]
	v_mfma_f32_16x16x32_bf16 v[50:53], v[166:169], v[190:193], v[50:53]
	v_mfma_f32_16x16x32_bf16 v[42:45], v[182:185], v[190:193], v[42:45]
	v_mfma_f32_16x16x32_bf16 v[34:37], v[166:169], v[198:201], v[34:37]
	v_mfma_f32_16x16x32_bf16 v[26:29], v[182:185], v[198:201], v[26:29]
	v_mfma_f32_16x16x32_bf16 v[18:21], v[166:169], v[216:219], v[18:21]
	v_mfma_f32_16x16x32_bf16 v[10:13], v[182:185], v[216:219], v[10:13]
	v_mfma_f32_16x16x32_bf16 v[6:9], v[166:169], v[224:227], v[6:9]
	v_mfma_f32_16x16x32_bf16 v[2:5], v[182:185], v[224:227], v[2:5]
	s_barrier
	s_add_i32 s50, s50, 2
	s_add_u32 s48, s48, 0x100
	s_addc_u32 s49, s49, 0
	s_add_u32 s28, s28, 0x100
	s_addc_u32 s29, s29, 0
	s_cmp_gt_u32 s50, 29
	s_cbranch_scc0 .LBB0_861
	s_and_b64 vcc, exec, s[12:13]
	s_cbranch_vccz .LBB0_864
	s_barrier
